# SSD v5 (per-l-tile specialised, swizzled LDS images, dripped prefetch/fill, balanced wave roles) + dt side-GEMM split-K with LDS reduce and hoisted epilogue loads
# speedup vs baseline: 1.0220x; 1.0220x over previous
; #define GAS __attribute__((address_space(1)))
; template <class F> __device__ __forceinline__ void skinny_tile(const GAS bf16* A, int lda, const GAS bf16* Bt, int K, int n0, int lane, F&& epi) {
;     const int fr = lane & 15, fq = lane >> 4;
;     const GAS bf16* ap = A + (size_t)fr * lda + fq * 8; const GAS bf16* bp = Bt + (size_t)(n0 + fr) * K + fq * 8;
;     f32x4 acc0 = {0.f, 0.f, 0.f, 0.f}, acc1 = {0.f, 0.f, 0.f, 0.f};
;     bf16x8 a[4], bb[4], a2[4], b2[4];
; #pragma unroll
;     for (int i = 0; i < 4; ++i) { a[i] = *(const GAS bf16x8*)(ap + i * 32); bb[i] = *(const GAS bf16x8*)(bp + i * 32); }
; __device__ __forceinline__ void side_gemm1(const Params& P, int seg) {
;     ...
;     for (int it = gw; it < nrt * 4; it += NGW) { const int rt = it >> 2, r0 = (rt < RS / 16) ? rt * 16 : RS + 48;
;         skinny_tile(xb + (size_t)r0 * DM, DM, Wt + (size_t)NPROJ * DM, DM, (it & 3) * 16, lane, [&](int row, int j, int col, float v) {
;             const float t = v * rstd1[r0 + row] + P.dt_bias[col]; dtv[(size_t)(r0 + row) * 64 + col] = (t > 20.f) ? t : log1pf(__expf(t)); }); }
.LBB0_93:
	v_readlane_b32 s0, v254, 38
	s_cmp_lg_u32 s0, 0
	s_cselect_b64 s[12:13], -1, 0
	s_cmp_eq_u32 s0, 0
	v_readlane_b32 s1, v254, 39
	s_cselect_b64 s[36:37], -1, 0
	s_mul_hi_u32 s14, s0, 0x2100000
	s_mul_i32 s15, s0, 0x2100000
	s_mul_hi_u32 s16, s0, 0x8400
	s_mul_i32 s17, s0, 0x8400
	s_and_b64 s[0:1], s[36:37], exec
	s_movk_i32 s0, 0x804
	s_mov_b64 s[40:41], s[80:81]
	v_mov_b32_e32 v24, v172
	s_mov_b32 s20, s82
	s_cselect_b32 s22, s0, 0x800
	v_readlane_b32 s0, v252, 40
	v_ashrrev_i32_e32 v26, 6, v24
	s_lshl_b32 s9, s20, 3
	v_add_u32_e32 v25, s0, v26
	s_add_u32 s0, s40, s15
	s_addc_u32 s1, s41, s14
	s_add_u32 s0, s0, 0xb0c0000
	s_addc_u32 s1, s1, 0
	s_add_u32 s14, s40, s17
	s_addc_u32 s15, s41, s16
	s_add_u32 s14, s14, 0x134c0000
	s_addc_u32 s15, s15, 0
	s_add_u32 s42, s40, 0x302e1000
	v_and_b32_e32 v27, 63, v24
	s_addc_u32 s43, s41, 0
	v_cmp_gt_i32_e32 vcc, s22, v25
	s_and_saveexec_b64 s[16:17], vcc
	v_readlane_b32 s44, v252, 24
	v_readlane_b32 s45, v252, 25
	s_mov_b32 s28, 0x41a00000
	s_mov_b32 s29, 0x3f2aaaab
	s_mov_b32 s30, 0x3f317218
	s_mov_b32 s31, 0x7f800000
	s_mov_b32 s38, 0x33800000
	v_readlane_b32 s46, v252, 26
	v_readlane_b32 s47, v252, 27
	v_readlane_b32 s48, v252, 28
	v_readlane_b32 s49, v252, 29
	v_readlane_b32 s50, v252, 30
	v_readlane_b32 s51, v252, 31
	v_readlane_b32 s52, v252, 32
	v_readlane_b32 s53, v252, 33
	v_readlane_b32 s54, v252, 34
	v_readlane_b32 s55, v252, 35
	v_readlane_b32 s56, v252, 36
	v_readlane_b32 s57, v252, 37
	v_readlane_b32 s58, v252, 38
	v_readlane_b32 s59, v252, 39
	s_cbranch_execz .LBB0_104
	s_waitcnt vmcnt(13)
	v_and_b32_e32 v28, 15, v24
	v_lshlrev_b32_e32 v174, 12, v28
	s_waitcnt lgkmcnt(0)
	v_lshl_add_u64 v[4:5], s[0:1], 0, v[174:175]
	v_and_b32_e32 v174, 48, v27
	v_lshl_add_u64 v[12:13], v[4:5], 0, v[174:175]
	v_lshl_add_u64 v[4:5], s[40:41], 0, v[174:175]
	s_mov_b64 s[18:19], 0x5000000
	v_lshl_add_u64 v[14:15], v[4:5], 0, s[18:19]
	v_lshrrev_b32_e32 v4, 2, v27
	v_readlane_b32 s18, v254, 6
	v_and_b32_e32 v29, 12, v4
	s_lshl_b32 s23, s20, 7
	v_lshl_add_u32 v30, v26, 4, s18
	s_mov_b64 s[18:19], 0
	v_mov_b32_e32 v31, v25
	s_cmp_eq_u32 s9, 0x800
	s_cselect_b32 s100, 1, 0
	s_branch .LBB0_96
.Lsg1_new:
	s_mov_b32 s100, 0
	v_lshrrev_b32_e32 v116, 6, v172
	v_and_b32_e32 v117, 3, v116
	v_lshlrev_b32_e32 v18, 10, v117
	v_mov_b32_e32 v19, 0
	v_lshl_add_u64 v[212:213], v[4:5], 0, v[18:19]
	v_and_b32_e32 v214, 48, v172
	v_lshl_add_u32 v214, v28, 12, v214
	v_add_u32_e32 v214, v214, v18
	s_add_u32 s46, s40, 0x5000000
	s_addc_u32 s47, s41, 0
	s_add_u32 s48, s46, 0x10000
	s_addc_u32 s49, s47, 0
	s_add_u32 s50, s46, 0x20000
	s_addc_u32 s51, s47, 0
	s_add_u32 s52, s46, 0x30000
	s_addc_u32 s53, s47, 0
	global_load_dwordx4 v[36:39], v[212:213], off offset:0
	global_load_dwordx4 v[40:43], v[212:213], off offset:64
	global_load_dwordx4 v[44:47], v[212:213], off offset:128
	global_load_dwordx4 v[48:51], v[212:213], off offset:192
	global_load_dwordx4 v[52:55], v214, s[46:47] offset:0
	global_load_dwordx4 v[56:59], v214, s[46:47] offset:64
	global_load_dwordx4 v[60:63], v214, s[46:47] offset:128
	global_load_dwordx4 v[64:67], v214, s[46:47] offset:192
	global_load_dwordx4 v[68:71], v214, s[48:49] offset:0
	global_load_dwordx4 v[72:75], v214, s[48:49] offset:64
	global_load_dwordx4 v[76:79], v214, s[48:49] offset:128
	global_load_dwordx4 v[80:83], v214, s[48:49] offset:192
	global_load_dwordx4 v[84:87], v214, s[50:51] offset:0
	global_load_dwordx4 v[88:91], v214, s[50:51] offset:64
	global_load_dwordx4 v[92:95], v214, s[50:51] offset:128
	global_load_dwordx4 v[96:99], v214, s[50:51] offset:192
	global_load_dwordx4 v[100:103], v214, s[52:53] offset:0
	global_load_dwordx4 v[104:107], v214, s[52:53] offset:64
	global_load_dwordx4 v[108:111], v214, s[52:53] offset:128
	global_load_dwordx4 v[112:115], v214, s[52:53] offset:192
	global_load_dwordx4 v[120:123], v[212:213], off offset:256
	global_load_dwordx4 v[124:127], v[212:213], off offset:320
	global_load_dwordx4 v[128:131], v[212:213], off offset:384
	global_load_dwordx4 v[132:135], v[212:213], off offset:448
	global_load_dwordx4 v[136:139], v214, s[46:47] offset:256
	global_load_dwordx4 v[140:143], v214, s[46:47] offset:320
	global_load_dwordx4 v[144:147], v214, s[46:47] offset:384
	global_load_dwordx4 v[148:151], v214, s[46:47] offset:448
	global_load_dwordx4 v[152:155], v214, s[48:49] offset:256
	global_load_dwordx4 v[156:159], v214, s[48:49] offset:320
	global_load_dwordx4 v[160:163], v214, s[48:49] offset:384
	global_load_dwordx4 v[164:167], v214, s[48:49] offset:448
	global_load_dwordx4 v[168:171], v214, s[50:51] offset:256
	global_load_dwordx4 v[184:187], v214, s[50:51] offset:320
	global_load_dwordx4 v[188:191], v214, s[50:51] offset:384
	global_load_dwordx4 v[192:195], v214, s[50:51] offset:448
	global_load_dwordx4 v[196:199], v214, s[52:53] offset:256
	global_load_dwordx4 v[200:203], v214, s[52:53] offset:320
	global_load_dwordx4 v[204:207], v214, s[52:53] offset:384
	global_load_dwordx4 v[208:211], v214, s[52:53] offset:448
	s_waitcnt vmcnt(20)
; #define GAS __attribute__((address_space(1)))
; __device__ __forceinline__ f32x4 mfma16(const bf16x8& a, const bf16x8& b, const f32x4& c) { return __builtin_amdgcn_mfma_f32_16x16x32_bf16(a, b, c, 0, 0, 0); }
; template <class F> __device__ __forceinline__ void skinny_tile_sk(const GAS bf16* A, int lda, const GAS bf16* Bt, int K, int n0, int wave, int lane, float* red, F&& epi) {
;     const int fr = lane & 15, fq = lane >> 4, kc = K >> 3;
;     const GAS bf16* ap = A + (size_t)fr * lda + wave * kc + fq * 8; const GAS bf16* bp = Bt + (size_t)(n0 + fr) * K + wave * kc + fq * 8;
;     f32x4 acc0 = {0.f, 0.f, 0.f, 0.f}, acc1 = {0.f, 0.f, 0.f, 0.f};
;     for (int k = 0; k < kc; k += 256) { bf16x8 a[8], bb[8];
; #pragma unroll
;         for (int i = 0; i < 8; ++i) { a[i] = *(const GAS bf16x8*)(ap + k + i * 32); bb[i] = *(const GAS bf16x8*)(bp + k + i * 32); }
; #pragma unroll
;         for (int i = 0; i < 8; i += 2) { acc0 = mfma16(a[i], bb[i], acc0); acc1 = mfma16(a[i + 1], bb[i + 1], acc1); } }
;     __syncthreads();
;     *(f32x4*)(red + wave * 256 + lane * 4) = acc0 + acc1;
;     __syncthreads();
	v_mfma_f32_16x16x32_bf16 v[4:7], v[36:39], v[52:55], 0
	v_mfma_f32_16x16x32_bf16 v[8:11], v[36:39], v[68:71], 0
	v_mfma_f32_16x16x32_bf16 v[20:23], v[36:39], v[84:87], 0
	v_mfma_f32_16x16x32_bf16 v[32:35], v[36:39], v[100:103], 0
	v_mfma_f32_16x16x32_bf16 v[4:7], v[40:43], v[56:59], v[4:7]
	v_mfma_f32_16x16x32_bf16 v[8:11], v[40:43], v[72:75], v[8:11]
	v_mfma_f32_16x16x32_bf16 v[20:23], v[40:43], v[88:91], v[20:23]
	v_mfma_f32_16x16x32_bf16 v[32:35], v[40:43], v[104:107], v[32:35]
	v_mfma_f32_16x16x32_bf16 v[4:7], v[44:47], v[60:63], v[4:7]
	v_mfma_f32_16x16x32_bf16 v[8:11], v[44:47], v[76:79], v[8:11]
	v_mfma_f32_16x16x32_bf16 v[20:23], v[44:47], v[92:95], v[20:23]
	v_mfma_f32_16x16x32_bf16 v[32:35], v[44:47], v[108:111], v[32:35]
	v_mfma_f32_16x16x32_bf16 v[4:7], v[48:51], v[64:67], v[4:7]
	v_mfma_f32_16x16x32_bf16 v[8:11], v[48:51], v[80:83], v[8:11]
	v_mfma_f32_16x16x32_bf16 v[20:23], v[48:51], v[96:99], v[20:23]
	v_mfma_f32_16x16x32_bf16 v[32:35], v[48:51], v[112:115], v[32:35]
	global_load_dwordx4 v[36:39], v[212:213], off offset:512
	global_load_dwordx4 v[40:43], v[212:213], off offset:576
	global_load_dwordx4 v[44:47], v[212:213], off offset:640
	global_load_dwordx4 v[48:51], v[212:213], off offset:704
	global_load_dwordx4 v[52:55], v214, s[46:47] offset:512
	global_load_dwordx4 v[56:59], v214, s[46:47] offset:576
	global_load_dwordx4 v[60:63], v214, s[46:47] offset:640
	global_load_dwordx4 v[64:67], v214, s[46:47] offset:704
	global_load_dwordx4 v[68:71], v214, s[48:49] offset:512
	global_load_dwordx4 v[72:75], v214, s[48:49] offset:576
	global_load_dwordx4 v[76:79], v214, s[48:49] offset:640
	global_load_dwordx4 v[80:83], v214, s[48:49] offset:704
	global_load_dwordx4 v[84:87], v214, s[50:51] offset:512
	global_load_dwordx4 v[88:91], v214, s[50:51] offset:576
	global_load_dwordx4 v[92:95], v214, s[50:51] offset:640
	global_load_dwordx4 v[96:99], v214, s[50:51] offset:704
	global_load_dwordx4 v[100:103], v214, s[52:53] offset:512
	global_load_dwordx4 v[104:107], v214, s[52:53] offset:576
	global_load_dwordx4 v[108:111], v214, s[52:53] offset:640
	global_load_dwordx4 v[112:115], v214, s[52:53] offset:704
	s_waitcnt vmcnt(20)
	v_mfma_f32_16x16x32_bf16 v[4:7], v[120:123], v[136:139], v[4:7]
	v_mfma_f32_16x16x32_bf16 v[8:11], v[120:123], v[152:155], v[8:11]
	v_mfma_f32_16x16x32_bf16 v[20:23], v[120:123], v[168:171], v[20:23]
	v_mfma_f32_16x16x32_bf16 v[32:35], v[120:123], v[196:199], v[32:35]
	v_mfma_f32_16x16x32_bf16 v[4:7], v[124:127], v[140:143], v[4:7]
	v_mfma_f32_16x16x32_bf16 v[8:11], v[124:127], v[156:159], v[8:11]
	v_mfma_f32_16x16x32_bf16 v[20:23], v[124:127], v[184:187], v[20:23]
	v_mfma_f32_16x16x32_bf16 v[32:35], v[124:127], v[200:203], v[32:35]
	v_mfma_f32_16x16x32_bf16 v[4:7], v[128:131], v[144:147], v[4:7]
	v_mfma_f32_16x16x32_bf16 v[8:11], v[128:131], v[160:163], v[8:11]
	v_mfma_f32_16x16x32_bf16 v[20:23], v[128:131], v[188:191], v[20:23]
	v_mfma_f32_16x16x32_bf16 v[32:35], v[128:131], v[204:207], v[32:35]
	v_mfma_f32_16x16x32_bf16 v[4:7], v[132:135], v[148:151], v[4:7]
	v_mfma_f32_16x16x32_bf16 v[8:11], v[132:135], v[164:167], v[8:11]
	v_mfma_f32_16x16x32_bf16 v[20:23], v[132:135], v[192:195], v[20:23]
	v_mfma_f32_16x16x32_bf16 v[32:35], v[132:135], v[208:211], v[32:35]
	global_load_dwordx4 v[120:123], v[212:213], off offset:768
	global_load_dwordx4 v[124:127], v[212:213], off offset:832
	global_load_dwordx4 v[128:131], v[212:213], off offset:896
	global_load_dwordx4 v[132:135], v[212:213], off offset:960
	global_load_dwordx4 v[136:139], v214, s[46:47] offset:768
	global_load_dwordx4 v[140:143], v214, s[46:47] offset:832
	global_load_dwordx4 v[144:147], v214, s[46:47] offset:896
	global_load_dwordx4 v[148:151], v214, s[46:47] offset:960
	global_load_dwordx4 v[152:155], v214, s[48:49] offset:768
	global_load_dwordx4 v[156:159], v214, s[48:49] offset:832
	global_load_dwordx4 v[160:163], v214, s[48:49] offset:896
	global_load_dwordx4 v[164:167], v214, s[48:49] offset:960
	global_load_dwordx4 v[168:171], v214, s[50:51] offset:768
	global_load_dwordx4 v[184:187], v214, s[50:51] offset:832
	global_load_dwordx4 v[188:191], v214, s[50:51] offset:896
	global_load_dwordx4 v[192:195], v214, s[50:51] offset:960
	global_load_dwordx4 v[196:199], v214, s[52:53] offset:768
	global_load_dwordx4 v[200:203], v214, s[52:53] offset:832
	global_load_dwordx4 v[204:207], v214, s[52:53] offset:896
	global_load_dwordx4 v[208:211], v214, s[52:53] offset:960
	s_waitcnt vmcnt(20)
	v_mfma_f32_16x16x32_bf16 v[4:7], v[36:39], v[52:55], v[4:7]
	v_mfma_f32_16x16x32_bf16 v[8:11], v[36:39], v[68:71], v[8:11]
	v_mfma_f32_16x16x32_bf16 v[20:23], v[36:39], v[84:87], v[20:23]
	v_mfma_f32_16x16x32_bf16 v[32:35], v[36:39], v[100:103], v[32:35]
	v_mfma_f32_16x16x32_bf16 v[4:7], v[40:43], v[56:59], v[4:7]
	v_mfma_f32_16x16x32_bf16 v[8:11], v[40:43], v[72:75], v[8:11]
	v_mfma_f32_16x16x32_bf16 v[20:23], v[40:43], v[88:91], v[20:23]
	v_mfma_f32_16x16x32_bf16 v[32:35], v[40:43], v[104:107], v[32:35]
	v_mfma_f32_16x16x32_bf16 v[4:7], v[44:47], v[60:63], v[4:7]
	v_mfma_f32_16x16x32_bf16 v[8:11], v[44:47], v[76:79], v[8:11]
	v_mfma_f32_16x16x32_bf16 v[20:23], v[44:47], v[92:95], v[20:23]
	v_mfma_f32_16x16x32_bf16 v[32:35], v[44:47], v[108:111], v[32:35]
	v_mfma_f32_16x16x32_bf16 v[4:7], v[48:51], v[64:67], v[4:7]
	v_mfma_f32_16x16x32_bf16 v[8:11], v[48:51], v[80:83], v[8:11]
	v_mfma_f32_16x16x32_bf16 v[20:23], v[48:51], v[96:99], v[20:23]
	v_mfma_f32_16x16x32_bf16 v[32:35], v[48:51], v[112:115], v[32:35]
	s_waitcnt vmcnt(0)
	v_mfma_f32_16x16x32_bf16 v[4:7], v[120:123], v[136:139], v[4:7]
	v_mfma_f32_16x16x32_bf16 v[8:11], v[120:123], v[152:155], v[8:11]
	v_mfma_f32_16x16x32_bf16 v[20:23], v[120:123], v[168:171], v[20:23]
	v_mfma_f32_16x16x32_bf16 v[32:35], v[120:123], v[196:199], v[32:35]
	v_mfma_f32_16x16x32_bf16 v[4:7], v[124:127], v[140:143], v[4:7]
	v_mfma_f32_16x16x32_bf16 v[8:11], v[124:127], v[156:159], v[8:11]
	v_mfma_f32_16x16x32_bf16 v[20:23], v[124:127], v[184:187], v[20:23]
	v_mfma_f32_16x16x32_bf16 v[32:35], v[124:127], v[200:203], v[32:35]
	v_mfma_f32_16x16x32_bf16 v[4:7], v[128:131], v[144:147], v[4:7]
	v_mfma_f32_16x16x32_bf16 v[8:11], v[128:131], v[160:163], v[8:11]
	v_mfma_f32_16x16x32_bf16 v[20:23], v[128:131], v[188:191], v[20:23]
	v_mfma_f32_16x16x32_bf16 v[32:35], v[128:131], v[204:207], v[32:35]
	v_mfma_f32_16x16x32_bf16 v[4:7], v[132:135], v[148:151], v[4:7]
	v_mfma_f32_16x16x32_bf16 v[8:11], v[132:135], v[164:167], v[8:11]
	v_mfma_f32_16x16x32_bf16 v[20:23], v[132:135], v[192:195], v[20:23]
	v_mfma_f32_16x16x32_bf16 v[32:35], v[132:135], v[208:211], v[32:35]
	v_and_b32_e32 v18, 63, v172
	v_lshlrev_b32_e32 v18, 4, v18
	v_lshl_add_u32 v19, v116, 12, v18
	s_nop 5
	ds_write_b128 v19, v[4:7] offset:0
	ds_write_b128 v19, v[8:11] offset:1024
	ds_write_b128 v19, v[20:23] offset:2048
	ds_write_b128 v19, v[32:35] offset:3072
	s_waitcnt lgkmcnt(0)
	s_barrier
; template <class F> __device__ __forceinline__ void skinny_tile_sk(const GAS bf16* A, int lda, const GAS bf16* Bt, int K, int n0, int wave, int lane, float* red, F&& epi) {
;     ...
;     if (wave == 0) { f32x4 s = {0.f, 0.f, 0.f, 0.f};
; #pragma unroll
;         for (int w = 0; w < 8; ++w) s += *(const f32x4*)(red + w * 256 + lane * 4);
; #pragma unroll
;         for (int j = 0; j < 4; ++j) epi(fq * 4 + j, j, n0 + fr, s[j]); }
	v_lshrrev_b32_e32 v19, 2, v116
	v_lshl_add_u32 v19, v19, 14, v18
	v_lshl_add_u32 v19, v117, 10, v19
	ds_read_b128 v[36:39], v19 offset:0
	ds_read_b128 v[40:43], v19 offset:4096
	ds_read_b128 v[44:47], v19 offset:8192
	ds_read_b128 v[48:51], v19 offset:12288
	s_waitcnt lgkmcnt(0)
	v_add_f32_e32 v4, v36, v40
	v_add_f32_e32 v8, v44, v48
	v_add_f32_e32 v5, v37, v41
	v_add_f32_e32 v9, v45, v49
	v_add_f32_e32 v6, v38, v42
	v_add_f32_e32 v10, v46, v50
	v_add_f32_e32 v7, v39, v43
	v_add_f32_e32 v11, v47, v51
	v_add_f32_e32 v4, v4, v8
	v_add_f32_e32 v5, v5, v9
	v_add_f32_e32 v6, v6, v10
	v_add_f32_e32 v7, v7, v11
	v_mov_b32_e32 v8, 0
	v_mov_b32_e32 v9, 0
	v_mov_b32_e32 v10, 0
	v_mov_b32_e32 v11, 0
	v_or_b32_e32 v16, v16, v29
	v_lshlrev_b32_e32 v174, 2, v17
	v_ashrrev_i32_e32 v17, 31, v16
	v_lshl_add_u64 v[18:19], v[16:17], 2, s[14:15]
	s_branch .Lsg1_join

; #define GAS __attribute__((address_space(1)))
; __device__ __forceinline__ f32x4 mfma16(const bf16x8& a, const bf16x8& b, const f32x4& c) { return __builtin_amdgcn_mfma_f32_16x16x32_bf16(a, b, c, 0, 0, 0); }
; template <class F> __device__ __forceinline__ void skinny_tile(const GAS bf16* A, int lda, const GAS bf16* Bt, int K, int n0, int lane, F&& epi) {
;     const int fr = lane & 15, fq = lane >> 4;
;     const GAS bf16* ap = A + (size_t)fr * lda + fq * 8; const GAS bf16* bp = Bt + (size_t)(n0 + fr) * K + fq * 8;
;     f32x4 acc0 = {0.f, 0.f, 0.f, 0.f}, acc1 = {0.f, 0.f, 0.f, 0.f};
;     bf16x8 a[4], bb[4], a2[4], b2[4];
; #pragma unroll
;     for (int i = 0; i < 4; ++i) { a[i] = *(const GAS bf16x8*)(ap + i * 32); bb[i] = *(const GAS bf16x8*)(bp + i * 32); }
;     for (int k = 0; k < K; k += 256) {
; #pragma unroll
;         for (int i = 0; i < 4; ++i) { a2[i] = *(const GAS bf16x8*)(ap + k + 128 + i * 32); b2[i] = *(const GAS bf16x8*)(bp + k + 128 + i * 32); }
; #pragma unroll
;         for (int i = 0; i < 4; i += 2) { acc0 = mfma16(a[i], bb[i], acc0); acc1 = mfma16(a[i + 1], bb[i + 1], acc1); }
;         if (k + 256 < K) {
; #pragma unroll
;             for (int i = 0; i < 4; ++i) { a[i] = *(const GAS bf16x8*)(ap + k + 256 + i * 32); bb[i] = *(const GAS bf16x8*)(bp + k + 256 + i * 32); } }
; #pragma unroll
;         for (int i = 0; i < 4; i += 2) { acc0 = mfma16(a2[i], b2[i], acc0); acc1 = mfma16(a2[i + 1], b2[i + 1], acc1); } }
; __device__ __forceinline__ void side_gemm1(const Params& P, int seg) {
;     ...
;     for (int it = gw; it < nrt * 4; it += NGW) { const int rt = it >> 2, r0 = (rt < RS / 16) ? rt * 16 : RS + 48;
;         skinny_tile(xb + (size_t)r0 * DM, DM, Wt + (size_t)NPROJ * DM, DM, (it & 3) * 16, lane, [&](int row, int j, int col, float v) {
.LBB0_96:
	v_ashrrev_i32_e32 v4, 2, v31
	s_movk_i32 s24, 0x200
	v_cmp_gt_i32_e32 vcc, s24, v4
	v_lshlrev_b32_e32 v4, 4, v4
	s_nop 0
	v_cndmask_b32_e32 v16, v239, v4, vcc
	v_ashrrev_i32_e32 v17, 31, v16
	v_lshlrev_b64 v[4:5], 12, v[16:17]
	v_and_or_b32 v17, v30, 48, v28
	v_lshl_add_u64 v[4:5], v[12:13], 0, v[4:5]
	v_lshlrev_b32_e32 v174, 12, v17
	v_lshl_add_u64 v[6:7], v[14:15], 0, v[174:175]
	s_cmp_eq_u32 s100, 1
	s_cbranch_scc1 .Lsg1_new
	global_load_dwordx4 v[8:11], v[4:5], off
	global_load_dwordx4 v[18:21], v[6:7], off
	global_load_dwordx4 v[32:35], v[4:5], off offset:64
	global_load_dwordx4 v[36:39], v[6:7], off offset:64
	global_load_dwordx4 v[40:43], v[4:5], off offset:128
	global_load_dwordx4 v[44:47], v[6:7], off offset:128
	global_load_dwordx4 v[48:51], v[4:5], off offset:192
	global_load_dwordx4 v[52:55], v[6:7], off offset:192
	global_load_dwordx4 v[56:59], v[4:5], off offset:256
	global_load_dwordx4 v[60:63], v[6:7], off offset:256
	global_load_dwordx4 v[64:67], v[4:5], off offset:320
	global_load_dwordx4 v[68:71], v[6:7], off offset:320
	global_load_dwordx4 v[72:75], v[4:5], off offset:384
	global_load_dwordx4 v[76:79], v[6:7], off offset:384
	global_load_dwordx4 v[80:83], v[4:5], off offset:448
	global_load_dwordx4 v[84:87], v[6:7], off offset:448
	v_or_b32_e32 v16, v16, v29
	v_lshlrev_b32_e32 v174, 2, v17
	v_ashrrev_i32_e32 v17, 31, v16
	s_waitcnt vmcnt(14)
	v_mfma_f32_16x16x32_bf16 v[8:11], v[8:11], v[18:21], 0
	s_waitcnt vmcnt(12)
	v_mfma_f32_16x16x32_bf16 v[18:21], v[32:35], v[36:39], 0
	s_waitcnt vmcnt(10)
	v_mfma_f32_16x16x32_bf16 v[8:11], v[40:43], v[44:47], v[8:11]
	s_waitcnt vmcnt(8)
	v_mfma_f32_16x16x32_bf16 v[18:21], v[48:51], v[52:55], v[18:21]
	global_load_dwordx4 v[32:35], v[6:7], off offset:704
	global_load_dwordx4 v[36:39], v[4:5], off offset:512
	global_load_dwordx4 v[40:43], v[4:5], off offset:576
	global_load_dwordx4 v[44:47], v[4:5], off offset:640
	global_load_dwordx4 v[48:51], v[4:5], off offset:704
	global_load_dwordx4 v[52:55], v[6:7], off offset:640
	global_load_dwordx4 v[88:91], v[6:7], off offset:576
	global_load_dwordx4 v[92:95], v[6:7], off offset:512
	s_waitcnt vmcnt(14)
	v_mfma_f32_16x16x32_bf16 v[8:11], v[56:59], v[60:63], v[8:11]
	s_waitcnt vmcnt(12)
	v_mfma_f32_16x16x32_bf16 v[18:21], v[64:67], v[68:71], v[18:21]
	s_waitcnt vmcnt(10)
	v_mfma_f32_16x16x32_bf16 v[8:11], v[72:75], v[76:79], v[8:11]
	s_waitcnt vmcnt(8)
	v_mfma_f32_16x16x32_bf16 v[18:21], v[80:83], v[84:87], v[18:21]
	global_load_dwordx4 v[56:59], v[4:5], off offset:768
	global_load_dwordx4 v[60:63], v[6:7], off offset:768
	global_load_dwordx4 v[64:67], v[4:5], off offset:832
	global_load_dwordx4 v[68:71], v[6:7], off offset:832
	global_load_dwordx4 v[72:75], v[4:5], off offset:896
	global_load_dwordx4 v[76:79], v[6:7], off offset:896
	global_load_dwordx4 v[80:83], v[4:5], off offset:960
	global_load_dwordx4 v[84:87], v[6:7], off offset:960
	s_waitcnt vmcnt(9)
	v_mfma_f32_16x16x32_bf16 v[18:21], v[40:43], v[88:91], v[18:21]
	s_waitcnt vmcnt(8)
	v_mfma_f32_16x16x32_bf16 v[8:11], v[36:39], v[92:95], v[8:11]
	v_mfma_f32_16x16x32_bf16 v[8:11], v[44:47], v[52:55], v[8:11]
	v_mfma_f32_16x16x32_bf16 v[18:21], v[48:51], v[32:35], v[18:21]
	global_load_dwordx4 v[32:35], v[6:7], off offset:1216
	global_load_dwordx4 v[36:39], v[4:5], off offset:1024
	global_load_dwordx4 v[40:43], v[4:5], off offset:1088
	global_load_dwordx4 v[44:47], v[4:5], off offset:1152
	global_load_dwordx4 v[48:51], v[4:5], off offset:1216
	global_load_dwordx4 v[52:55], v[6:7], off offset:1152
	global_load_dwordx4 v[88:91], v[6:7], off offset:1088
	global_load_dwordx4 v[92:95], v[6:7], off offset:1024
	s_waitcnt vmcnt(14)
	v_mfma_f32_16x16x32_bf16 v[8:11], v[56:59], v[60:63], v[8:11]
	s_waitcnt vmcnt(12)
	v_mfma_f32_16x16x32_bf16 v[18:21], v[64:67], v[68:71], v[18:21]
	s_waitcnt vmcnt(10)
	v_mfma_f32_16x16x32_bf16 v[8:11], v[72:75], v[76:79], v[8:11]
	s_waitcnt vmcnt(8)
	v_mfma_f32_16x16x32_bf16 v[18:21], v[80:83], v[84:87], v[18:21]
	global_load_dwordx4 v[56:59], v[4:5], off offset:1280
	global_load_dwordx4 v[60:63], v[6:7], off offset:1280
	global_load_dwordx4 v[64:67], v[4:5], off offset:1344
	global_load_dwordx4 v[68:71], v[6:7], off offset:1344
	global_load_dwordx4 v[72:75], v[4:5], off offset:1408
	global_load_dwordx4 v[76:79], v[6:7], off offset:1408
	global_load_dwordx4 v[80:83], v[4:5], off offset:1472
	global_load_dwordx4 v[84:87], v[6:7], off offset:1472
	s_waitcnt vmcnt(9)
	v_mfma_f32_16x16x32_bf16 v[18:21], v[40:43], v[88:91], v[18:21]
	s_waitcnt vmcnt(8)
	v_mfma_f32_16x16x32_bf16 v[8:11], v[36:39], v[92:95], v[8:11]
	v_mfma_f32_16x16x32_bf16 v[8:11], v[44:47], v[52:55], v[8:11]
	v_mfma_f32_16x16x32_bf16 v[18:21], v[48:51], v[32:35], v[18:21]
	global_load_dwordx4 v[32:35], v[6:7], off offset:1728
	global_load_dwordx4 v[36:39], v[4:5], off offset:1536
	global_load_dwordx4 v[40:43], v[4:5], off offset:1600
	global_load_dwordx4 v[44:47], v[4:5], off offset:1664
	global_load_dwordx4 v[48:51], v[4:5], off offset:1728
	global_load_dwordx4 v[52:55], v[6:7], off offset:1664
	global_load_dwordx4 v[88:91], v[6:7], off offset:1600
	global_load_dwordx4 v[92:95], v[6:7], off offset:1536
	s_waitcnt vmcnt(14)
	v_mfma_f32_16x16x32_bf16 v[8:11], v[56:59], v[60:63], v[8:11]
	s_waitcnt vmcnt(12)
	v_mfma_f32_16x16x32_bf16 v[18:21], v[64:67], v[68:71], v[18:21]
	s_waitcnt vmcnt(10)
	v_mfma_f32_16x16x32_bf16 v[8:11], v[72:75], v[76:79], v[8:11]
	s_waitcnt vmcnt(8)
; #define GAS __attribute__((address_space(1)))
; __device__ __forceinline__ f32x4 mfma16(const bf16x8& a, const bf16x8& b, const f32x4& c) { return __builtin_amdgcn_mfma_f32_16x16x32_bf16(a, b, c, 0, 0, 0); }
; template <class F> __device__ __forceinline__ void skinny_tile(const GAS bf16* A, int lda, const GAS bf16* Bt, int K, int n0, int lane, F&& epi) {
;     ...
;     for (int k = 0; k < K; k += 256) {
; #pragma unroll
;         for (int i = 0; i < 4; ++i) { a2[i] = *(const GAS bf16x8*)(ap + k + 128 + i * 32); b2[i] = *(const GAS bf16x8*)(bp + k + 128 + i * 32); }
; #pragma unroll
;         for (int i = 0; i < 4; i += 2) { acc0 = mfma16(a[i], bb[i], acc0); acc1 = mfma16(a[i + 1], bb[i + 1], acc1); }
;         if (k + 256 < K) {
; #pragma unroll
;             for (int i = 0; i < 4; ++i) { a[i] = *(const GAS bf16x8*)(ap + k + 256 + i * 32); bb[i] = *(const GAS bf16x8*)(bp + k + 256 + i * 32); } }
; #pragma unroll
;         for (int i = 0; i < 4; i += 2) { acc0 = mfma16(a2[i], b2[i], acc0); acc1 = mfma16(a2[i + 1], b2[i + 1], acc1); } }
	v_mfma_f32_16x16x32_bf16 v[18:21], v[80:83], v[84:87], v[18:21]
	global_load_dwordx4 v[56:59], v[4:5], off offset:1792
	global_load_dwordx4 v[60:63], v[6:7], off offset:1792
	global_load_dwordx4 v[64:67], v[4:5], off offset:1856
	global_load_dwordx4 v[68:71], v[6:7], off offset:1856
	global_load_dwordx4 v[72:75], v[4:5], off offset:1920
	global_load_dwordx4 v[76:79], v[6:7], off offset:1920
	global_load_dwordx4 v[80:83], v[4:5], off offset:1984
	global_load_dwordx4 v[84:87], v[6:7], off offset:1984
	s_waitcnt vmcnt(9)
	v_mfma_f32_16x16x32_bf16 v[18:21], v[40:43], v[88:91], v[18:21]
	s_waitcnt vmcnt(8)
	v_mfma_f32_16x16x32_bf16 v[8:11], v[36:39], v[92:95], v[8:11]
	v_mfma_f32_16x16x32_bf16 v[8:11], v[44:47], v[52:55], v[8:11]
	v_mfma_f32_16x16x32_bf16 v[18:21], v[48:51], v[32:35], v[18:21]
	global_load_dwordx4 v[32:35], v[6:7], off offset:2240
	global_load_dwordx4 v[36:39], v[4:5], off offset:2048
	global_load_dwordx4 v[40:43], v[4:5], off offset:2112
	global_load_dwordx4 v[44:47], v[4:5], off offset:2176
	global_load_dwordx4 v[48:51], v[4:5], off offset:2240
	global_load_dwordx4 v[52:55], v[6:7], off offset:2176
	global_load_dwordx4 v[88:91], v[6:7], off offset:2112
	global_load_dwordx4 v[92:95], v[6:7], off offset:2048
	s_waitcnt vmcnt(14)
	v_mfma_f32_16x16x32_bf16 v[8:11], v[56:59], v[60:63], v[8:11]
	s_waitcnt vmcnt(12)
	v_mfma_f32_16x16x32_bf16 v[18:21], v[64:67], v[68:71], v[18:21]
	s_waitcnt vmcnt(10)
	v_mfma_f32_16x16x32_bf16 v[8:11], v[72:75], v[76:79], v[8:11]
	s_waitcnt vmcnt(8)
	v_mfma_f32_16x16x32_bf16 v[18:21], v[80:83], v[84:87], v[18:21]
	global_load_dwordx4 v[56:59], v[4:5], off offset:2304
	global_load_dwordx4 v[60:63], v[6:7], off offset:2304
	global_load_dwordx4 v[64:67], v[4:5], off offset:2368
	global_load_dwordx4 v[68:71], v[6:7], off offset:2368
	global_load_dwordx4 v[72:75], v[4:5], off offset:2432
	global_load_dwordx4 v[76:79], v[6:7], off offset:2432
	global_load_dwordx4 v[80:83], v[4:5], off offset:2496
	global_load_dwordx4 v[84:87], v[6:7], off offset:2496
	s_waitcnt vmcnt(9)
	v_mfma_f32_16x16x32_bf16 v[18:21], v[40:43], v[88:91], v[18:21]
	s_waitcnt vmcnt(8)
	v_mfma_f32_16x16x32_bf16 v[8:11], v[36:39], v[92:95], v[8:11]
	v_mfma_f32_16x16x32_bf16 v[8:11], v[44:47], v[52:55], v[8:11]
	v_mfma_f32_16x16x32_bf16 v[18:21], v[48:51], v[32:35], v[18:21]
	global_load_dwordx4 v[32:35], v[6:7], off offset:2752
	global_load_dwordx4 v[36:39], v[4:5], off offset:2560
	global_load_dwordx4 v[40:43], v[4:5], off offset:2624
	global_load_dwordx4 v[44:47], v[4:5], off offset:2688
	global_load_dwordx4 v[48:51], v[4:5], off offset:2752
	global_load_dwordx4 v[52:55], v[6:7], off offset:2688
	global_load_dwordx4 v[88:91], v[6:7], off offset:2624
	global_load_dwordx4 v[92:95], v[6:7], off offset:2560
	s_waitcnt vmcnt(14)
	v_mfma_f32_16x16x32_bf16 v[8:11], v[56:59], v[60:63], v[8:11]
	s_waitcnt vmcnt(12)
	v_mfma_f32_16x16x32_bf16 v[18:21], v[64:67], v[68:71], v[18:21]
	s_waitcnt vmcnt(10)
	v_mfma_f32_16x16x32_bf16 v[8:11], v[72:75], v[76:79], v[8:11]
	s_waitcnt vmcnt(8)
	v_mfma_f32_16x16x32_bf16 v[18:21], v[80:83], v[84:87], v[18:21]
	global_load_dwordx4 v[56:59], v[4:5], off offset:2816
	global_load_dwordx4 v[60:63], v[6:7], off offset:2816
	global_load_dwordx4 v[64:67], v[4:5], off offset:2880
	global_load_dwordx4 v[68:71], v[6:7], off offset:2880
	global_load_dwordx4 v[72:75], v[4:5], off offset:2944
	global_load_dwordx4 v[76:79], v[6:7], off offset:2944
	global_load_dwordx4 v[80:83], v[4:5], off offset:3008
	global_load_dwordx4 v[84:87], v[6:7], off offset:3008
	s_waitcnt vmcnt(9)
	v_mfma_f32_16x16x32_bf16 v[18:21], v[40:43], v[88:91], v[18:21]
	s_waitcnt vmcnt(8)
	v_mfma_f32_16x16x32_bf16 v[8:11], v[36:39], v[92:95], v[8:11]
	v_mfma_f32_16x16x32_bf16 v[8:11], v[44:47], v[52:55], v[8:11]
	v_mfma_f32_16x16x32_bf16 v[18:21], v[48:51], v[32:35], v[18:21]
	global_load_dwordx4 v[32:35], v[6:7], off offset:3264
	global_load_dwordx4 v[36:39], v[4:5], off offset:3072
	global_load_dwordx4 v[40:43], v[4:5], off offset:3136
	global_load_dwordx4 v[44:47], v[4:5], off offset:3200
	global_load_dwordx4 v[48:51], v[4:5], off offset:3264
	global_load_dwordx4 v[52:55], v[6:7], off offset:3200
	global_load_dwordx4 v[88:91], v[6:7], off offset:3136
	global_load_dwordx4 v[92:95], v[6:7], off offset:3072
	s_waitcnt vmcnt(14)
	v_mfma_f32_16x16x32_bf16 v[8:11], v[56:59], v[60:63], v[8:11]
	s_waitcnt vmcnt(12)
	v_mfma_f32_16x16x32_bf16 v[18:21], v[64:67], v[68:71], v[18:21]
	s_waitcnt vmcnt(10)
	v_mfma_f32_16x16x32_bf16 v[8:11], v[72:75], v[76:79], v[8:11]
	s_waitcnt vmcnt(8)
	v_mfma_f32_16x16x32_bf16 v[18:21], v[80:83], v[84:87], v[18:21]
	global_load_dwordx4 v[56:59], v[4:5], off offset:3328
	global_load_dwordx4 v[60:63], v[6:7], off offset:3328
	global_load_dwordx4 v[64:67], v[4:5], off offset:3392
	global_load_dwordx4 v[68:71], v[6:7], off offset:3392
	global_load_dwordx4 v[72:75], v[4:5], off offset:3456
	global_load_dwordx4 v[76:79], v[6:7], off offset:3456
	global_load_dwordx4 v[80:83], v[4:5], off offset:3520
	global_load_dwordx4 v[84:87], v[6:7], off offset:3520
	s_waitcnt vmcnt(9)
	v_mfma_f32_16x16x32_bf16 v[18:21], v[40:43], v[88:91], v[18:21]
	s_waitcnt vmcnt(8)
	v_mfma_f32_16x16x32_bf16 v[8:11], v[36:39], v[92:95], v[8:11]
	v_mfma_f32_16x16x32_bf16 v[8:11], v[44:47], v[52:55], v[8:11]
	v_mfma_f32_16x16x32_bf16 v[18:21], v[48:51], v[32:35], v[18:21]
	global_load_dwordx4 v[32:35], v[6:7], off offset:3776
	global_load_dwordx4 v[36:39], v[4:5], off offset:3584
	global_load_dwordx4 v[40:43], v[4:5], off offset:3648
	global_load_dwordx4 v[44:47], v[4:5], off offset:3712
	global_load_dwordx4 v[48:51], v[4:5], off offset:3776
	global_load_dwordx4 v[52:55], v[6:7], off offset:3712
	global_load_dwordx4 v[88:91], v[6:7], off offset:3648
	global_load_dwordx4 v[92:95], v[6:7], off offset:3584
	s_waitcnt vmcnt(14)
; __device__ __forceinline__ f32x4 mfma16(const bf16x8& a, const bf16x8& b, const f32x4& c) { return __builtin_amdgcn_mfma_f32_16x16x32_bf16(a, b, c, 0, 0, 0); }
; template <class F> __device__ __forceinline__ void skinny_tile(const GAS bf16* A, int lda, const GAS bf16* Bt, int K, int n0, int lane, F&& epi) {
;     ...
;         for (int i = 0; i < 4; i += 2) { acc0 = mfma16(a2[i], b2[i], acc0); acc1 = mfma16(a2[i + 1], b2[i + 1], acc1); } }
; #pragma unroll
;     for (int j = 0; j < 4; ++j) epi(fq * 4 + j, j, n0 + fr, acc0[j] + acc1[j]);
; __device__ __forceinline__ void side_gemm1(const Params& P, int seg) {
;     ...
;         skinny_tile(xb + (size_t)r0 * DM, DM, Wt + (size_t)NPROJ * DM, DM, (it & 3) * 16, lane, [&](int row, int j, int col, float v) {
;             const float t = v * rstd1[r0 + row] + P.dt_bias[col]; dtv[(size_t)(r0 + row) * 64 + col] = (t > 20.f) ? t : log1pf(__expf(t)); }); }
	v_mfma_f32_16x16x32_bf16 v[8:11], v[56:59], v[60:63], v[8:11]
	s_waitcnt vmcnt(12)
	v_mfma_f32_16x16x32_bf16 v[18:21], v[64:67], v[68:71], v[18:21]
	s_waitcnt vmcnt(10)
	v_mfma_f32_16x16x32_bf16 v[8:11], v[72:75], v[76:79], v[8:11]
	s_waitcnt vmcnt(8)
	v_mfma_f32_16x16x32_bf16 v[18:21], v[80:83], v[84:87], v[18:21]
	global_load_dwordx4 v[56:59], v[4:5], off offset:3840
	global_load_dwordx4 v[60:63], v[6:7], off offset:3840
	global_load_dwordx4 v[64:67], v[4:5], off offset:3904
	global_load_dwordx4 v[68:71], v[6:7], off offset:3904
	global_load_dwordx4 v[72:75], v[4:5], off offset:3968
	global_load_dwordx4 v[76:79], v[6:7], off offset:3968
	global_load_dwordx4 v[80:83], v[4:5], off offset:4032
	global_load_dwordx4 v[84:87], v[6:7], off offset:4032
	s_waitcnt vmcnt(8)
	v_mfma_f32_16x16x32_bf16 v[4:7], v[36:39], v[92:95], v[8:11]
	v_mfma_f32_16x16x32_bf16 v[8:11], v[40:43], v[88:91], v[18:21]
	v_mfma_f32_16x16x32_bf16 v[4:7], v[44:47], v[52:55], v[4:7]
	s_nop 1
	v_lshl_add_u64 v[18:19], v[16:17], 2, s[14:15]
	v_mfma_f32_16x16x32_bf16 v[8:11], v[48:51], v[32:35], v[8:11]
	s_waitcnt vmcnt(6)
	v_mfma_f32_16x16x32_bf16 v[4:7], v[56:59], v[60:63], v[4:7]
	s_waitcnt vmcnt(4)
	v_mfma_f32_16x16x32_bf16 v[8:11], v[64:67], v[68:71], v[8:11]
	s_waitcnt vmcnt(2)
	v_mfma_f32_16x16x32_bf16 v[4:7], v[72:75], v[76:79], v[4:7]
	s_waitcnt vmcnt(0)
	v_mfma_f32_16x16x32_bf16 v[8:11], v[80:83], v[84:87], v[8:11]
.Lsg1_join:
	s_nop 7
	v_add_f32_e32 v4, v4, v8
	global_load_dword v8, v[18:19], off
	global_load_dword v32, v174, s[44:45]
	global_load_dword v216, v[18:19], off offset:4
	global_load_dword v217, v[18:19], off offset:8
	global_load_dword v218, v[18:19], off offset:12
	s_waitcnt vmcnt(0)
	v_mov_b32_e32 v219, v32
	v_fmac_f32_e32 v32, v8, v4
	v_cmp_nlt_f32_e32 vcc, s28, v32
	s_and_saveexec_b64 s[26:27], vcc
	s_cbranch_execz .LBB0_98
	v_mul_f32_e32 v4, 0x3fb8aa3b, v32
	v_exp_f32_e32 v4, v4
	s_nop 0
	v_add_f32_e32 v8, 1.0, v4
	v_frexp_mant_f32_e32 v23, v8
	v_cvt_f64_f32_e32 v[20:21], v8
	v_add_f32_e32 v22, -1.0, v8
	v_frexp_exp_i32_f64_e32 v20, v[20:21]
	v_cmp_gt_f32_e32 vcc, s29, v23
	v_sub_f32_e32 v32, v22, v8
	v_sub_f32_e32 v22, v4, v22
	v_subbrev_co_u32_e32 v36, vcc, 0, v20, vcc
	v_add_f32_e32 v32, 1.0, v32
	v_sub_u32_e32 v20, 0, v36
	v_add_f32_e32 v22, v22, v32
	v_ldexp_f32 v8, v8, v20
	v_ldexp_f32 v20, v22, v20
	v_add_f32_e32 v22, -1.0, v8
	v_add_f32_e32 v21, 1.0, v22
	v_sub_f32_e32 v21, v8, v21
	v_add_f32_e32 v23, v20, v21
	v_add_f32_e32 v21, 1.0, v8
	v_add_f32_e32 v32, -1.0, v21
	v_sub_f32_e32 v8, v8, v32
	v_add_f32_e32 v8, v20, v8
	v_add_f32_e32 v37, v21, v8
	v_rcp_f32_e32 v38, v37
	v_sub_f32_e32 v20, v37, v21
	v_add_f32_e32 v21, v22, v23
	v_sub_f32_e32 v8, v8, v20
	v_mul_f32_e32 v40, v21, v38
	v_sub_f32_e32 v20, v21, v22
	v_mul_f32_e32 v22, v37, v40
	v_fma_f32 v32, v40, v37, -v22
	v_fmac_f32_e32 v32, v40, v8
	v_sub_f32_e32 v39, v23, v20
	v_add_f32_e32 v20, v22, v32
	v_sub_f32_e32 v23, v21, v20
	v_pk_add_f32 v[34:35], v[20:21], v[22:23] neg_lo:[0,1] neg_hi:[0,1]
	v_mov_b32_e32 v33, v20
	v_pk_add_f32 v[20:21], v[34:35], v[32:33] neg_lo:[0,1] neg_hi:[0,1]
	v_cmp_neq_f32_e32 vcc, s31, v4
	v_add_f32_e32 v21, v39, v21
	v_add_f32_e32 v20, v20, v21
	v_add_f32_e32 v21, v23, v20
	v_mul_f32_e32 v39, v38, v21
	v_mul_f32_e32 v22, v37, v39
	v_fma_f32 v32, v39, v37, -v22
	v_fmac_f32_e32 v32, v39, v8
	v_sub_f32_e32 v8, v23, v21
	v_add_f32_e32 v8, v20, v8
	v_add_f32_e32 v20, v22, v32
	v_sub_f32_e32 v23, v21, v20
	v_pk_add_f32 v[34:35], v[20:21], v[22:23] neg_lo:[0,1] neg_hi:[0,1]
	v_mov_b32_e32 v33, v20
	v_pk_add_f32 v[20:21], v[34:35], v[32:33] neg_lo:[0,1] neg_hi:[0,1]
	s_nop 0
	v_add_f32_e32 v8, v8, v21
	v_add_f32_e32 v8, v20, v8
	v_add_f32_e32 v21, v40, v39
	v_add_f32_e32 v8, v23, v8
	v_sub_f32_e32 v20, v21, v40
	v_mul_f32_e32 v8, v38, v8
	v_sub_f32_e32 v20, v39, v20
	v_add_f32_e32 v8, v20, v8
	v_add_f32_e32 v22, v21, v8
	v_mul_f32_e32 v32, v22, v22
	v_fmamk_f32 v20, v32, 0x3e9b6dac, v177
	v_fmaak_f32 v179, v32, v20, 0x3f2aaada
	v_cvt_f32_i32_e32 v20, v36
	v_sub_f32_e32 v21, v22, v21
	v_sub_f32_e32 v8, v8, v21
	v_mul_f32_e32 v21, v22, v32
	v_pk_mul_f32 v[32:33], v[20:21], v[178:179]
	v_ldexp_f32 v23, v22, 1
	v_fma_f32 v22, v20, s30, -v32
	v_fmac_f32_e32 v22, 0xb102e308, v20
	v_pk_add_f32 v[20:21], v[32:33], v[22:23]
	v_ldexp_f32 v8, v8, 1
	v_sub_f32_e32 v23, v21, v23
	v_sub_f32_e32 v23, v33, v23
	v_add_f32_e32 v35, v8, v23
	v_mov_b32_e32 v34, v32
	v_pk_add_f32 v[32:33], v[20:21], v[32:33] neg_lo:[0,1] neg_hi:[0,1]
	v_pk_add_f32 v[36:37], v[20:21], v[34:35]
	v_mov_b32_e32 v23, v20
	v_mov_b32_e32 v33, v37
	v_pk_add_f32 v[38:39], v[22:23], v[32:33] neg_lo:[0,1] neg_hi:[0,1]
	v_pk_add_f32 v[22:23], v[22:23], v[32:33]
	v_mov_b32_e32 v34, v35
	v_pk_add_f32 v[32:33], v[22:23], v[20:21] op_sel:[1,0] op_sel_hi:[0,1] neg_lo:[0,1] neg_hi:[0,1]
	v_pk_add_f32 v[40:41], v[36:37], v[32:33] op_sel_hi:[1,0] neg_lo:[0,1] neg_hi:[0,1]
	v_mov_b32_e32 v36, v37
	v_mov_b32_e32 v37, v23
	v_pk_mov_b32 v[32:33], v[20:21], v[32:33] op_sel:[1,0]
	v_mov_b32_e32 v35, v20
	v_pk_add_f32 v[32:33], v[36:37], v[32:33] neg_lo:[0,1] neg_hi:[0,1]
	v_mov_b32_e32 v40, v38
	v_pk_add_f32 v[20:21], v[34:35], v[32:33] neg_lo:[0,1] neg_hi:[0,1]
	v_mov_b32_e32 v39, v23
	v_pk_add_f32 v[32:33], v[40:41], v[20:21]
	s_nop 0
	v_pk_add_f32 v[34:35], v[32:33], v[32:33] op_sel:[0,1] op_sel_hi:[1,0]
	s_nop 0
	v_pk_add_f32 v[22:23], v[22:23], v[34:35] op_sel:[1,0] op_sel_hi:[0,1]
	v_mov_b32_e32 v33, v22
	v_pk_add_f32 v[36:37], v[32:33], v[38:39] neg_lo:[0,1] neg_hi:[0,1]
	v_mov_b32_e32 v21, v34
	v_sub_f32_e32 v8, v32, v36
	v_pk_add_f32 v[20:21], v[20:21], v[36:37] neg_lo:[0,1] neg_hi:[0,1]
	v_sub_f32_e32 v8, v38, v8
	v_add_f32_e32 v8, v20, v8
	v_add_f32_e32 v8, v8, v21
	v_add_f32_e32 v8, v22, v8
	v_cndmask_b32_e32 v8, v240, v8, vcc
	v_cmp_ngt_f32_e32 vcc, -1.0, v4
	s_nop 1
	v_cndmask_b32_e32 v8, v241, v8, vcc
	v_cmp_neq_f32_e32 vcc, -1.0, v4
	s_nop 1
	v_cndmask_b32_e32 v8, v242, v8, vcc
	v_cmp_lt_f32_e64 vcc, |v4|, s38
	s_nop 1
	v_cndmask_b32_e32 v32, v8, v4, vcc
; __device__ __forceinline__ void side_gemm1(const Params& P, int seg) {
;     ...
;         skinny_tile(xb + (size_t)r0 * DM, DM, Wt + (size_t)NPROJ * DM, DM, (it & 3) * 16, lane, [&](int row, int j, int col, float v) {
;             const float t = v * rstd1[r0 + row] + P.dt_bias[col]; dtv[(size_t)(r0 + row) * 64 + col] = (t > 20.f) ? t : log1pf(__expf(t)); }); }
.LBB0_98:
	s_or_b64 exec, exec, s[26:27]
	v_lshl_add_u64 v[20:21], s[42:43], 0, v[174:175]
	v_lshlrev_b64 v[34:35], 8, v[16:17]
	v_lshl_add_u64 v[34:35], v[20:21], 0, v[34:35]
	global_store_dword v[34:35], v32, off
	v_lshl_add_u64 v[22:23], s[44:45], 0, v[174:175]
	v_mov_b32_e32 v8, v216
	v_mov_b32_e32 v4, v219
	v_add_f32_e32 v5, v5, v9
	v_fmac_f32_e32 v4, v5, v8
	v_cmp_nlt_f32_e32 vcc, s28, v4
	s_and_saveexec_b64 s[26:27], vcc
	s_cbranch_execz .LBB0_100
	v_mul_f32_e32 v4, 0x3fb8aa3b, v4
	v_exp_f32_e32 v17, v4
	s_nop 0
	v_add_f32_e32 v8, 1.0, v17
	v_frexp_mant_f32_e32 v32, v8
	v_cvt_f64_f32_e32 v[4:5], v8
	v_frexp_exp_i32_f64_e32 v4, v[4:5]
	v_cmp_gt_f32_e32 vcc, s29, v32
	v_add_f32_e32 v9, -1.0, v8
	v_sub_f32_e32 v33, v9, v8
	v_subbrev_co_u32_e32 v36, vcc, 0, v4, vcc
	v_sub_u32_e32 v4, 0, v36
	v_sub_f32_e32 v9, v17, v9
	v_add_f32_e32 v33, 1.0, v33
	v_ldexp_f32 v5, v8, v4
	v_add_f32_e32 v9, v9, v33
	v_add_f32_e32 v8, -1.0, v5
	v_add_f32_e32 v32, 1.0, v5
	v_ldexp_f32 v4, v9, v4
	v_add_f32_e32 v9, 1.0, v8
	v_add_f32_e32 v33, -1.0, v32
	v_sub_f32_e32 v9, v5, v9
	v_sub_f32_e32 v5, v5, v33
	v_add_f32_e32 v9, v4, v9
	v_add_f32_e32 v4, v4, v5
	v_add_f32_e32 v37, v32, v4
	v_rcp_f32_e32 v39, v37
	v_sub_f32_e32 v5, v37, v32
	v_sub_f32_e32 v38, v4, v5
	v_add_f32_e32 v5, v8, v9
	v_mul_f32_e32 v41, v5, v39
	v_sub_f32_e32 v4, v5, v8
	v_mul_f32_e32 v8, v37, v41
	v_fma_f32 v32, v41, v37, -v8
	v_fmac_f32_e32 v32, v41, v38
	v_sub_f32_e32 v40, v9, v4
	v_add_f32_e32 v4, v8, v32
	v_sub_f32_e32 v9, v5, v4
	v_pk_add_f32 v[34:35], v[4:5], v[8:9] neg_lo:[0,1] neg_hi:[0,1]
	v_mov_b32_e32 v33, v4
	v_pk_add_f32 v[4:5], v[34:35], v[32:33] neg_lo:[0,1] neg_hi:[0,1]
	v_cmp_neq_f32_e32 vcc, s31, v17
	v_add_f32_e32 v5, v40, v5
	v_add_f32_e32 v4, v4, v5
	v_add_f32_e32 v5, v9, v4
	v_mul_f32_e32 v40, v39, v5
	v_mul_f32_e32 v8, v37, v40
	v_fma_f32 v32, v40, v37, -v8
	v_fmac_f32_e32 v32, v40, v38
	v_sub_f32_e32 v9, v9, v5
	v_add_f32_e32 v37, v4, v9
	v_add_f32_e32 v4, v8, v32
	v_sub_f32_e32 v9, v5, v4
	v_pk_add_f32 v[34:35], v[4:5], v[8:9] neg_lo:[0,1] neg_hi:[0,1]
	v_mov_b32_e32 v33, v4
	v_pk_add_f32 v[4:5], v[34:35], v[32:33] neg_lo:[0,1] neg_hi:[0,1]
	s_nop 0
	v_add_f32_e32 v5, v37, v5
	v_add_f32_e32 v4, v4, v5
	v_add_f32_e32 v5, v41, v40
	v_add_f32_e32 v4, v9, v4
	v_sub_f32_e32 v8, v5, v41
	v_mul_f32_e32 v4, v39, v4
	v_sub_f32_e32 v8, v40, v8
	v_add_f32_e32 v8, v8, v4
	v_add_f32_e32 v32, v5, v8
	v_mul_f32_e32 v33, v32, v32
	v_fmamk_f32 v4, v33, 0x3e9b6dac, v177
	v_fmaak_f32 v179, v33, v4, 0x3f2aaada
	v_cvt_f32_i32_e32 v4, v36
	v_sub_f32_e32 v5, v32, v5
	v_sub_f32_e32 v5, v8, v5
	v_ldexp_f32 v34, v5, 1
	v_mul_f32_e32 v5, v32, v33
	v_ldexp_f32 v9, v32, 1
	v_pk_mul_f32 v[32:33], v[4:5], v[178:179]
	s_nop 0
	v_fma_f32 v8, v4, s30, -v32
	v_fmac_f32_e32 v8, 0xb102e308, v4
	v_pk_add_f32 v[4:5], v[32:33], v[8:9]
	s_nop 0
	v_sub_f32_e32 v9, v5, v9
	v_sub_f32_e32 v9, v33, v9
	v_add_f32_e32 v35, v34, v9
	v_mov_b32_e32 v34, v32
	v_pk_add_f32 v[32:33], v[4:5], v[32:33] neg_lo:[0,1] neg_hi:[0,1]
	v_pk_add_f32 v[36:37], v[4:5], v[34:35]
	v_mov_b32_e32 v9, v4
	v_mov_b32_e32 v33, v37
	v_pk_add_f32 v[38:39], v[8:9], v[32:33] neg_lo:[0,1] neg_hi:[0,1]
	v_pk_add_f32 v[8:9], v[8:9], v[32:33]
	v_mov_b32_e32 v34, v35
	v_pk_add_f32 v[32:33], v[8:9], v[4:5] op_sel:[1,0] op_sel_hi:[0,1] neg_lo:[0,1] neg_hi:[0,1]
	v_pk_add_f32 v[40:41], v[36:37], v[32:33] op_sel_hi:[1,0] neg_lo:[0,1] neg_hi:[0,1]
	v_mov_b32_e32 v36, v37
	v_mov_b32_e32 v37, v9
	v_pk_mov_b32 v[32:33], v[4:5], v[32:33] op_sel:[1,0]
	v_mov_b32_e32 v35, v4
	v_pk_add_f32 v[32:33], v[36:37], v[32:33] neg_lo:[0,1] neg_hi:[0,1]
	v_mov_b32_e32 v40, v38
	v_pk_add_f32 v[4:5], v[34:35], v[32:33] neg_lo:[0,1] neg_hi:[0,1]
	v_mov_b32_e32 v39, v9
	v_pk_add_f32 v[32:33], v[40:41], v[4:5]
	s_nop 0
	v_pk_add_f32 v[34:35], v[32:33], v[32:33] op_sel:[0,1] op_sel_hi:[1,0]
	s_nop 0
	v_pk_add_f32 v[8:9], v[8:9], v[34:35] op_sel:[1,0] op_sel_hi:[0,1]
	v_mov_b32_e32 v33, v8
	v_pk_add_f32 v[36:37], v[32:33], v[38:39] neg_lo:[0,1] neg_hi:[0,1]
	v_mov_b32_e32 v5, v34
	v_sub_f32_e32 v9, v32, v36
	v_pk_add_f32 v[4:5], v[4:5], v[36:37] neg_lo:[0,1] neg_hi:[0,1]
	v_sub_f32_e32 v9, v38, v9
	v_add_f32_e32 v4, v4, v9
	v_add_f32_e32 v4, v4, v5
	v_add_f32_e32 v4, v8, v4
	v_cndmask_b32_e32 v4, v240, v4, vcc
	v_cmp_ngt_f32_e32 vcc, -1.0, v17
	s_nop 1
	v_cndmask_b32_e32 v4, v241, v4, vcc
	v_cmp_neq_f32_e32 vcc, -1.0, v17
	s_nop 1
	v_cndmask_b32_e32 v4, v242, v4, vcc
	v_cmp_lt_f32_e64 vcc, |v17|, s38
	s_nop 1
	v_cndmask_b32_e32 v4, v4, v17, vcc
; __device__ __forceinline__ void side_gemm1(const Params& P, int seg) {
;     ...
;         skinny_tile(xb + (size_t)r0 * DM, DM, Wt + (size_t)NPROJ * DM, DM, (it & 3) * 16, lane, [&](int row, int j, int col, float v) {
;             const float t = v * rstd1[r0 + row] + P.dt_bias[col]; dtv[(size_t)(r0 + row) * 64 + col] = (t > 20.f) ? t : log1pf(__expf(t)); }); }
.LBB0_100:
	s_or_b64 exec, exec, s[26:27]
	v_or_b32_e32 v8, 1, v16
	v_ashrrev_i32_e32 v9, 31, v8
	v_lshlrev_b64 v[8:9], 8, v[8:9]
	v_lshl_add_u64 v[8:9], v[20:21], 0, v[8:9]
	global_store_dword v[8:9], v4, off
	v_mov_b32_e32 v5, v217
	v_mov_b32_e32 v4, v219
	v_add_f32_e32 v6, v6, v10
	v_fmac_f32_e32 v4, v6, v5
	v_cmp_nlt_f32_e32 vcc, s28, v4
	s_and_saveexec_b64 s[26:27], vcc
	s_cbranch_execz .LBB0_102
	v_mul_f32_e32 v4, 0x3fb8aa3b, v4
	v_exp_f32_e32 v6, v4
	s_nop 0
	v_add_f32_e32 v8, 1.0, v6
	v_frexp_mant_f32_e32 v10, v8
	v_cvt_f64_f32_e32 v[4:5], v8
	v_frexp_exp_i32_f64_e32 v4, v[4:5]
	v_cmp_gt_f32_e32 vcc, s29, v10
	v_add_f32_e32 v9, -1.0, v8
	v_sub_f32_e32 v17, v9, v8
	v_subbrev_co_u32_e32 v10, vcc, 0, v4, vcc
	v_sub_u32_e32 v4, 0, v10
	v_sub_f32_e32 v9, v6, v9
	v_add_f32_e32 v17, 1.0, v17
	v_ldexp_f32 v5, v8, v4
	v_add_f32_e32 v9, v9, v17
	v_add_f32_e32 v8, -1.0, v5
	v_add_f32_e32 v17, 1.0, v5
	v_ldexp_f32 v4, v9, v4
	v_add_f32_e32 v9, 1.0, v8
	v_add_f32_e32 v32, -1.0, v17
	v_sub_f32_e32 v9, v5, v9
	v_sub_f32_e32 v5, v5, v32
	v_add_f32_e32 v9, v4, v9
	v_add_f32_e32 v4, v4, v5
	v_add_f32_e32 v36, v17, v4
	v_rcp_f32_e32 v37, v36
	v_sub_f32_e32 v5, v36, v17
	v_sub_f32_e32 v17, v4, v5
	v_add_f32_e32 v5, v8, v9
	v_mul_f32_e32 v39, v5, v37
	v_sub_f32_e32 v4, v5, v8
	v_mul_f32_e32 v8, v36, v39
	v_fma_f32 v32, v39, v36, -v8
	v_fmac_f32_e32 v32, v39, v17
	v_sub_f32_e32 v38, v9, v4
	v_add_f32_e32 v4, v8, v32
	v_sub_f32_e32 v9, v5, v4
	v_pk_add_f32 v[34:35], v[4:5], v[8:9] neg_lo:[0,1] neg_hi:[0,1]
	v_mov_b32_e32 v33, v4
	v_pk_add_f32 v[4:5], v[34:35], v[32:33] neg_lo:[0,1] neg_hi:[0,1]
	v_cmp_neq_f32_e32 vcc, s31, v6
	v_add_f32_e32 v5, v38, v5
	v_add_f32_e32 v4, v4, v5
	v_add_f32_e32 v5, v9, v4
	v_mul_f32_e32 v38, v37, v5
	v_mul_f32_e32 v8, v36, v38
	v_fma_f32 v32, v38, v36, -v8
	v_fmac_f32_e32 v32, v38, v17
	v_sub_f32_e32 v9, v9, v5
	v_add_f32_e32 v17, v4, v9
	v_add_f32_e32 v4, v8, v32
	v_sub_f32_e32 v9, v5, v4
	v_pk_add_f32 v[34:35], v[4:5], v[8:9] neg_lo:[0,1] neg_hi:[0,1]
	v_mov_b32_e32 v33, v4
	v_pk_add_f32 v[4:5], v[34:35], v[32:33] neg_lo:[0,1] neg_hi:[0,1]
	s_nop 0
	v_add_f32_e32 v5, v17, v5
	v_add_f32_e32 v4, v4, v5
	v_add_f32_e32 v5, v39, v38
	v_add_f32_e32 v4, v9, v4
	v_sub_f32_e32 v8, v5, v39
	v_mul_f32_e32 v4, v37, v4
	v_sub_f32_e32 v8, v38, v8
	v_add_f32_e32 v8, v8, v4
	v_add_f32_e32 v17, v5, v8
	v_mul_f32_e32 v32, v17, v17
	v_fmamk_f32 v4, v32, 0x3e9b6dac, v177
	v_fmaak_f32 v179, v32, v4, 0x3f2aaada
	v_cvt_f32_i32_e32 v4, v10
	v_sub_f32_e32 v5, v17, v5
	v_sub_f32_e32 v5, v8, v5
	v_ldexp_f32 v10, v5, 1
	v_mul_f32_e32 v5, v17, v32
	v_pk_mul_f32 v[32:33], v[4:5], v[178:179]
	v_ldexp_f32 v9, v17, 1
	v_fma_f32 v8, v4, s30, -v32
	v_fmac_f32_e32 v8, 0xb102e308, v4
	v_pk_add_f32 v[4:5], v[32:33], v[8:9]
	v_mov_b32_e32 v34, v32
	v_sub_f32_e32 v9, v5, v9
	v_sub_f32_e32 v9, v33, v9
	v_add_f32_e32 v35, v10, v9
	v_pk_add_f32 v[32:33], v[4:5], v[32:33] neg_lo:[0,1] neg_hi:[0,1]
	v_pk_add_f32 v[36:37], v[4:5], v[34:35]
	v_mov_b32_e32 v9, v4
	v_mov_b32_e32 v33, v37
	v_pk_add_f32 v[38:39], v[8:9], v[32:33] neg_lo:[0,1] neg_hi:[0,1]
	v_pk_add_f32 v[8:9], v[8:9], v[32:33]
	v_mov_b32_e32 v34, v35
	v_pk_add_f32 v[32:33], v[8:9], v[4:5] op_sel:[1,0] op_sel_hi:[0,1] neg_lo:[0,1] neg_hi:[0,1]
	v_pk_add_f32 v[40:41], v[36:37], v[32:33] op_sel_hi:[1,0] neg_lo:[0,1] neg_hi:[0,1]
	v_mov_b32_e32 v36, v37
	v_mov_b32_e32 v37, v9
	v_pk_mov_b32 v[32:33], v[4:5], v[32:33] op_sel:[1,0]
	v_mov_b32_e32 v35, v4
	v_pk_add_f32 v[32:33], v[36:37], v[32:33] neg_lo:[0,1] neg_hi:[0,1]
	v_mov_b32_e32 v40, v38
	v_pk_add_f32 v[4:5], v[34:35], v[32:33] neg_lo:[0,1] neg_hi:[0,1]
	v_mov_b32_e32 v39, v9
	v_pk_add_f32 v[32:33], v[40:41], v[4:5]
	s_nop 0
	v_pk_add_f32 v[34:35], v[32:33], v[32:33] op_sel:[0,1] op_sel_hi:[1,0]
	s_nop 0
	v_pk_add_f32 v[8:9], v[8:9], v[34:35] op_sel:[1,0] op_sel_hi:[0,1]
	v_mov_b32_e32 v33, v8
	v_pk_add_f32 v[36:37], v[32:33], v[38:39] neg_lo:[0,1] neg_hi:[0,1]
	v_mov_b32_e32 v5, v34
	v_sub_f32_e32 v9, v32, v36
	v_pk_add_f32 v[4:5], v[4:5], v[36:37] neg_lo:[0,1] neg_hi:[0,1]
	v_sub_f32_e32 v9, v38, v9
	v_add_f32_e32 v4, v4, v9
	v_add_f32_e32 v4, v4, v5
	v_add_f32_e32 v4, v8, v4
	v_cndmask_b32_e32 v4, v240, v4, vcc
	v_cmp_ngt_f32_e32 vcc, -1.0, v6
	s_nop 1
	v_cndmask_b32_e32 v4, v241, v4, vcc
	v_cmp_neq_f32_e32 vcc, -1.0, v6
	s_nop 1
	v_cndmask_b32_e32 v4, v242, v4, vcc
	v_cmp_lt_f32_e64 vcc, |v6|, s38
	s_nop 1
	v_cndmask_b32_e32 v4, v4, v6, vcc
; __device__ __forceinline__ void side_gemm1(const Params& P, int seg) {
;     ...
;         skinny_tile(xb + (size_t)r0 * DM, DM, Wt + (size_t)NPROJ * DM, DM, (it & 3) * 16, lane, [&](int row, int j, int col, float v) {
;             const float t = v * rstd1[r0 + row] + P.dt_bias[col]; dtv[(size_t)(r0 + row) * 64 + col] = (t > 20.f) ? t : log1pf(__expf(t)); }); }
.LBB0_102:
	s_or_b64 exec, exec, s[26:27]
	v_or_b32_e32 v8, 2, v16
	v_ashrrev_i32_e32 v9, 31, v8
	v_lshlrev_b64 v[8:9], 8, v[8:9]
	v_lshl_add_u64 v[8:9], v[20:21], 0, v[8:9]
	global_store_dword v[8:9], v4, off
	v_mov_b32_e32 v5, v218
	v_mov_b32_e32 v4, v219
	v_add_f32_e32 v6, v7, v11
	v_fmac_f32_e32 v4, v6, v5
	v_cmp_nlt_f32_e32 vcc, s28, v4
	s_and_saveexec_b64 s[26:27], vcc
	s_cbranch_execz .LBB0_95
	v_mul_f32_e32 v4, 0x3fb8aa3b, v4
	v_exp_f32_e32 v17, v4
	s_nop 0
	v_add_f32_e32 v6, 1.0, v17
	v_frexp_mant_f32_e32 v8, v6
	v_cvt_f64_f32_e32 v[4:5], v6
	v_frexp_exp_i32_f64_e32 v4, v[4:5]
	v_cmp_gt_f32_e32 vcc, s29, v8
	v_add_f32_e32 v7, -1.0, v6
	v_sub_f32_e32 v9, v7, v6
	v_subbrev_co_u32_e32 v18, vcc, 0, v4, vcc
	v_sub_u32_e32 v4, 0, v18
	v_sub_f32_e32 v7, v17, v7
	v_add_f32_e32 v9, 1.0, v9
	v_ldexp_f32 v5, v6, v4
	v_add_f32_e32 v7, v7, v9
	v_add_f32_e32 v6, -1.0, v5
	v_add_f32_e32 v8, 1.0, v5
	v_ldexp_f32 v4, v7, v4
	v_add_f32_e32 v7, 1.0, v6
	v_add_f32_e32 v9, -1.0, v8
	v_sub_f32_e32 v7, v5, v7
	v_sub_f32_e32 v5, v5, v9
	v_add_f32_e32 v7, v4, v7
	v_add_f32_e32 v4, v4, v5
	v_add_f32_e32 v19, v8, v4
	v_rcp_f32_e32 v23, v19
	v_sub_f32_e32 v5, v19, v8
	v_sub_f32_e32 v22, v4, v5
	v_add_f32_e32 v5, v6, v7
	v_mul_f32_e32 v33, v5, v23
	v_sub_f32_e32 v4, v5, v6
	v_mul_f32_e32 v6, v19, v33
	v_fma_f32 v8, v33, v19, -v6
	v_fmac_f32_e32 v8, v33, v22
	v_sub_f32_e32 v32, v7, v4
	v_add_f32_e32 v4, v6, v8
	v_sub_f32_e32 v7, v5, v4
	v_pk_add_f32 v[10:11], v[4:5], v[6:7] neg_lo:[0,1] neg_hi:[0,1]
	v_mov_b32_e32 v9, v4
	v_pk_add_f32 v[4:5], v[10:11], v[8:9] neg_lo:[0,1] neg_hi:[0,1]
	v_cmp_neq_f32_e32 vcc, s31, v17
	v_add_f32_e32 v5, v32, v5
	v_add_f32_e32 v4, v4, v5
	v_add_f32_e32 v5, v7, v4
	v_mul_f32_e32 v32, v23, v5
	v_mul_f32_e32 v6, v19, v32
	v_fma_f32 v8, v32, v19, -v6
	v_fmac_f32_e32 v8, v32, v22
	v_sub_f32_e32 v7, v7, v5
	v_add_f32_e32 v19, v4, v7
	v_add_f32_e32 v4, v6, v8
	v_sub_f32_e32 v7, v5, v4
	v_pk_add_f32 v[10:11], v[4:5], v[6:7] neg_lo:[0,1] neg_hi:[0,1]
	v_mov_b32_e32 v9, v4
	v_pk_add_f32 v[4:5], v[10:11], v[8:9] neg_lo:[0,1] neg_hi:[0,1]
	s_nop 0
	v_add_f32_e32 v5, v19, v5
	v_add_f32_e32 v4, v4, v5
	v_add_f32_e32 v5, v33, v32
	v_add_f32_e32 v4, v7, v4
	v_sub_f32_e32 v6, v5, v33
	v_mul_f32_e32 v4, v23, v4
	v_sub_f32_e32 v6, v32, v6
	v_add_f32_e32 v6, v6, v4
	v_add_f32_e32 v8, v5, v6
	v_mul_f32_e32 v9, v8, v8
	v_fmamk_f32 v4, v9, 0x3e9b6dac, v177
	v_fmaak_f32 v179, v9, v4, 0x3f2aaada
	v_cvt_f32_i32_e32 v4, v18
	v_sub_f32_e32 v5, v8, v5
	v_sub_f32_e32 v5, v6, v5
	v_ldexp_f32 v10, v5, 1
	v_mul_f32_e32 v5, v8, v9
	v_ldexp_f32 v7, v8, 1
	v_pk_mul_f32 v[8:9], v[4:5], v[178:179]
	s_nop 0
	v_fma_f32 v6, v4, s30, -v8
	v_fmac_f32_e32 v6, 0xb102e308, v4
	v_pk_add_f32 v[4:5], v[8:9], v[6:7]
	s_nop 0
	v_sub_f32_e32 v7, v5, v7
	v_sub_f32_e32 v7, v9, v7
	v_add_f32_e32 v11, v10, v7
	v_mov_b32_e32 v10, v8
	v_pk_add_f32 v[8:9], v[4:5], v[8:9] neg_lo:[0,1] neg_hi:[0,1]
	v_pk_add_f32 v[18:19], v[4:5], v[10:11]
	v_mov_b32_e32 v7, v4
	v_mov_b32_e32 v9, v19
	v_pk_add_f32 v[22:23], v[6:7], v[8:9] neg_lo:[0,1] neg_hi:[0,1]
	v_pk_add_f32 v[6:7], v[6:7], v[8:9]
	v_mov_b32_e32 v10, v11
	v_pk_add_f32 v[8:9], v[6:7], v[4:5] op_sel:[1,0] op_sel_hi:[0,1] neg_lo:[0,1] neg_hi:[0,1]
	v_pk_add_f32 v[32:33], v[18:19], v[8:9] op_sel_hi:[1,0] neg_lo:[0,1] neg_hi:[0,1]
	v_mov_b32_e32 v18, v19
	v_mov_b32_e32 v19, v7
	v_pk_mov_b32 v[8:9], v[4:5], v[8:9] op_sel:[1,0]
	v_mov_b32_e32 v11, v4
	v_pk_add_f32 v[8:9], v[18:19], v[8:9] neg_lo:[0,1] neg_hi:[0,1]
	v_mov_b32_e32 v32, v22
	v_pk_add_f32 v[4:5], v[10:11], v[8:9] neg_lo:[0,1] neg_hi:[0,1]
	v_mov_b32_e32 v23, v7
	v_pk_add_f32 v[8:9], v[32:33], v[4:5]
	s_nop 0
	v_pk_add_f32 v[10:11], v[8:9], v[8:9] op_sel:[0,1] op_sel_hi:[1,0]
	s_nop 0
	v_pk_add_f32 v[6:7], v[6:7], v[10:11] op_sel:[1,0] op_sel_hi:[0,1]
	v_mov_b32_e32 v9, v6
	v_pk_add_f32 v[18:19], v[8:9], v[22:23] neg_lo:[0,1] neg_hi:[0,1]
	v_mov_b32_e32 v5, v10
	v_sub_f32_e32 v7, v8, v18
	v_pk_add_f32 v[4:5], v[4:5], v[18:19] neg_lo:[0,1] neg_hi:[0,1]
	v_sub_f32_e32 v7, v22, v7
	v_add_f32_e32 v4, v4, v7
	v_add_f32_e32 v4, v4, v5
	v_add_f32_e32 v4, v6, v4
	v_cndmask_b32_e32 v4, v240, v4, vcc
	v_cmp_ngt_f32_e32 vcc, -1.0, v17
	s_nop 1
	v_cndmask_b32_e32 v4, v241, v4, vcc
	v_cmp_neq_f32_e32 vcc, -1.0, v17
	s_nop 1
	v_cndmask_b32_e32 v4, v242, v4, vcc
	v_cmp_lt_f32_e64 vcc, |v17|, s38
	s_nop 1
	v_cndmask_b32_e32 v4, v4, v17, vcc
	s_branch .LBB0_95

; #define GAS __attribute__((address_space(1)))
; #define LAS __attribute__((address_space(3)))
; __device__ __forceinline__ gws_t launder_s(const void* p0) { unsigned char* p = (unsigned char*)p0; asm volatile("" : "+s"(p)); return (gws_t)p; }
; __device__ __forceinline__ int launder_v(int v) { asm volatile("" : "+v"(v)); return v; }
; __device__ __forceinline__ int grid_x() { int g = (int)gridDim.x; asm volatile("" : "+s"(g)); return g; }
; __device__ __forceinline__ void phase_ssd(const Params& P, int seg, unsigned char* smem) {
;     gws_t ws = launder_s(P.ws);
;     const GAS bf16* proj = (const GAS bf16*)(ws + WS_PROJ); const GAS bf16* xconv = (const GAS bf16*)(ws + WS_XCONV); const GAS float* dtv = (const GAS float*)(ws + WS_DT); const GAS float* acv = (const GAS float*)(ws + WS_ACUM);
;     GAS bf16* ypre = (GAS bf16*)(ws + WS_YPRE); GAS float* state = (GAS float*)(ws + WS_STATE);
;     const int tid = launder_v(threadIdx.x), lane = tid & 63, w = tid >> 6, fr = lane & 15, fq = lane >> 4;
;     const unsigned lds0 = (unsigned)(size_t)(LAS unsigned char*)smem;
;     bf16* StS = (bf16*)(smem + T_ST); float* acS = (float*)(smem + T_AC);
;     const int lt = w >> 1, pt = w & 1, tq = (lane & 15) >> 2, tp = lane & 3;
;     if (__builtin_amdgcn_readfirstlane(tid) >= 256) __builtin_amdgcn_s_setprio(1);
;     const int gx = grid_x();
.LBB0_292:
	v_readlane_b32 s14, v253, 47
	v_readlane_b32 s15, v253, 48
	s_mov_b32 s9, s82
	s_andn2_b64 vcc, exec, s[14:15]
	v_cndmask_b32_e64 v4, 0, 1, s[14:15]
	v_cmp_ne_u32_e64 s[16:17], 1, v4
	s_nop 1
	v_writelane_b32 v255, s16, 7
	s_nop 1
	v_writelane_b32 v255, s17, 8
	s_cbranch_vccnz .LBB0_338
	s_mov_b64 exec, -1
	s_mov_b64 s[0:1], s[80:81]
	s_mov_b32 s63, s82
	v_readlane_b32 s24, v254, 38
	v_readlane_b32 s52, v252, 28
	v_readlane_b32 s53, v252, 29
	v_and_b32_e32 v184, 63, v172
	v_lshrrev_b32_e32 v185, 6, v172
	v_and_b32_e32 v186, 15, v172
	v_bfe_u32 v187, v172, 4, 2
	v_bfe_u32 v188, v172, 2, 2
	v_and_b32_e32 v189, 3, v172
	v_lshrrev_b32_e32 v190, 7, v172
	v_lshrrev_b32_e32 v191, 8, v172
	v_xor_b32_e32 v190, v190, v191
	v_bfe_u32 v191, v172, 6, 1
	v_readfirstlane_b32 s73, v185
	s_nop 3
	s_lshr_b32 s55, s73, 1
	s_lshr_b32 s65, s73, 2
	s_xor_b32 s55, s55, s65
	v_lshrrev_b32_e32 v170, 4, v172
	v_and_b32_e32 v171, 7, v170
	v_lshlrev_b32_e32 v171, 1, v171
	v_xor_b32_e32 v171, v171, v186
	v_lshlrev_b32_e32 v171, 4, v171
	v_lshl_add_u32 v212, v170, 8, v171
	v_lshrrev_b32_e32 v171, 3, v172
	v_and_b32_e32 v192, 7, v172
	v_mul_u32_u24_e32 v214, 80, v171
	v_lshl_add_u32 v214, v192, 3, v214
	v_mul_u32_u24_e32 v216, 72, v171
	v_lshl_add_u32 v216, v192, 3, v216
	v_lshlrev_b32_e32 v218, 2, v171
	v_add_u32_e32 v218, 0x1d800, v218
	v_and_b32_e32 v193, 7, v186
	v_lshlrev_b32_e32 v193, 1, v193
	v_lshl_add_u32 v195, v191, 4, v186
	v_lshlrev_b32_e32 v195, 8, v195
	v_add_u32_e32 v195, 0x19800, v195
	v_add_u32_e32 v170, 0, v187
	v_xor_b32_e32 v170, v170, v193
	v_lshlrev_b32_e32 v170, 4, v170
	v_lshl_add_u32 v219, v186, 8, v170
	v_add_u32_e32 v227, v195, v170
	v_add_u32_e32 v170, 4, v187
	v_xor_b32_e32 v170, v170, v193
	v_lshlrev_b32_e32 v170, 4, v170
	v_lshl_add_u32 v220, v186, 8, v170
	v_add_u32_e32 v228, v195, v170
	v_add_u32_e32 v170, 8, v187
	v_xor_b32_e32 v170, v170, v193
	v_lshlrev_b32_e32 v170, 4, v170
	v_lshl_add_u32 v221, v186, 8, v170
	v_add_u32_e32 v229, v195, v170
	v_add_u32_e32 v170, 12, v187
	v_xor_b32_e32 v170, v170, v193
	v_lshlrev_b32_e32 v170, 4, v170
	v_lshl_add_u32 v222, v186, 8, v170
	v_add_u32_e32 v230, v195, v170
	v_lshlrev_b32_e32 v231, 2, v186
	v_add_u32_e32 v231, 0x1d800, v231
	v_lshlrev_b32_e32 v232, 4, v187
	v_add_u32_e32 v232, 0x1d800, v232
	v_lshl_add_u32 v170, v187, 2, v188
	v_mul_u32_u24_e32 v233, 80, v170
	v_lshl_add_u32 v233, v191, 5, v233
	v_lshl_add_u32 v233, v189, 3, v233
	v_mul_u32_u24_e32 v235, 72, v186
	v_lshl_add_u32 v235, v191, 5, v235
	v_lshl_add_u32 v235, v187, 3, v235
	v_mul_u32_u24_e32 v237, 80, v170
	v_lshl_add_u32 v237, v189, 3, v237
	v_and_b32_e32 v171, 7, v170
	v_lshlrev_b32_e32 v171, 1, v171
	v_lshrrev_b32_e32 v192, 1, v189
	v_and_b32_e32 v195, 1, v189
	v_lshlrev_b32_e32 v195, 3, v195
	v_lshl_add_u32 v195, v170, 8, v195
	v_and_b32_e32 v194, 3, v185
	v_lshl_add_u32 v193, v194, 2, v192
	v_xor_b32_e32 v193, v193, v171
	v_lshl_add_u32 v244, v193, 4, v195
	v_lshl_add_u32 v193, v194, 2, v192
	v_add_u32_e32 v193, 2, v193
	v_xor_b32_e32 v193, v193, v171
	v_lshl_add_u32 v245, v193, 4, v195
	v_and_b32_e32 v171, 7, v186
	v_lshlrev_b32_e32 v171, 1, v171
	v_lshrrev_b32_e32 v192, 1, v187
	v_and_b32_e32 v195, 1, v187
	v_lshlrev_b32_e32 v195, 3, v195
	v_lshl_add_u32 v195, v186, 8, v195
	v_add_u32_e32 v195, 0x19800, v195
	v_lshl_add_u32 v193, v194, 2, v192
	v_xor_b32_e32 v193, v193, v171
	v_lshl_add_u32 v248, v193, 4, v195
	v_lshl_add_u32 v193, v194, 2, v192
	v_add_u32_e32 v193, 2, v193
	v_xor_b32_e32 v193, v193, v171
	v_lshl_add_u32 v249, v193, 4, v195
	v_add_u32_e32 v213, 0xcc00, v212
	v_add_u32_e32 v215, 0xcc00, v214
	v_add_u32_e32 v217, 0xcc00, v216
	v_add_u32_e32 v234, 0xcc00, v233
	v_add_u32_e32 v236, 0xcc00, v235
	v_add_u32_e32 v243, 0xcc00, v237
	v_add_u32_e32 v223, 0xcc00, v219
	v_add_u32_e32 v224, 0xcc00, v220
	v_add_u32_e32 v225, 0xcc00, v221
	v_add_u32_e32 v226, 0xcc00, v222
	v_add_u32_e32 v246, 0xcc00, v244
	v_add_u32_e32 v247, 0xcc00, v245
	v_lshlrev_b32_e32 v170, 2, v187
	v_add_u32_e32 v171, 0, v170
	v_cmp_le_u32_e64 s[14:15], v171, v186
	v_add_u32_e32 v171, 1, v170
	v_cmp_le_u32_e64 s[16:17], v171, v186
	v_add_u32_e32 v171, 2, v170
	v_cmp_le_u32_e64 s[22:23], v171, v186
	v_add_u32_e32 v171, 3, v170
	v_cmp_le_u32_e64 s[34:35], v171, v186
	v_lshlrev_b32_e32 v211, 9, v186
	v_lshl_add_u32 v211, v194, 7, v211
	v_lshl_add_u32 v211, v187, 4, v211
	s_cmp_eq_u32 s24, 0
	s_cselect_b32 s60, 1, 0
	s_add_u32 s39, s60, 64
	s_mov_b32 s18, s2
; #define GAS __attribute__((address_space(1)))
; __device__ __forceinline__ void phase_ssd(const Params& P, int seg, unsigned char* smem) {
;     ...
;     for (int item = blockIdx.x; item < 256; item += gx) {
;         const int xcd = item & 7, ix = item >> 3, bg = xcd * 2 + (ix >> 4), b = bg >> 3, g = bg & 7, h = g * 8 + ((ix & 15) >> 1), ph = ix & 1;
;         const float Dh = P.d_skip[h];
;         const GAS float* stg = state + (size_t)(seg & 1) * (2 * 64 * 64 * 128) + ((size_t)(b * 64 + h) * 64 + ph * 32) * 128;
;         GAS float* stw = state + (size_t)((seg + 1) & 1) * (2 * 64 * 64 * 128) + ((size_t)(b * 64 + h) * 64 + ph * 32) * 128;
;         f32x4 st[2];
; #pragma unroll
;         for (int p2 = 0; p2 < 2; ++p2)
; #pragma unroll
;             for (int j = 0; j < 4; ++j) st[p2][j] = (seg == 0) ? 0.f : stg[(size_t)(p2 * 16 + fq * 4 + j) * 128 + w * 16 + fr];
;         __syncthreads();
; #pragma unroll
;         for (int p2 = 0; p2 < 2; ++p2)
; #pragma unroll
;             for (int j = 0; j < 4; ++j) StS[(p2 * 16 + fq * 4 + j) * 136 + w * 16 + fr] = (bf16)f2bf(st[p2][j]);
;         const int nchunks = TSEG / 64 + (seg == 0 ? 1 : 0);
;         struct Pre { v4u Br[2], Cr[2]; v2u Xr, Zr; float dtl, acl, alast, aclane; }; Pre RA, RB;
;         auto chunk_row0 = [&](int ci) -> int { return (seg == 0) ? (ci == 0 ? RS : b * TSEG + (ci - 1) * 64) : b * TSEG + ci * 64; };
;         auto load_chunk = [&](int ci, Pre& R) { const int row0 = chunk_row0(ci);
; #pragma unroll
;             for (int i = 0; i < 2; ++i) { const int q = tid + 512 * i, l = q >> 4, c8 = q & 15; const GAS bf16* rp = xconv + (size_t)(row0 + l) * DXBC + g * 128 + c8 * 8;
;                 R.Br[i] = *(const GAS v4u*)(rp + 4096); R.Cr[i] = *(const GAS v4u*)(rp + 5120); }
;             { const int l = tid >> 3, p4 = (tid & 7) * 4; R.Xr = *(const GAS v2u*)(xconv + (size_t)(row0 + l) * DXBC + h * 64 + ph * 32 + p4);
;               R.Zr = __builtin_nontemporal_load((const GAS v2u*)(proj + (size_t)(row0 + l) * NPROJ + OFF_Z + h * 64 + ph * 32 + p4));
;               R.dtl = dtv[(size_t)(row0 + l) * 64 + h]; R.acl = acv[(size_t)(row0 + l) * 64 + h]; }
;             R.alast = acv[(size_t)(row0 + 63) * 64 + h]; R.aclane = acv[(size_t)(row0 + lane) * 64 + h]; };
;         load_chunk(0, RA); if (nchunks > 1) load_chunk(1, RB);
.Lssd_item:
	v_and_b32_e32 v186, 15, v172
	v_bfe_u32 v187, v172, 4, 2
	v_lshrrev_b32_e32 v190, 7, v172
	v_lshrrev_b32_e32 v191, 8, v172
	v_xor_b32_e32 v190, v190, v191
	v_bfe_u32 v191, v172, 6, 1
	v_lshrrev_b32_e32 v170, 4, v172
	v_lshrrev_b32_e32 v171, 3, v172
	v_and_b32_e32 v192, 7, v172
	v_mul_u32_u24_e32 v205, 0x3000, v170
	v_lshl_add_u32 v205, v186, 4, v205
	v_add_u32_e32 v205, 0x2000, v205
	v_mul_u32_u24_e32 v184, 0x3000, v171
	v_lshl_add_u32 v184, v192, 3, v184
	v_mul_u32_u24_e32 v188, 0xa000, v171
	v_lshl_add_u32 v188, v192, 3, v188
	v_add_u32_e32 v188, 0x3000, v188
	v_lshlrev_b32_e32 v189, 8, v171
	v_and_b32_e32 v193, 63, v172
	v_lshlrev_b32_e32 v193, 8, v193
	v_lshl_add_u32 v195, v190, 4, v186
	v_lshlrev_b32_e32 v195, 13, v195
	v_lshl_add_u32 v195, v191, 5, v195
	v_lshl_add_u32 v195, v187, 3, v195
	s_and_b32 s65, s18, 7
	s_lshr_b32 s66, s18, 3
	s_lshr_b32 s67, s66, 4
	s_lshl_b32 s65, s65, 1
	s_add_u32 s65, s65, s67
	s_lshr_b32 s72, s65, 3
	s_and_b32 s70, s65, 7
	s_and_b32 s71, s66, 1
	s_bfe_u32 s67, s66, 0x30001
	s_lshl_b32 s69, s70, 3
	s_add_u32 s69, s69, s67
	s_lshl_b32 s20, s72, 12
	s_cmp_eq_u32 s60, 1
	s_cselect_b32 s57, 0x2000, s20
	s_lshl_b32 s65, s70, 8
	v_add_u32_e32 v204, s65, v205
	v_add_u32_e32 v205, 0x60000, v204
	s_lshl_b32 s65, s69, 7
	s_lshl_b32 s66, s71, 6
	s_add_u32 s65, s65, s66
	v_add_u32_e32 v206, s65, v184
	v_add_u32_e32 v207, s65, v188
	v_add_u32_e32 v210, s65, v195
	s_lshl_b32 s66, s69, 2
	v_add_u32_e32 v208, s66, v189
	s_add_u32 s67, s66, 0x3f00
	v_mov_b32_e32 v209, s67
	s_load_dword s61, s[52:53], s66
	s_lshl_b32 s65, s72, 6
	s_add_u32 s65, s65, s69
	s_lshl_b32 s65, s65, 6
	s_lshl_b32 s66, s71, 5
	s_add_u32 s65, s65, s66
	s_lshl_b32 s65, s65, 9
	s_add_u32 s65, s65, 0x3aef9000
	s_and_b32 s66, s24, 1
	s_mul_i32 s67, s66, 0x400000
	s_xor_b32 s66, s66, 1
	s_mul_i32 s68, s66, 0x400000
	s_add_u32 s68, s68, s65
	s_add_u32 s50, s0, s68
	s_addc_u32 s51, s1, 0
	s_add_u32 s67, s67, s65
	s_add_u32 s48, s0, s67
	s_addc_u32 s49, s1, 0
	v_mov_b32_e32 v8, 0
	v_mov_b32_e32 v9, 0
	v_mov_b32_e32 v10, 0
	v_mov_b32_e32 v11, 0
	v_mov_b32_e32 v12, 0
	v_mov_b32_e32 v13, 0
	v_mov_b32_e32 v14, 0
	v_mov_b32_e32 v15, 0
	v_mov_b32_e32 v16, 0
	v_mov_b32_e32 v17, 0
	v_mov_b32_e32 v18, 0
	v_mov_b32_e32 v19, 0
	v_mov_b32_e32 v20, 0
	v_mov_b32_e32 v21, 0
	v_mov_b32_e32 v22, 0
	v_mov_b32_e32 v23, 0
	s_cmp_eq_u32 s60, 1
	s_cbranch_scc1 .Lssd_nostate
	s_cmp_ge_u32 s55, 2
	s_cbranch_scc1 .Lssd_nostate
	v_add_u32_e32 v185, 0x2000, v211
	global_load_dwordx4 v[8:11], v211, s[48:49]
	global_load_dwordx4 v[12:15], v185, s[48:49]
	global_load_dwordx4 v[16:19], v211, s[48:49] offset:64
	global_load_dwordx4 v[20:23], v185, s[48:49] offset:64
.Lssd_nostate:
	s_mov_b32 s54, 0
	s_mov_b32 s66, 0
	s_sub_u32 s65, s66, s60
	s_lshl_b32 s65, s65, 6
	s_add_u32 s65, s65, s20
	s_cmp_eq_u32 s66, 0
	s_cselect_b32 s56, s57, s65
	s_mul_i32 s65, s56, 0x3000
	s_add_u32 s65, s65, 0x29fe1000
	s_add_u32 s40, s0, s65
	s_addc_u32 s41, s1, 0
	s_mul_i32 s65, s56, 0xa000
	s_add_u32 s65, s65, 0x134e1000
	s_add_u32 s42, s0, s65
	s_addc_u32 s43, s1, 0
	s_mul_i32 s65, s56, 0x100
	s_add_u32 s65, s65, 0x302e1000
	s_add_u32 s44, s0, s65
	s_addc_u32 s45, s1, 0
	s_mul_i32 s65, s56, 0x100
	s_add_u32 s65, s65, 0x3b79e000
	s_add_u32 s46, s0, s65
	s_addc_u32 s47, s1, 0
	global_load_dwordx4 v[140:143], v204, s[40:41] offset:2048
	global_load_dwordx4 v[144:147], v205, s[40:41] offset:2048
	global_load_dwordx4 v[132:135], v204, s[40:41]
	global_load_dwordx4 v[136:139], v205, s[40:41]
	global_load_dwordx2 v[4:5], v206, s[40:41]
	global_load_dwordx2 v[36:37], v207, s[42:43] nt
	global_load_dword v6, v208, s[44:45]
	global_load_dword v116, v208, s[46:47]
	global_load_dword v117, v209, s[46:47]
	s_mov_b32 s66, 1
	s_sub_u32 s65, s66, s60
	s_lshl_b32 s65, s65, 6
	s_add_u32 s65, s65, s20
	s_cmp_eq_u32 s66, 0
	s_cselect_b32 s67, s57, s65
	s_mul_i32 s65, s67, 0x3000
	s_add_u32 s65, s65, 0x29fe1000
	s_add_u32 s40, s0, s65
	s_addc_u32 s41, s1, 0
	s_mul_i32 s65, s67, 0xa000
	s_add_u32 s65, s65, 0x134e1000
	s_add_u32 s42, s0, s65
	s_addc_u32 s43, s1, 0
	s_mul_i32 s65, s67, 0x100
	s_add_u32 s65, s65, 0x302e1000
	s_add_u32 s44, s0, s65
	s_addc_u32 s45, s1, 0
	s_mul_i32 s65, s67, 0x100
	s_add_u32 s65, s65, 0x3b79e000
	s_add_u32 s46, s0, s65
	s_addc_u32 s47, s1, 0
	global_load_dwordx4 v[156:159], v204, s[40:41] offset:2048
	global_load_dwordx4 v[160:163], v205, s[40:41] offset:2048
	global_load_dwordx4 v[148:151], v204, s[40:41]
	global_load_dwordx4 v[152:155], v205, s[40:41]
	global_load_dwordx2 v[164:165], v206, s[40:41]
	global_load_dwordx2 v[166:167], v207, s[42:43] nt
	global_load_dword v118, v208, s[44:45]
	global_load_dword v168, v208, s[46:47]
	global_load_dword v169, v209, s[46:47]
	s_mov_b32 s66, 2
	s_sub_u32 s65, s66, s60
	s_lshl_b32 s65, s65, 6
	s_add_u32 s65, s65, s20
	s_cmp_eq_u32 s66, 0
	s_cselect_b32 s67, s57, s65
	s_mul_i32 s65, s67, 0x3000
	s_add_u32 s65, s65, 0x29fe1000
	s_add_u32 s40, s0, s65
	s_addc_u32 s41, s1, 0
	s_mul_i32 s65, s67, 0xa000
	s_add_u32 s65, s65, 0x134e1000
	s_add_u32 s42, s0, s65
	s_addc_u32 s43, s1, 0
	s_mul_i32 s65, s67, 0x100
	s_add_u32 s65, s65, 0x302e1000
	s_add_u32 s44, s0, s65
	s_addc_u32 s45, s1, 0
	s_mul_i32 s65, s67, 0x100
	s_add_u32 s65, s65, 0x3b79e000
	s_add_u32 s46, s0, s65
	s_addc_u32 s47, s1, 0
	s_waitcnt vmcnt(0)
	s_waitcnt lgkmcnt(0)
	s_barrier
	s_cmp_ge_u32 s55, 2
	s_cbranch_scc1 .Lssd_noimg
	v_cvt_pk_bf16_f32 v184, v8, v9
	v_cvt_pk_bf16_f32 v185, v10, v11
	v_cvt_pk_bf16_f32 v186, v12, v13
	v_cvt_pk_bf16_f32 v187, v14, v15
	v_cvt_pk_bf16_f32 v188, v16, v17
	v_cvt_pk_bf16_f32 v189, v18, v19
	v_cvt_pk_bf16_f32 v190, v20, v21
	v_cvt_pk_bf16_f32 v191, v22, v23
	ds_write_b64 v248, v[184:185]
	ds_write_b64 v248, v[186:187] offset:4096
	ds_write_b64 v249, v[188:189]
	ds_write_b64 v249, v[190:191] offset:4096
	s_waitcnt lgkmcnt(0)
; __device__ __forceinline__ void phase_ssd(const Params& P, int seg, unsigned char* smem) {
;     ...
;         auto step = [&](int ci, Pre& R, const int par) {
;             const int row0 = chunk_row0(ci); unsigned char* sb = smem + par * T_BUF; float* acP = acS + par * 64;
;             const bf16* StR = StS + par * (T_STSZ / 2); bf16* StW = StS + (par ^ 1) * (T_STSZ / 2);
;             const float dec = __expf(R.alast);
;             { const float e2 = __expf(R.alast - R.acl);
; #pragma unroll
;               for (int i = 0; i < 2; ++i) { const int q = tid + 512 * i, l = q >> 4, c8 = q & 15; *(v4u*)(sb + T_CS + l * 272 + c8 * 16) = R.Cr[i]; *(v4u*)(sb + T_BS + l * 272 + c8 * 16) = R.Br[i]; }
;               const int l = tid >> 3, p4 = (tid & 7) * 4;
;               const float x0 = bflo(R.Xr.x) * R.dtl, x1 = bfhi(R.Xr.x) * R.dtl, x2 = bflo(R.Xr.y) * R.dtl, x3 = bfhi(R.Xr.y) * R.dtl;
;               v2u d; d.x = cvt_pk_bf16(x0, x1); d.y = cvt_pk_bf16(x2, x3); *(v2u*)(sb + T_XD + l * 80 + p4 * 2) = d;
;               v2u e; e.x = cvt_pk_bf16(x0 * e2, x1 * e2); e.y = cvt_pk_bf16(x2 * e2, x3 * e2); *(v2u*)(sb + T_XE + l * 80 + p4 * 2) = e;
;               *(v2u*)(sb + T_XS + l * 64 + p4 * 2) = R.Xr; *(v2u*)(sb + T_ZS + l * 64 + p4 * 2) = R.Zr;
;               if (w == 0) acP[lane] = R.aclane; }
;             BAR_LDS();
;             if (ci + 2 < nchunks) load_chunk(ci + 2, R);
;             bf16x8 cf[4];
; #pragma unroll
;             for (int k = 0; k < 4; ++k) cf[k] = *(const bf16x8*)(sb + T_CS + (lt * 16 + fr) * 272 + (k * 32 + fq * 8) * 2);
;             f32x4 yo = {0.f, 0.f, 0.f, 0.f};
; #pragma unroll
;             for (int k = 0; k < 4; ++k) { const bf16x8 bb = *(const bf16x8*)((const unsigned char*)StR + (pt * 16 + fr) * 272 + (k * 32 + fq * 8) * 2); yo = mfma16(cf[k], bb, yo); }
; { const f32x4 a4 = *(const f32x4*)(acP + lt * 16 + fq * 4);
; #pragma unroll
;               for (int j = 0; j < 4; ++j) yo[j] *= __expf(a4[j]); }
;             const float acl_fr = acP[lt * 16 + fr]; const int lrow = lt * 16 + fr;
; #pragma unroll
;             for (int t = 0; t < 2; ++t) {
;                 if (2 * t <= lt) {
;                     v2u xb0, xb1;
;                     { const unsigned a0 = lds0 + par * T_BUF + T_XD + (32 * t + 4 * fq + tq) * 80 + (pt * 16 + 4 * tp) * 2, a1 = a0 + 16 * 80; TR_ISSUE(xb0, a0); TR_ISSUE(xb1, a1); }
;                     float m[8];
.Lssd_noimg:
	ds_write_b128 v212, v[140:143]
	ds_write_b128 v212, v[144:147] offset:8192
	ds_write_b128 v212, v[132:135] offset:16384
	ds_write_b128 v212, v[136:139] offset:24576
	v_sub_f32_e32 v200, v117, v116
	v_mul_f32_e32 v200, 0x3fb8aa3b, v200
	v_exp_f32_e32 v200, v200
	v_lshlrev_b32_e32 v196, 16, v4
	v_and_b32_e32 v197, 0xffff0000, v4
	v_lshlrev_b32_e32 v198, 16, v5
	v_and_b32_e32 v199, 0xffff0000, v5
	v_mul_f32_e32 v196, v196, v6
	v_mul_f32_e32 v197, v197, v6
	v_mul_f32_e32 v198, v198, v6
	v_mul_f32_e32 v199, v199, v6
	v_cvt_pk_bf16_f32 v202, v196, v197
	v_cvt_pk_bf16_f32 v203, v198, v199
	ds_write_b64 v214, v[202:203] offset:32768
	v_mul_f32_e32 v196, v196, v200
	v_mul_f32_e32 v197, v197, v200
	v_mul_f32_e32 v198, v198, v200
	v_mul_f32_e32 v199, v199, v200
	v_cvt_pk_bf16_f32 v192, v196, v197
	v_cvt_pk_bf16_f32 v193, v198, v199
	ds_write_b64 v214, v[192:193] offset:37888
	ds_write_b64 v216, v[4:5] offset:43008
	ds_write_b64 v216, v[36:37] offset:47616
	v_mul_f32_e32 v201, 0x3fb8aa3b, v116
	ds_write_b32 v218, v201
	v_mul_f32_e32 v174, 0x3fb8aa3b, v117
	v_exp_f32_e32 v174, v174
	s_waitcnt lgkmcnt(0)
	s_barrier
	s_cmp_eq_u32 s55, 1
	s_cbranch_scc1 .Lssd_loop1
	s_cmp_eq_u32 s55, 2
	s_cbranch_scc1 .Lssd_loop2
	s_cmp_eq_u32 s55, 3
	s_cbranch_scc1 .Lssd_loop3
.Lssd_loop0:
	ds_read_b128 v[28:31], v219
	ds_read_b128 v[32:35], v220
	ds_read_b128 v[40:43], v221
	ds_read_b128 v[44:47], v222
	ds_read_b128 v[48:51], v227
	ds_read_b128 v[52:55], v228
	ds_read_b128 v[56:59], v229
	ds_read_b128 v[60:63], v230
	ds_read_b32 v194, v231
	ds_read_b64_tr_b16 v[96:97], v244 offset:16384
	ds_read_b64_tr_b16 v[98:99], v244 offset:20480
	ds_read_b64_tr_b16 v[100:101], v244 offset:24576
	ds_read_b64_tr_b16 v[102:103], v244 offset:28672
	ds_read_b64_tr_b16 v[104:105], v245 offset:16384
	ds_read_b64_tr_b16 v[106:107], v245 offset:20480
	s_waitcnt lgkmcnt(11)
	ds_read_b64_tr_b16 v[108:109], v245 offset:24576
	ds_read_b64_tr_b16 v[110:111], v245 offset:28672
	ds_read_b64_tr_b16 v[112:113], v237 offset:37888
	ds_read_b64_tr_b16 v[114:115], v237 offset:39168
	s_waitcnt lgkmcnt(11)
	ds_read_b64_tr_b16 v[124:125], v237 offset:37920
	ds_read_b64_tr_b16 v[126:127], v237 offset:39200
	ds_read_b64_tr_b16 v[120:121], v237 offset:40448
	ds_read_b64_tr_b16 v[122:123], v237 offset:41728
	global_load_dwordx4 v[140:143], v204, s[40:41] offset:2048
	s_waitcnt lgkmcnt(11)
	ds_read_b64_tr_b16 v[128:129], v237 offset:40480
	ds_read_b64_tr_b16 v[130:131], v237 offset:41760
	ds_read_b128 v[64:67], v219 offset:16384
	ds_read_b128 v[68:71], v220 offset:16384
	s_waitcnt lgkmcnt(11)
	ds_read_b128 v[72:75], v221 offset:16384
	global_load_dwordx4 v[144:147], v205, s[40:41] offset:2048
	ds_read_b128 v[76:79], v222 offset:16384
	v_mfma_f32_16x16x32_bf16 v[24:27], v[48:51], v[28:31], 0
	v_mfma_f32_16x16x32_bf16 v[24:27], v[52:55], v[32:35], v[24:27]
	v_mfma_f32_16x16x32_bf16 v[24:27], v[56:59], v[40:43], v[24:27]
	v_mfma_f32_16x16x32_bf16 v[24:27], v[60:63], v[44:47], v[24:27]
	global_load_dwordx4 v[132:135], v204, s[40:41]
	ds_read_b64_tr_b16 v[56:57], v233 offset:32768
	ds_read_b64_tr_b16 v[58:59], v233 offset:34048
	v_mul_f32_e32 v8, v8, v174
	v_mul_f32_e32 v9, v9, v174
	v_mul_f32_e32 v10, v10, v174
	v_mul_f32_e32 v11, v11, v174
	global_load_dwordx4 v[136:139], v205, s[40:41]
	v_mul_f32_e32 v12, v12, v174
	v_mul_f32_e32 v13, v13, v174
	v_mul_f32_e32 v14, v14, v174
	v_mul_f32_e32 v15, v15, v174
	v_mul_f32_e32 v16, v16, v174
	global_load_dwordx2 v[4:5], v206, s[40:41]
	v_mul_f32_e32 v17, v17, v174
	v_mul_f32_e32 v18, v18, v174
	v_mul_f32_e32 v19, v19, v174
	v_mul_f32_e32 v20, v20, v174
	v_mul_f32_e32 v21, v21, v174
	global_load_dwordx2 v[36:37], v207, s[42:43] nt
	v_mul_f32_e32 v22, v22, v174
	v_mul_f32_e32 v23, v23, v174
	s_waitcnt lgkmcnt(12)
	v_mfma_f32_16x16x32_bf16 v[8:11], v[96:99], v[112:115], v[8:11]
	s_waitcnt lgkmcnt(10)
	v_mfma_f32_16x16x32_bf16 v[12:15], v[96:99], v[124:127], v[12:15]
	v_mfma_f32_16x16x32_bf16 v[16:19], v[104:107], v[112:115], v[16:19]
	v_mfma_f32_16x16x32_bf16 v[20:23], v[104:107], v[124:127], v[20:23]
	global_load_dword v6, v208, s[44:45]
	s_waitcnt lgkmcnt(8)
	v_mfma_f32_16x16x32_bf16 v[8:11], v[100:103], v[120:123], v[8:11]
	s_waitcnt lgkmcnt(6)
	v_mfma_f32_16x16x32_bf16 v[12:15], v[100:103], v[128:131], v[12:15]
	v_mfma_f32_16x16x32_bf16 v[16:19], v[108:111], v[120:123], v[16:19]
	v_mfma_f32_16x16x32_bf16 v[20:23], v[108:111], v[128:131], v[20:23]
	ds_read_b128 v[96:99], v232
	global_load_dword v116, v208, s[46:47]
	ds_read_b64 v[124:125], v235 offset:43008
	ds_read_b64 v[126:127], v235 offset:47616
	s_waitcnt lgkmcnt(8)
	v_mfma_f32_16x16x32_bf16 v[48:51], v[64:67], v[28:31], 0
	s_waitcnt lgkmcnt(7)
	v_mfma_f32_16x16x32_bf16 v[48:51], v[68:71], v[32:35], v[48:51]
	s_waitcnt lgkmcnt(6)
	v_mfma_f32_16x16x32_bf16 v[48:51], v[72:75], v[40:43], v[48:51]
	global_load_dword v117, v209, s[46:47]
	s_waitcnt lgkmcnt(5)
	v_mfma_f32_16x16x32_bf16 v[48:51], v[76:79], v[44:47], v[48:51]
	v_exp_f32_e32 v195, v194
	s_nop 0
	v_mul_f32_e32 v24, v24, v195
	v_mul_f32_e32 v25, v25, v195
	v_mul_f32_e32 v26, v26, v195
	v_mul_f32_e32 v27, v27, v195
	s_add_u32 s66, s54, 3
	s_cmp_lt_u32 s66, s39
	s_cselect_b32 s74, 0xc0000, 0
	s_cselect_b32 s75, 0x280000, 0
	s_cselect_b32 s76, 0x4000, 0
	s_add_u32 s40, s40, s74
	s_addc_u32 s41, s41, 0
	s_add_u32 s42, s42, s75
	s_addc_u32 s43, s43, 0
	s_add_u32 s44, s44, s76
	s_addc_u32 s45, s45, 0
	s_add_u32 s46, s46, s76
	s_addc_u32 s47, s47, 0
	v_cvt_pk_bf16_f32 v184, v8, v9
	s_waitcnt vmcnt(10)
; __device__ __forceinline__ void phase_ssd(const Params& P, int seg, unsigned char* smem) {
;     ...
; #pragma unroll
;             for (int t = 0; t < 2; ++t) {
;                 if (2 * t <= lt) {
;                     v2u xb0, xb1;
;                     { const unsigned a0 = lds0 + par * T_BUF + T_XD + (32 * t + 4 * fq + tq) * 80 + (pt * 16 + 4 * tp) * 2, a1 = a0 + 16 * 80; TR_ISSUE(xb0, a0); TR_ISSUE(xb1, a1); }
;                     float m[8];
;                     { f32x4 s0 = {0.f, 0.f, 0.f, 0.f}, s1 = {0.f, 0.f, 0.f, 0.f};
; #pragma unroll
;                       for (int k = 0; k < 4; ++k) { const bf16x8 bf0 = *(const bf16x8*)(sb + T_BS + ((2 * t) * 16 + fr) * 272 + (k * 32 + fq * 8) * 2), bf1 = *(const bf16x8*)(sb + T_BS + ((2 * t + 1) * 16 + fr) * 272 + (k * 32 + fq * 8) * 2);
;                           s0 = mfma16(bf0, cf[k], s0); s1 = mfma16(bf1, cf[k], s1); }
;                       const f32x4 a0 = *(const f32x4*)(acP + (2 * t) * 16 + fq * 4), a1 = *(const f32x4*)(acP + (2 * t + 1) * 16 + fq * 4);
; #pragma unroll
;                       for (int j = 0; j < 4; ++j) { const int si0 = (2 * t) * 16 + fq * 4 + j, si1 = si0 + 16;
;                           const float e0 = s0[j] * __expf(fminf(acl_fr - a0[j], 0.f)), e1 = s1[j] * __expf(fminf(acl_fr - a1[j], 0.f));
;                           m[j] = (si0 <= lrow) ? e0 : 0.f; m[4 + j] = (si1 <= lrow) ? e1 : 0.f; } }
;                     v4u mp; mp.x = cvt_pk_bf16(m[0], m[1]); mp.y = cvt_pk_bf16(m[2], m[3]); mp.z = cvt_pk_bf16(m[4], m[5]); mp.w = cvt_pk_bf16(m[6], m[7]);
;                     asm volatile("s_waitcnt lgkmcnt(0)" : "+v"(xb0), "+v"(xb1) :: "memory");
;                     yo = mfma16(__builtin_bit_cast(bf16x8, mp), mk8(xb0, xb1), yo);
;                 }
;             }
; #pragma unroll
;             for (int j = 0; j < 4; ++j) { const int l = lt * 16 + fq * 4 + j, p = pt * 16 + fr; const float xv = bf2f(*(const bf16*)(sb + T_XS + l * 64 + p * 2)), zv = bf2f(*(const bf16*)(sb + T_ZS + l * 64 + p * 2));
;                 ypre[(size_t)(row0 + l) * DINNER + h * 64 + ph * 32 + p] = f2bfh((yo[j] + Dh * xv) * siluf_(zv)); }
;             { v2u xa[2][2][2], bb[2][2];
; #pragma unroll
;               for (int kk = 0; kk < 2; ++kk) {
; #pragma unroll
;                   for (int hh = 0; hh < 2; ++hh) { const int r = kk * 32 + 8 * fq + 4 * hh + tq;
	v_cvt_pk_bf16_f32 v185, v10, v11
	v_cvt_pk_bf16_f32 v186, v12, v13
	ds_write_b128 v213, v[156:159]
	v_cvt_pk_bf16_f32 v187, v14, v15
	v_cvt_pk_bf16_f32 v188, v16, v17
	ds_write_b128 v213, v[160:163] offset:8192
	v_cvt_pk_bf16_f32 v189, v18, v19
	v_cvt_pk_bf16_f32 v190, v20, v21
	ds_write_b128 v213, v[148:151] offset:16384
	v_cvt_pk_bf16_f32 v191, v22, v23
	ds_write_b64 v248, v[184:185] offset:8192
	ds_write_b128 v213, v[152:155] offset:24576
	ds_write_b64 v248, v[186:187] offset:12288
	v_sub_f32_e32 v200, v169, v168
	ds_write_b64 v249, v[188:189] offset:8192
	ds_write_b64 v249, v[190:191] offset:12288
	v_mul_f32_e32 v200, 0x3fb8aa3b, v200
	s_waitcnt lgkmcnt(8)
	v_lshlrev_b32_e32 v112, 16, v126
	v_and_b32_e32 v113, 0xffff0000, v126
	v_exp_f32_e32 v200, v200
	v_lshlrev_b32_e32 v114, 16, v127
	v_and_b32_e32 v115, 0xffff0000, v127
	v_lshlrev_b32_e32 v196, 16, v164
	v_mul_f32_e32 v120, 0xbfb8aa3b, v112
	v_and_b32_e32 v197, 0xffff0000, v164
	v_mul_f32_e32 v121, 0xbfb8aa3b, v113
	v_mul_f32_e32 v122, 0xbfb8aa3b, v114
	v_lshlrev_b32_e32 v198, 16, v165
	v_mul_f32_e32 v123, 0xbfb8aa3b, v115
	v_exp_f32_e32 v120, v120
	v_and_b32_e32 v199, 0xffff0000, v165
	v_exp_f32_e32 v121, v121
	v_exp_f32_e32 v122, v122
	v_mul_f32_e32 v196, v196, v118
	v_exp_f32_e32 v123, v123
	v_add_f32_e32 v120, 1.0, v120
	v_mul_f32_e32 v197, v197, v118
	v_add_f32_e32 v121, 1.0, v121
	v_mul_f32_e32 v198, v198, v118
	v_add_f32_e32 v122, 1.0, v122
	v_add_f32_e32 v123, 1.0, v123
	v_mul_f32_e32 v199, v199, v118
	v_rcp_f32_e32 v120, v120
	v_rcp_f32_e32 v121, v121
	v_cvt_pk_bf16_f32 v202, v196, v197
	v_rcp_f32_e32 v122, v122
	v_rcp_f32_e32 v123, v123
	v_cvt_pk_bf16_f32 v203, v198, v199
	v_mul_f32_e32 v112, v120, v112
	v_mul_f32_e32 v113, v121, v113
	ds_write_b64 v215, v[202:203] offset:32768
	v_mul_f32_e32 v114, v122, v114
	v_mul_f32_e32 v196, v196, v200
	v_mul_f32_e32 v115, v123, v115
	v_lshlrev_b32_e32 v120, 16, v124
	v_mul_f32_e32 v197, v197, v200
	v_and_b32_e32 v121, 0xffff0000, v124
	v_lshlrev_b32_e32 v122, 16, v125
	v_mul_f32_e32 v198, v198, v200
	v_and_b32_e32 v123, 0xffff0000, v125
	v_sub_f32_e32 v184, v194, v96
	v_mul_f32_e32 v199, v199, v200
	v_sub_f32_e32 v185, v194, v97
	v_cvt_pk_bf16_f32 v192, v196, v197
	v_sub_f32_e32 v186, v194, v98
	v_sub_f32_e32 v187, v194, v99
	v_cvt_pk_bf16_f32 v193, v198, v199
	v_exp_f32_e32 v184, v184
	v_exp_f32_e32 v185, v185
	ds_write_b64 v215, v[192:193] offset:37888
	v_exp_f32_e32 v186, v186
	v_exp_f32_e32 v187, v187
	ds_write_b64 v217, v[164:165] offset:43008
	v_mul_f32_e32 v184, v48, v184
	v_mul_f32_e32 v185, v49, v185
	ds_write_b64 v217, v[166:167] offset:47616
	v_mul_f32_e32 v186, v50, v186
	v_mul_f32_e32 v201, 0x3fb8aa3b, v168
	v_mul_f32_e32 v187, v51, v187
	v_cndmask_b32_e64 v184, 0, v184, s[14:15]
	ds_write_b32 v218, v201 offset:256
	v_cndmask_b32_e64 v185, 0, v185, s[16:17]
	v_cndmask_b32_e64 v186, 0, v186, s[22:23]
	v_mul_f32_e32 v174, 0x3fb8aa3b, v169
	v_cndmask_b32_e64 v187, 0, v187, s[34:35]
	v_cvt_pk_bf16_f32 v128, v184, v185
	v_exp_f32_e32 v174, v174
	v_cvt_pk_bf16_f32 v129, v186, v187
	v_mov_b32_e32 v130, 0
	v_mov_b32_e32 v131, 0
	s_nop 1
	v_mfma_f32_16x16x32_bf16 v[24:27], v[56:59], v[128:131], v[24:27]
	s_mul_i32 s65, s56, 0x2000
	s_add_u32 s65, s65, 0x304f1000
	s_add_u32 s48, s0, s65
	s_addc_u32 s49, s1, 0
	s_nop 3
	v_fma_f32 v184, s61, v120, v24
	v_fma_f32 v185, s61, v121, v25
	v_fma_f32 v186, s61, v122, v26
	v_fma_f32 v187, s61, v123, v27
	v_mul_f32_e32 v184, v184, v112
	v_mul_f32_e32 v185, v185, v113
	v_mul_f32_e32 v186, v186, v114
	v_mul_f32_e32 v187, v187, v115
	v_cvt_pk_bf16_f32 v170, v184, v185
	v_cvt_pk_bf16_f32 v171, v186, v187
	global_store_dwordx2 v210, v[170:171], s[48:49]
	s_add_u32 s65, s54, 1
	s_sub_u32 s65, s65, s60
	s_lshl_b32 s65, s65, 6
	s_add_u32 s56, s65, s20
	s_waitcnt lgkmcnt(0)
	s_barrier
	s_add_u32 s54, s54, 1
	s_cmp_ge_u32 s54, s39
	s_cbranch_scc1 .Lssd_done
	ds_read_b128 v[28:31], v223
	ds_read_b128 v[32:35], v224
	ds_read_b128 v[40:43], v225
	ds_read_b128 v[44:47], v226
	ds_read_b128 v[48:51], v227 offset:8192
	ds_read_b128 v[52:55], v228 offset:8192
	ds_read_b128 v[56:59], v229 offset:8192
	ds_read_b128 v[60:63], v230 offset:8192
	ds_read_b32 v194, v231 offset:256
	ds_read_b64_tr_b16 v[96:97], v246 offset:16384
	ds_read_b64_tr_b16 v[98:99], v246 offset:20480
	ds_read_b64_tr_b16 v[100:101], v246 offset:24576
	ds_read_b64_tr_b16 v[102:103], v246 offset:28672
	ds_read_b64_tr_b16 v[104:105], v247 offset:16384
	ds_read_b64_tr_b16 v[106:107], v247 offset:20480
	s_waitcnt lgkmcnt(11)
	ds_read_b64_tr_b16 v[108:109], v247 offset:24576
	ds_read_b64_tr_b16 v[110:111], v247 offset:28672
	ds_read_b64_tr_b16 v[112:113], v243 offset:37888
	ds_read_b64_tr_b16 v[114:115], v243 offset:39168
	s_waitcnt lgkmcnt(11)
	ds_read_b64_tr_b16 v[124:125], v243 offset:37920
	ds_read_b64_tr_b16 v[126:127], v243 offset:39200
	ds_read_b64_tr_b16 v[120:121], v243 offset:40448
	ds_read_b64_tr_b16 v[122:123], v243 offset:41728
	global_load_dwordx4 v[156:159], v204, s[40:41] offset:2048
	s_waitcnt lgkmcnt(11)
	ds_read_b64_tr_b16 v[128:129], v243 offset:40480
	ds_read_b64_tr_b16 v[130:131], v243 offset:41760
	ds_read_b128 v[64:67], v223 offset:16384
	ds_read_b128 v[68:71], v224 offset:16384
	s_waitcnt lgkmcnt(11)
; __device__ __forceinline__ void phase_ssd(const Params& P, int seg, unsigned char* smem) {
;     ...
;         auto step = [&](int ci, Pre& R, const int par) {
;             const int row0 = chunk_row0(ci); unsigned char* sb = smem + par * T_BUF; float* acP = acS + par * 64;
;             const bf16* StR = StS + par * (T_STSZ / 2); bf16* StW = StS + (par ^ 1) * (T_STSZ / 2);
;             const float dec = __expf(R.alast);
;             { const float e2 = __expf(R.alast - R.acl);
; #pragma unroll
;               for (int i = 0; i < 2; ++i) { const int q = tid + 512 * i, l = q >> 4, c8 = q & 15; *(v4u*)(sb + T_CS + l * 272 + c8 * 16) = R.Cr[i]; *(v4u*)(sb + T_BS + l * 272 + c8 * 16) = R.Br[i]; }
;               const int l = tid >> 3, p4 = (tid & 7) * 4;
;               const float x0 = bflo(R.Xr.x) * R.dtl, x1 = bfhi(R.Xr.x) * R.dtl, x2 = bflo(R.Xr.y) * R.dtl, x3 = bfhi(R.Xr.y) * R.dtl;
;               v2u d; d.x = cvt_pk_bf16(x0, x1); d.y = cvt_pk_bf16(x2, x3); *(v2u*)(sb + T_XD + l * 80 + p4 * 2) = d;
;               v2u e; e.x = cvt_pk_bf16(x0 * e2, x1 * e2); e.y = cvt_pk_bf16(x2 * e2, x3 * e2); *(v2u*)(sb + T_XE + l * 80 + p4 * 2) = e;
;               *(v2u*)(sb + T_XS + l * 64 + p4 * 2) = R.Xr; *(v2u*)(sb + T_ZS + l * 64 + p4 * 2) = R.Zr;
;               if (w == 0) acP[lane] = R.aclane; }
;             BAR_LDS();
;             if (ci + 2 < nchunks) load_chunk(ci + 2, R);
;             bf16x8 cf[4];
; #pragma unroll
;             for (int k = 0; k < 4; ++k) cf[k] = *(const bf16x8*)(sb + T_CS + (lt * 16 + fr) * 272 + (k * 32 + fq * 8) * 2);
;             f32x4 yo = {0.f, 0.f, 0.f, 0.f};
; #pragma unroll
;             for (int k = 0; k < 4; ++k) { const bf16x8 bb = *(const bf16x8*)((const unsigned char*)StR + (pt * 16 + fr) * 272 + (k * 32 + fq * 8) * 2); yo = mfma16(cf[k], bb, yo); }
; { const f32x4 a4 = *(const f32x4*)(acP + lt * 16 + fq * 4);
; #pragma unroll
;               for (int j = 0; j < 4; ++j) yo[j] *= __expf(a4[j]); }
;             const float acl_fr = acP[lt * 16 + fr]; const int lrow = lt * 16 + fr;
; #pragma unroll
;             for (int t = 0; t < 2; ++t) {
;                 if (2 * t <= lt) {
;                     v2u xb0, xb1;
;                     { const unsigned a0 = lds0 + par * T_BUF + T_XD + (32 * t + 4 * fq + tq) * 80 + (pt * 16 + 4 * tp) * 2, a1 = a0 + 16 * 80; TR_ISSUE(xb0, a0); TR_ISSUE(xb1, a1); }
;                     float m[8];
	ds_read_b128 v[72:75], v225 offset:16384
	global_load_dwordx4 v[160:163], v205, s[40:41] offset:2048
	ds_read_b128 v[76:79], v226 offset:16384
	v_mfma_f32_16x16x32_bf16 v[24:27], v[48:51], v[28:31], 0
	v_mfma_f32_16x16x32_bf16 v[24:27], v[52:55], v[32:35], v[24:27]
	v_mfma_f32_16x16x32_bf16 v[24:27], v[56:59], v[40:43], v[24:27]
	v_mfma_f32_16x16x32_bf16 v[24:27], v[60:63], v[44:47], v[24:27]
	global_load_dwordx4 v[148:151], v204, s[40:41]
	ds_read_b64_tr_b16 v[56:57], v234 offset:32768
	ds_read_b64_tr_b16 v[58:59], v234 offset:34048
	v_mul_f32_e32 v8, v8, v174
	v_mul_f32_e32 v9, v9, v174
	v_mul_f32_e32 v10, v10, v174
	v_mul_f32_e32 v11, v11, v174
	global_load_dwordx4 v[152:155], v205, s[40:41]
	v_mul_f32_e32 v12, v12, v174
	v_mul_f32_e32 v13, v13, v174
	v_mul_f32_e32 v14, v14, v174
	v_mul_f32_e32 v15, v15, v174
	v_mul_f32_e32 v16, v16, v174
	global_load_dwordx2 v[164:165], v206, s[40:41]
	v_mul_f32_e32 v17, v17, v174
	v_mul_f32_e32 v18, v18, v174
	v_mul_f32_e32 v19, v19, v174
	v_mul_f32_e32 v20, v20, v174
	v_mul_f32_e32 v21, v21, v174
	global_load_dwordx2 v[166:167], v207, s[42:43] nt
	v_mul_f32_e32 v22, v22, v174
	v_mul_f32_e32 v23, v23, v174
	s_waitcnt lgkmcnt(12)
	v_mfma_f32_16x16x32_bf16 v[8:11], v[96:99], v[112:115], v[8:11]
	s_waitcnt lgkmcnt(10)
	v_mfma_f32_16x16x32_bf16 v[12:15], v[96:99], v[124:127], v[12:15]
	v_mfma_f32_16x16x32_bf16 v[16:19], v[104:107], v[112:115], v[16:19]
	v_mfma_f32_16x16x32_bf16 v[20:23], v[104:107], v[124:127], v[20:23]
	global_load_dword v118, v208, s[44:45]
	s_waitcnt lgkmcnt(8)
	v_mfma_f32_16x16x32_bf16 v[8:11], v[100:103], v[120:123], v[8:11]
	s_waitcnt lgkmcnt(6)
	v_mfma_f32_16x16x32_bf16 v[12:15], v[100:103], v[128:131], v[12:15]
	v_mfma_f32_16x16x32_bf16 v[16:19], v[108:111], v[120:123], v[16:19]
	v_mfma_f32_16x16x32_bf16 v[20:23], v[108:111], v[128:131], v[20:23]
	ds_read_b128 v[96:99], v232 offset:256
	global_load_dword v168, v208, s[46:47]
	ds_read_b64 v[124:125], v236 offset:43008
	ds_read_b64 v[126:127], v236 offset:47616
	s_waitcnt lgkmcnt(8)
	v_mfma_f32_16x16x32_bf16 v[48:51], v[64:67], v[28:31], 0
	s_waitcnt lgkmcnt(7)
	v_mfma_f32_16x16x32_bf16 v[48:51], v[68:71], v[32:35], v[48:51]
	s_waitcnt lgkmcnt(6)
	v_mfma_f32_16x16x32_bf16 v[48:51], v[72:75], v[40:43], v[48:51]
	global_load_dword v169, v209, s[46:47]
	s_waitcnt lgkmcnt(5)
	v_mfma_f32_16x16x32_bf16 v[48:51], v[76:79], v[44:47], v[48:51]
	v_exp_f32_e32 v195, v194
	s_nop 0
	v_mul_f32_e32 v24, v24, v195
	v_mul_f32_e32 v25, v25, v195
	v_mul_f32_e32 v26, v26, v195
	v_mul_f32_e32 v27, v27, v195
	s_add_u32 s66, s54, 3
	s_cmp_lt_u32 s66, s39
	s_cselect_b32 s74, 0xc0000, 0
	s_cselect_b32 s75, 0x280000, 0
	s_cselect_b32 s76, 0x4000, 0
	s_add_u32 s40, s40, s74
	s_addc_u32 s41, s41, 0
	s_add_u32 s42, s42, s75
	s_addc_u32 s43, s43, 0
	s_add_u32 s44, s44, s76
	s_addc_u32 s45, s45, 0
	s_add_u32 s46, s46, s76
	s_addc_u32 s47, s47, 0
	v_cvt_pk_bf16_f32 v184, v8, v9
	s_waitcnt vmcnt(10)
	v_cvt_pk_bf16_f32 v185, v10, v11
	v_cvt_pk_bf16_f32 v186, v12, v13
	ds_write_b128 v212, v[140:143]
	v_cvt_pk_bf16_f32 v187, v14, v15
	v_cvt_pk_bf16_f32 v188, v16, v17
	ds_write_b128 v212, v[144:147] offset:8192
	v_cvt_pk_bf16_f32 v189, v18, v19
	v_cvt_pk_bf16_f32 v190, v20, v21
	ds_write_b128 v212, v[132:135] offset:16384
	v_cvt_pk_bf16_f32 v191, v22, v23
	ds_write_b64 v248, v[184:185]
	ds_write_b128 v212, v[136:139] offset:24576
	ds_write_b64 v248, v[186:187] offset:4096
	v_sub_f32_e32 v200, v117, v116
	ds_write_b64 v249, v[188:189]
	ds_write_b64 v249, v[190:191] offset:4096
	v_mul_f32_e32 v200, 0x3fb8aa3b, v200
	s_waitcnt lgkmcnt(8)
	v_lshlrev_b32_e32 v112, 16, v126
	v_and_b32_e32 v113, 0xffff0000, v126
	v_exp_f32_e32 v200, v200
	v_lshlrev_b32_e32 v114, 16, v127
	v_and_b32_e32 v115, 0xffff0000, v127
	v_lshlrev_b32_e32 v196, 16, v4
	v_mul_f32_e32 v120, 0xbfb8aa3b, v112
	v_and_b32_e32 v197, 0xffff0000, v4
	v_mul_f32_e32 v121, 0xbfb8aa3b, v113
	v_mul_f32_e32 v122, 0xbfb8aa3b, v114
	v_lshlrev_b32_e32 v198, 16, v5
	v_mul_f32_e32 v123, 0xbfb8aa3b, v115
	v_exp_f32_e32 v120, v120
	v_and_b32_e32 v199, 0xffff0000, v5
	v_exp_f32_e32 v121, v121
	v_exp_f32_e32 v122, v122
	v_mul_f32_e32 v196, v196, v6
	v_exp_f32_e32 v123, v123
	v_add_f32_e32 v120, 1.0, v120
	v_mul_f32_e32 v197, v197, v6
	v_add_f32_e32 v121, 1.0, v121
	v_mul_f32_e32 v198, v198, v6
	v_add_f32_e32 v122, 1.0, v122
	v_add_f32_e32 v123, 1.0, v123
	v_mul_f32_e32 v199, v199, v6
	v_rcp_f32_e32 v120, v120
	v_rcp_f32_e32 v121, v121
	v_cvt_pk_bf16_f32 v202, v196, v197
	v_rcp_f32_e32 v122, v122
	v_rcp_f32_e32 v123, v123
	v_cvt_pk_bf16_f32 v203, v198, v199
	v_mul_f32_e32 v112, v120, v112
	v_mul_f32_e32 v113, v121, v113
	ds_write_b64 v214, v[202:203] offset:32768
	v_mul_f32_e32 v114, v122, v114
	v_mul_f32_e32 v196, v196, v200
	v_mul_f32_e32 v115, v123, v115
	v_lshlrev_b32_e32 v120, 16, v124
	v_mul_f32_e32 v197, v197, v200
	v_and_b32_e32 v121, 0xffff0000, v124
	v_lshlrev_b32_e32 v122, 16, v125
	v_mul_f32_e32 v198, v198, v200
	v_and_b32_e32 v123, 0xffff0000, v125
	v_sub_f32_e32 v184, v194, v96
	v_mul_f32_e32 v199, v199, v200
	v_sub_f32_e32 v185, v194, v97
	v_cvt_pk_bf16_f32 v192, v196, v197
	v_sub_f32_e32 v186, v194, v98
	v_sub_f32_e32 v187, v194, v99
	v_cvt_pk_bf16_f32 v193, v198, v199
	v_exp_f32_e32 v184, v184
	v_exp_f32_e32 v185, v185
	ds_write_b64 v214, v[192:193] offset:37888
	v_exp_f32_e32 v186, v186
	v_exp_f32_e32 v187, v187
	ds_write_b64 v216, v[4:5] offset:43008
	v_mul_f32_e32 v184, v48, v184
	v_mul_f32_e32 v185, v49, v185
	ds_write_b64 v216, v[36:37] offset:47616
	v_mul_f32_e32 v186, v50, v186
	v_mul_f32_e32 v201, 0x3fb8aa3b, v116
	v_mul_f32_e32 v187, v51, v187
	v_cndmask_b32_e64 v184, 0, v184, s[14:15]
	ds_write_b32 v218, v201
	v_cndmask_b32_e64 v185, 0, v185, s[16:17]
	v_cndmask_b32_e64 v186, 0, v186, s[22:23]
	v_mul_f32_e32 v174, 0x3fb8aa3b, v117
	v_cndmask_b32_e64 v187, 0, v187, s[34:35]
	v_cvt_pk_bf16_f32 v128, v184, v185
	v_exp_f32_e32 v174, v174
	v_cvt_pk_bf16_f32 v129, v186, v187
	v_mov_b32_e32 v130, 0
	v_mov_b32_e32 v131, 0
	s_nop 1
	v_mfma_f32_16x16x32_bf16 v[24:27], v[56:59], v[128:131], v[24:27]
	s_mul_i32 s65, s56, 0x2000
	s_add_u32 s65, s65, 0x304f1000
	s_add_u32 s48, s0, s65
	s_addc_u32 s49, s1, 0
	s_nop 3
	v_fma_f32 v184, s61, v120, v24
	v_fma_f32 v185, s61, v121, v25
	v_fma_f32 v186, s61, v122, v26
	v_fma_f32 v187, s61, v123, v27
	v_mul_f32_e32 v184, v184, v112
	v_mul_f32_e32 v185, v185, v113
	v_mul_f32_e32 v186, v186, v114
	v_mul_f32_e32 v187, v187, v115
	v_cvt_pk_bf16_f32 v170, v184, v185
	v_cvt_pk_bf16_f32 v171, v186, v187
	global_store_dwordx2 v210, v[170:171], s[48:49]
	s_add_u32 s65, s54, 1
	s_sub_u32 s65, s65, s60
	s_lshl_b32 s65, s65, 6
	s_add_u32 s56, s65, s20
	s_waitcnt lgkmcnt(0)
	s_barrier
	s_add_u32 s54, s54, 1
	s_cmp_lt_u32 s54, s39
	s_cbranch_scc1 .Lssd_loop0
	s_branch .Lssd_done
; __device__ __forceinline__ void phase_ssd(const Params& P, int seg, unsigned char* smem) {
;     ...
;             bf16x8 cf[4];
; #pragma unroll
;             for (int k = 0; k < 4; ++k) cf[k] = *(const bf16x8*)(sb + T_CS + (lt * 16 + fr) * 272 + (k * 32 + fq * 8) * 2);
;             f32x4 yo = {0.f, 0.f, 0.f, 0.f};
; #pragma unroll
;             for (int k = 0; k < 4; ++k) { const bf16x8 bb = *(const bf16x8*)((const unsigned char*)StR + (pt * 16 + fr) * 272 + (k * 32 + fq * 8) * 2); yo = mfma16(cf[k], bb, yo); }
; { const f32x4 a4 = *(const f32x4*)(acP + lt * 16 + fq * 4);
; #pragma unroll
;               for (int j = 0; j < 4; ++j) yo[j] *= __expf(a4[j]); }
;             const float acl_fr = acP[lt * 16 + fr]; const int lrow = lt * 16 + fr;
; #pragma unroll
;             for (int t = 0; t < 2; ++t) {
;                 if (2 * t <= lt) {
;                     v2u xb0, xb1;
;                     { const unsigned a0 = lds0 + par * T_BUF + T_XD + (32 * t + 4 * fq + tq) * 80 + (pt * 16 + 4 * tp) * 2, a1 = a0 + 16 * 80; TR_ISSUE(xb0, a0); TR_ISSUE(xb1, a1); }
;                     float m[8];
;                     { f32x4 s0 = {0.f, 0.f, 0.f, 0.f}, s1 = {0.f, 0.f, 0.f, 0.f};
; #pragma unroll
;                       for (int k = 0; k < 4; ++k) { const bf16x8 bf0 = *(const bf16x8*)(sb + T_BS + ((2 * t) * 16 + fr) * 272 + (k * 32 + fq * 8) * 2), bf1 = *(const bf16x8*)(sb + T_BS + ((2 * t + 1) * 16 + fr) * 272 + (k * 32 + fq * 8) * 2);
;                           s0 = mfma16(bf0, cf[k], s0); s1 = mfma16(bf1, cf[k], s1); }
;                       const f32x4 a0 = *(const f32x4*)(acP + (2 * t) * 16 + fq * 4), a1 = *(const f32x4*)(acP + (2 * t + 1) * 16 + fq * 4);
; #pragma unroll
;                       for (int j = 0; j < 4; ++j) { const int si0 = (2 * t) * 16 + fq * 4 + j, si1 = si0 + 16;
;                           const float e0 = s0[j] * __expf(fminf(acl_fr - a0[j], 0.f)), e1 = s1[j] * __expf(fminf(acl_fr - a1[j], 0.f));
;                           m[j] = (si0 <= lrow) ? e0 : 0.f; m[4 + j] = (si1 <= lrow) ? e1 : 0.f; } }
;                     v4u mp; mp.x = cvt_pk_bf16(m[0], m[1]); mp.y = cvt_pk_bf16(m[2], m[3]); mp.z = cvt_pk_bf16(m[4], m[5]); mp.w = cvt_pk_bf16(m[6], m[7]);
;                     asm volatile("s_waitcnt lgkmcnt(0)" : "+v"(xb0), "+v"(xb1) :: "memory");
;                     yo = mfma16(__builtin_bit_cast(bf16x8, mp), mk8(xb0, xb1), yo);
.Lssd_loop1:
	ds_read_b128 v[28:31], v219 offset:4096
	ds_read_b128 v[32:35], v220 offset:4096
	ds_read_b128 v[40:43], v221 offset:4096
	ds_read_b128 v[44:47], v222 offset:4096
	ds_read_b128 v[48:51], v227
	ds_read_b128 v[52:55], v228
	ds_read_b128 v[56:59], v229
	ds_read_b128 v[60:63], v230
	ds_read_b32 v194, v231 offset:64
	ds_read_b64_tr_b16 v[96:97], v244 offset:16384
	ds_read_b64_tr_b16 v[98:99], v244 offset:20480
	ds_read_b64_tr_b16 v[100:101], v244 offset:24576
	ds_read_b64_tr_b16 v[102:103], v244 offset:28672
	ds_read_b64_tr_b16 v[104:105], v245 offset:16384
	ds_read_b64_tr_b16 v[106:107], v245 offset:20480
	s_waitcnt lgkmcnt(11)
	ds_read_b64_tr_b16 v[108:109], v245 offset:24576
	ds_read_b64_tr_b16 v[110:111], v245 offset:28672
	ds_read_b64_tr_b16 v[112:113], v237 offset:37888
	ds_read_b64_tr_b16 v[114:115], v237 offset:39168
	s_waitcnt lgkmcnt(11)
	ds_read_b64_tr_b16 v[124:125], v237 offset:37920
	ds_read_b64_tr_b16 v[126:127], v237 offset:39200
	ds_read_b64_tr_b16 v[120:121], v237 offset:40448
	ds_read_b64_tr_b16 v[122:123], v237 offset:41728
	s_waitcnt lgkmcnt(11)
	ds_read_b64_tr_b16 v[128:129], v237 offset:40480
	ds_read_b64_tr_b16 v[130:131], v237 offset:41760
	ds_read_b128 v[64:67], v219 offset:16384
	ds_read_b128 v[68:71], v220 offset:16384
	global_load_dwordx4 v[140:143], v204, s[40:41] offset:2048
	s_waitcnt lgkmcnt(11)
	ds_read_b128 v[72:75], v221 offset:16384
	ds_read_b128 v[76:79], v222 offset:16384
	ds_read_b128 v[80:83], v219 offset:20480
	ds_read_b128 v[84:87], v220 offset:20480
	s_waitcnt lgkmcnt(11)
	ds_read_b128 v[88:91], v221 offset:20480
	ds_read_b128 v[92:95], v222 offset:20480
	global_load_dwordx4 v[144:147], v205, s[40:41] offset:2048
	v_mfma_f32_16x16x32_bf16 v[24:27], v[48:51], v[28:31], 0
	v_mfma_f32_16x16x32_bf16 v[24:27], v[52:55], v[32:35], v[24:27]
	v_mfma_f32_16x16x32_bf16 v[24:27], v[56:59], v[40:43], v[24:27]
	v_mfma_f32_16x16x32_bf16 v[24:27], v[60:63], v[44:47], v[24:27]
	ds_read_b64_tr_b16 v[56:57], v233 offset:32768
	ds_read_b64_tr_b16 v[58:59], v233 offset:34048
	global_load_dwordx4 v[132:135], v204, s[40:41]
	v_mul_f32_e32 v8, v8, v174
	v_mul_f32_e32 v9, v9, v174
	v_mul_f32_e32 v10, v10, v174
	v_mul_f32_e32 v11, v11, v174
	v_mul_f32_e32 v12, v12, v174
	v_mul_f32_e32 v13, v13, v174
	global_load_dwordx4 v[136:139], v205, s[40:41]
	v_mul_f32_e32 v14, v14, v174
	v_mul_f32_e32 v15, v15, v174
	v_mul_f32_e32 v16, v16, v174
	v_mul_f32_e32 v17, v17, v174
	v_mul_f32_e32 v18, v18, v174
	v_mul_f32_e32 v19, v19, v174
	global_load_dwordx2 v[4:5], v206, s[40:41]
	v_mul_f32_e32 v20, v20, v174
	v_mul_f32_e32 v21, v21, v174
	v_mul_f32_e32 v22, v22, v174
	v_mul_f32_e32 v23, v23, v174
	v_mfma_f32_16x16x32_bf16 v[8:11], v[96:99], v[112:115], v[8:11]
	s_waitcnt lgkmcnt(14)
	v_mfma_f32_16x16x32_bf16 v[12:15], v[96:99], v[124:127], v[12:15]
	v_mfma_f32_16x16x32_bf16 v[16:19], v[104:107], v[112:115], v[16:19]
	global_load_dwordx2 v[36:37], v207, s[42:43] nt
	v_mfma_f32_16x16x32_bf16 v[20:23], v[104:107], v[124:127], v[20:23]
	s_waitcnt lgkmcnt(12)
	v_mfma_f32_16x16x32_bf16 v[8:11], v[100:103], v[120:123], v[8:11]
	s_waitcnt lgkmcnt(10)
	v_mfma_f32_16x16x32_bf16 v[12:15], v[100:103], v[128:131], v[12:15]
	v_mfma_f32_16x16x32_bf16 v[16:19], v[108:111], v[120:123], v[16:19]
	v_mfma_f32_16x16x32_bf16 v[20:23], v[108:111], v[128:131], v[20:23]
	ds_read_b128 v[96:99], v232
	global_load_dword v6, v208, s[44:45]
	ds_read_b128 v[100:103], v232 offset:64
	ds_read_b64 v[124:125], v235 offset:44160
	ds_read_b64 v[126:127], v235 offset:48768
	s_waitcnt lgkmcnt(13)
	v_mfma_f32_16x16x32_bf16 v[48:51], v[64:67], v[28:31], 0
	s_waitcnt lgkmcnt(9)
	v_mfma_f32_16x16x32_bf16 v[52:55], v[80:83], v[28:31], 0
	v_mfma_f32_16x16x32_bf16 v[48:51], v[68:71], v[32:35], v[48:51]
	global_load_dword v116, v208, s[46:47]
	s_waitcnt lgkmcnt(8)
	v_mfma_f32_16x16x32_bf16 v[52:55], v[84:87], v[32:35], v[52:55]
	v_mfma_f32_16x16x32_bf16 v[48:51], v[72:75], v[40:43], v[48:51]
	s_waitcnt lgkmcnt(7)
	v_mfma_f32_16x16x32_bf16 v[52:55], v[88:91], v[40:43], v[52:55]
	v_mfma_f32_16x16x32_bf16 v[48:51], v[76:79], v[44:47], v[48:51]
	s_waitcnt lgkmcnt(6)
	v_mfma_f32_16x16x32_bf16 v[52:55], v[92:95], v[44:47], v[52:55]
	v_exp_f32_e32 v195, v194
	global_load_dword v117, v209, s[46:47]
	v_mul_f32_e32 v24, v24, v195
	v_mul_f32_e32 v25, v25, v195
	v_mul_f32_e32 v26, v26, v195
	v_mul_f32_e32 v27, v27, v195
	v_cvt_pk_bf16_f32 v184, v8, v9
	v_cvt_pk_bf16_f32 v185, v10, v11
	s_add_u32 s66, s54, 3
	s_cmp_lt_u32 s66, s39
	s_cselect_b32 s74, 0xc0000, 0
	s_cselect_b32 s75, 0x280000, 0
	s_cselect_b32 s76, 0x4000, 0
	s_add_u32 s40, s40, s74
	s_addc_u32 s41, s41, 0
	s_add_u32 s42, s42, s75
	s_addc_u32 s43, s43, 0
	s_add_u32 s44, s44, s76
	s_addc_u32 s45, s45, 0
	s_add_u32 s46, s46, s76
	s_addc_u32 s47, s47, 0
	v_cvt_pk_bf16_f32 v186, v12, v13
	v_cvt_pk_bf16_f32 v187, v14, v15
	s_waitcnt vmcnt(10)
	v_cvt_pk_bf16_f32 v188, v16, v17
	v_cvt_pk_bf16_f32 v189, v18, v19
	ds_write_b128 v213, v[156:159]
	v_cvt_pk_bf16_f32 v190, v20, v21
	v_cvt_pk_bf16_f32 v191, v22, v23
	ds_write_b64 v248, v[184:185] offset:8192
	ds_write_b128 v213, v[160:163] offset:8192
	ds_write_b64 v248, v[186:187] offset:12288
	ds_write_b64 v249, v[188:189] offset:8192
	ds_write_b128 v213, v[148:151] offset:16384
	ds_write_b64 v249, v[190:191] offset:12288
	s_waitcnt lgkmcnt(7)
; __device__ __forceinline__ void phase_ssd(const Params& P, int seg, unsigned char* smem) {
;     ...
;             for (int t = 0; t < 2; ++t) {
;                 if (2 * t <= lt) {
;                     v2u xb0, xb1;
;                     { const unsigned a0 = lds0 + par * T_BUF + T_XD + (32 * t + 4 * fq + tq) * 80 + (pt * 16 + 4 * tp) * 2, a1 = a0 + 16 * 80; TR_ISSUE(xb0, a0); TR_ISSUE(xb1, a1); }
;                     float m[8];
;                     { f32x4 s0 = {0.f, 0.f, 0.f, 0.f}, s1 = {0.f, 0.f, 0.f, 0.f};
; #pragma unroll
;                       for (int k = 0; k < 4; ++k) { const bf16x8 bf0 = *(const bf16x8*)(sb + T_BS + ((2 * t) * 16 + fr) * 272 + (k * 32 + fq * 8) * 2), bf1 = *(const bf16x8*)(sb + T_BS + ((2 * t + 1) * 16 + fr) * 272 + (k * 32 + fq * 8) * 2);
;                           s0 = mfma16(bf0, cf[k], s0); s1 = mfma16(bf1, cf[k], s1); }
;                       const f32x4 a0 = *(const f32x4*)(acP + (2 * t) * 16 + fq * 4), a1 = *(const f32x4*)(acP + (2 * t + 1) * 16 + fq * 4);
; #pragma unroll
;                       for (int j = 0; j < 4; ++j) { const int si0 = (2 * t) * 16 + fq * 4 + j, si1 = si0 + 16;
;                           const float e0 = s0[j] * __expf(fminf(acl_fr - a0[j], 0.f)), e1 = s1[j] * __expf(fminf(acl_fr - a1[j], 0.f));
;                           m[j] = (si0 <= lrow) ? e0 : 0.f; m[4 + j] = (si1 <= lrow) ? e1 : 0.f; } }
;                     v4u mp; mp.x = cvt_pk_bf16(m[0], m[1]); mp.y = cvt_pk_bf16(m[2], m[3]); mp.z = cvt_pk_bf16(m[4], m[5]); mp.w = cvt_pk_bf16(m[6], m[7]);
;                     asm volatile("s_waitcnt lgkmcnt(0)" : "+v"(xb0), "+v"(xb1) :: "memory");
;                     yo = mfma16(__builtin_bit_cast(bf16x8, mp), mk8(xb0, xb1), yo);
;                 }
;             }
; #pragma unroll
;             for (int j = 0; j < 4; ++j) { const int l = lt * 16 + fq * 4 + j, p = pt * 16 + fr; const float xv = bf2f(*(const bf16*)(sb + T_XS + l * 64 + p * 2)), zv = bf2f(*(const bf16*)(sb + T_ZS + l * 64 + p * 2));
;                 ypre[(size_t)(row0 + l) * DINNER + h * 64 + ph * 32 + p] = f2bfh((yo[j] + Dh * xv) * siluf_(zv)); }
;             { v2u xa[2][2][2], bb[2][2];
; #pragma unroll
;               for (int kk = 0; kk < 2; ++kk) {
; #pragma unroll
;                   for (int hh = 0; hh < 2; ++hh) { const int r = kk * 32 + 8 * fq + 4 * hh + tq;
	v_lshlrev_b32_e32 v112, 16, v126
	ds_write_b128 v213, v[152:155] offset:24576
	v_and_b32_e32 v113, 0xffff0000, v126
	v_lshlrev_b32_e32 v114, 16, v127
	v_sub_f32_e32 v200, v169, v168
	v_and_b32_e32 v115, 0xffff0000, v127
	v_mul_f32_e32 v120, 0xbfb8aa3b, v112
	v_mul_f32_e32 v200, 0x3fb8aa3b, v200
	v_mul_f32_e32 v121, 0xbfb8aa3b, v113
	v_mul_f32_e32 v122, 0xbfb8aa3b, v114
	v_exp_f32_e32 v200, v200
	v_mul_f32_e32 v123, 0xbfb8aa3b, v115
	v_exp_f32_e32 v120, v120
	v_lshlrev_b32_e32 v196, 16, v164
	v_exp_f32_e32 v121, v121
	v_exp_f32_e32 v122, v122
	v_and_b32_e32 v197, 0xffff0000, v164
	v_exp_f32_e32 v123, v123
	v_add_f32_e32 v120, 1.0, v120
	v_lshlrev_b32_e32 v198, 16, v165
	v_add_f32_e32 v121, 1.0, v121
	v_add_f32_e32 v122, 1.0, v122
	v_and_b32_e32 v199, 0xffff0000, v165
	v_add_f32_e32 v123, 1.0, v123
	v_rcp_f32_e32 v120, v120
	v_mul_f32_e32 v196, v196, v118
	v_rcp_f32_e32 v121, v121
	v_rcp_f32_e32 v122, v122
	v_mul_f32_e32 v197, v197, v118
	v_rcp_f32_e32 v123, v123
	v_mul_f32_e32 v112, v120, v112
	v_mul_f32_e32 v198, v198, v118
	v_mul_f32_e32 v113, v121, v113
	v_mul_f32_e32 v114, v122, v114
	v_mul_f32_e32 v199, v199, v118
	v_mul_f32_e32 v115, v123, v115
	v_lshlrev_b32_e32 v120, 16, v124
	v_cvt_pk_bf16_f32 v202, v196, v197
	v_and_b32_e32 v121, 0xffff0000, v124
	v_lshlrev_b32_e32 v122, 16, v125
	v_and_b32_e32 v123, 0xffff0000, v125
	v_cvt_pk_bf16_f32 v203, v198, v199
	v_sub_f32_e32 v184, v194, v96
	v_sub_f32_e32 v185, v194, v97
	ds_write_b64 v215, v[202:203] offset:32768
	v_sub_f32_e32 v186, v194, v98
	v_sub_f32_e32 v187, v194, v99
	v_mul_f32_e32 v196, v196, v200
	v_exp_f32_e32 v184, v184
	v_exp_f32_e32 v185, v185
	v_mul_f32_e32 v197, v197, v200
	v_exp_f32_e32 v186, v186
	v_exp_f32_e32 v187, v187
	v_mul_f32_e32 v198, v198, v200
	v_mul_f32_e32 v184, v48, v184
	v_mul_f32_e32 v185, v49, v185
	v_mul_f32_e32 v199, v199, v200
	v_mul_f32_e32 v186, v50, v186
	v_mul_f32_e32 v187, v51, v187
	v_cvt_pk_bf16_f32 v192, v196, v197
	v_sub_f32_e32 v188, v194, v100
	v_sub_f32_e32 v189, v194, v101
	v_cvt_pk_bf16_f32 v193, v198, v199
	v_sub_f32_e32 v190, v194, v102
	v_sub_f32_e32 v191, v194, v103
	ds_write_b64 v215, v[192:193] offset:37888
	v_exp_f32_e32 v188, v188
	v_exp_f32_e32 v189, v189
	ds_write_b64 v217, v[164:165] offset:43008
	v_exp_f32_e32 v190, v190
	v_exp_f32_e32 v191, v191
	ds_write_b64 v217, v[166:167] offset:47616
	v_mul_f32_e32 v188, v52, v188
	v_mul_f32_e32 v189, v53, v189
	v_mul_f32_e32 v201, 0x3fb8aa3b, v168
	v_mul_f32_e32 v190, v54, v190
	v_mul_f32_e32 v191, v55, v191
	ds_write_b32 v218, v201 offset:256
	v_cndmask_b32_e64 v188, 0, v188, s[14:15]
	v_cndmask_b32_e64 v189, 0, v189, s[16:17]
	v_mul_f32_e32 v174, 0x3fb8aa3b, v169
	v_cndmask_b32_e64 v190, 0, v190, s[22:23]
	v_cndmask_b32_e64 v191, 0, v191, s[34:35]
	v_exp_f32_e32 v174, v174
	v_cvt_pk_bf16_f32 v128, v184, v185
	v_cvt_pk_bf16_f32 v129, v186, v187
	v_cvt_pk_bf16_f32 v130, v188, v189
	v_cvt_pk_bf16_f32 v131, v190, v191
	s_nop 1
	v_mfma_f32_16x16x32_bf16 v[24:27], v[56:59], v[128:131], v[24:27]
	s_mul_i32 s65, s56, 0x2000
	s_add_u32 s65, s65, 0x304f1000
	s_add_u32 s48, s0, s65
	s_addc_u32 s49, s1, 0
	s_nop 3
	v_fma_f32 v184, s61, v120, v24
	v_fma_f32 v185, s61, v121, v25
	v_fma_f32 v186, s61, v122, v26
	v_fma_f32 v187, s61, v123, v27
	v_mul_f32_e32 v184, v184, v112
	v_mul_f32_e32 v185, v185, v113
	v_mul_f32_e32 v186, v186, v114
	v_mul_f32_e32 v187, v187, v115
	v_cvt_pk_bf16_f32 v170, v184, v185
	v_cvt_pk_bf16_f32 v171, v186, v187
	global_store_dwordx2 v210, v[170:171], s[48:49]
	s_add_u32 s65, s54, 1
	s_sub_u32 s65, s65, s60
	s_lshl_b32 s65, s65, 6
	s_add_u32 s56, s65, s20
	s_waitcnt lgkmcnt(0)
	s_barrier
	s_add_u32 s54, s54, 1
	s_cmp_ge_u32 s54, s39
	s_cbranch_scc1 .Lssd_done
	ds_read_b128 v[28:31], v223 offset:4096
	ds_read_b128 v[32:35], v224 offset:4096
	ds_read_b128 v[40:43], v225 offset:4096
	ds_read_b128 v[44:47], v226 offset:4096
	ds_read_b128 v[48:51], v227 offset:8192
	ds_read_b128 v[52:55], v228 offset:8192
	ds_read_b128 v[56:59], v229 offset:8192
	ds_read_b128 v[60:63], v230 offset:8192
	ds_read_b32 v194, v231 offset:320
	ds_read_b64_tr_b16 v[96:97], v246 offset:16384
	ds_read_b64_tr_b16 v[98:99], v246 offset:20480
	ds_read_b64_tr_b16 v[100:101], v246 offset:24576
	ds_read_b64_tr_b16 v[102:103], v246 offset:28672
	ds_read_b64_tr_b16 v[104:105], v247 offset:16384
	ds_read_b64_tr_b16 v[106:107], v247 offset:20480
	s_waitcnt lgkmcnt(11)
	ds_read_b64_tr_b16 v[108:109], v247 offset:24576
	ds_read_b64_tr_b16 v[110:111], v247 offset:28672
	ds_read_b64_tr_b16 v[112:113], v243 offset:37888
	ds_read_b64_tr_b16 v[114:115], v243 offset:39168
	s_waitcnt lgkmcnt(11)
	ds_read_b64_tr_b16 v[124:125], v243 offset:37920
	ds_read_b64_tr_b16 v[126:127], v243 offset:39200
	ds_read_b64_tr_b16 v[120:121], v243 offset:40448
	ds_read_b64_tr_b16 v[122:123], v243 offset:41728
	s_waitcnt lgkmcnt(11)
	ds_read_b64_tr_b16 v[128:129], v243 offset:40480
	ds_read_b64_tr_b16 v[130:131], v243 offset:41760
	ds_read_b128 v[64:67], v223 offset:16384
	ds_read_b128 v[68:71], v224 offset:16384
	global_load_dwordx4 v[156:159], v204, s[40:41] offset:2048
	s_waitcnt lgkmcnt(11)
	ds_read_b128 v[72:75], v225 offset:16384
	ds_read_b128 v[76:79], v226 offset:16384
	ds_read_b128 v[80:83], v223 offset:20480
	ds_read_b128 v[84:87], v224 offset:20480
	s_waitcnt lgkmcnt(11)
; __device__ __forceinline__ void phase_ssd(const Params& P, int seg, unsigned char* smem) {
;     ...
;             bf16x8 cf[4];
; #pragma unroll
;             for (int k = 0; k < 4; ++k) cf[k] = *(const bf16x8*)(sb + T_CS + (lt * 16 + fr) * 272 + (k * 32 + fq * 8) * 2);
;             f32x4 yo = {0.f, 0.f, 0.f, 0.f};
; #pragma unroll
;             for (int k = 0; k < 4; ++k) { const bf16x8 bb = *(const bf16x8*)((const unsigned char*)StR + (pt * 16 + fr) * 272 + (k * 32 + fq * 8) * 2); yo = mfma16(cf[k], bb, yo); }
; { const f32x4 a4 = *(const f32x4*)(acP + lt * 16 + fq * 4);
; #pragma unroll
;               for (int j = 0; j < 4; ++j) yo[j] *= __expf(a4[j]); }
;             const float acl_fr = acP[lt * 16 + fr]; const int lrow = lt * 16 + fr;
; #pragma unroll
;             for (int t = 0; t < 2; ++t) {
;                 if (2 * t <= lt) {
;                     v2u xb0, xb1;
;                     { const unsigned a0 = lds0 + par * T_BUF + T_XD + (32 * t + 4 * fq + tq) * 80 + (pt * 16 + 4 * tp) * 2, a1 = a0 + 16 * 80; TR_ISSUE(xb0, a0); TR_ISSUE(xb1, a1); }
;                     float m[8];
;                     { f32x4 s0 = {0.f, 0.f, 0.f, 0.f}, s1 = {0.f, 0.f, 0.f, 0.f};
; #pragma unroll
;                       for (int k = 0; k < 4; ++k) { const bf16x8 bf0 = *(const bf16x8*)(sb + T_BS + ((2 * t) * 16 + fr) * 272 + (k * 32 + fq * 8) * 2), bf1 = *(const bf16x8*)(sb + T_BS + ((2 * t + 1) * 16 + fr) * 272 + (k * 32 + fq * 8) * 2);
;                           s0 = mfma16(bf0, cf[k], s0); s1 = mfma16(bf1, cf[k], s1); }
;                       const f32x4 a0 = *(const f32x4*)(acP + (2 * t) * 16 + fq * 4), a1 = *(const f32x4*)(acP + (2 * t + 1) * 16 + fq * 4);
; #pragma unroll
;                       for (int j = 0; j < 4; ++j) { const int si0 = (2 * t) * 16 + fq * 4 + j, si1 = si0 + 16;
;                           const float e0 = s0[j] * __expf(fminf(acl_fr - a0[j], 0.f)), e1 = s1[j] * __expf(fminf(acl_fr - a1[j], 0.f));
;                           m[j] = (si0 <= lrow) ? e0 : 0.f; m[4 + j] = (si1 <= lrow) ? e1 : 0.f; } }
;                     v4u mp; mp.x = cvt_pk_bf16(m[0], m[1]); mp.y = cvt_pk_bf16(m[2], m[3]); mp.z = cvt_pk_bf16(m[4], m[5]); mp.w = cvt_pk_bf16(m[6], m[7]);
;                     asm volatile("s_waitcnt lgkmcnt(0)" : "+v"(xb0), "+v"(xb1) :: "memory");
;                     yo = mfma16(__builtin_bit_cast(bf16x8, mp), mk8(xb0, xb1), yo);
	ds_read_b128 v[88:91], v225 offset:20480
	ds_read_b128 v[92:95], v226 offset:20480
	global_load_dwordx4 v[160:163], v205, s[40:41] offset:2048
	v_mfma_f32_16x16x32_bf16 v[24:27], v[48:51], v[28:31], 0
	v_mfma_f32_16x16x32_bf16 v[24:27], v[52:55], v[32:35], v[24:27]
	v_mfma_f32_16x16x32_bf16 v[24:27], v[56:59], v[40:43], v[24:27]
	v_mfma_f32_16x16x32_bf16 v[24:27], v[60:63], v[44:47], v[24:27]
	ds_read_b64_tr_b16 v[56:57], v234 offset:32768
	ds_read_b64_tr_b16 v[58:59], v234 offset:34048
	global_load_dwordx4 v[148:151], v204, s[40:41]
	v_mul_f32_e32 v8, v8, v174
	v_mul_f32_e32 v9, v9, v174
	v_mul_f32_e32 v10, v10, v174
	v_mul_f32_e32 v11, v11, v174
	v_mul_f32_e32 v12, v12, v174
	v_mul_f32_e32 v13, v13, v174
	global_load_dwordx4 v[152:155], v205, s[40:41]
	v_mul_f32_e32 v14, v14, v174
	v_mul_f32_e32 v15, v15, v174
	v_mul_f32_e32 v16, v16, v174
	v_mul_f32_e32 v17, v17, v174
	v_mul_f32_e32 v18, v18, v174
	v_mul_f32_e32 v19, v19, v174
	global_load_dwordx2 v[164:165], v206, s[40:41]
	v_mul_f32_e32 v20, v20, v174
	v_mul_f32_e32 v21, v21, v174
	v_mul_f32_e32 v22, v22, v174
	v_mul_f32_e32 v23, v23, v174
	v_mfma_f32_16x16x32_bf16 v[8:11], v[96:99], v[112:115], v[8:11]
	s_waitcnt lgkmcnt(14)
	v_mfma_f32_16x16x32_bf16 v[12:15], v[96:99], v[124:127], v[12:15]
	v_mfma_f32_16x16x32_bf16 v[16:19], v[104:107], v[112:115], v[16:19]
	global_load_dwordx2 v[166:167], v207, s[42:43] nt
	v_mfma_f32_16x16x32_bf16 v[20:23], v[104:107], v[124:127], v[20:23]
	s_waitcnt lgkmcnt(12)
	v_mfma_f32_16x16x32_bf16 v[8:11], v[100:103], v[120:123], v[8:11]
	s_waitcnt lgkmcnt(10)
	v_mfma_f32_16x16x32_bf16 v[12:15], v[100:103], v[128:131], v[12:15]
	v_mfma_f32_16x16x32_bf16 v[16:19], v[108:111], v[120:123], v[16:19]
	v_mfma_f32_16x16x32_bf16 v[20:23], v[108:111], v[128:131], v[20:23]
	ds_read_b128 v[96:99], v232 offset:256
	global_load_dword v118, v208, s[44:45]
	ds_read_b128 v[100:103], v232 offset:320
	ds_read_b64 v[124:125], v236 offset:44160
	ds_read_b64 v[126:127], v236 offset:48768
	s_waitcnt lgkmcnt(13)
	v_mfma_f32_16x16x32_bf16 v[48:51], v[64:67], v[28:31], 0
	s_waitcnt lgkmcnt(9)
	v_mfma_f32_16x16x32_bf16 v[52:55], v[80:83], v[28:31], 0
	v_mfma_f32_16x16x32_bf16 v[48:51], v[68:71], v[32:35], v[48:51]
	global_load_dword v168, v208, s[46:47]
	s_waitcnt lgkmcnt(8)
	v_mfma_f32_16x16x32_bf16 v[52:55], v[84:87], v[32:35], v[52:55]
	v_mfma_f32_16x16x32_bf16 v[48:51], v[72:75], v[40:43], v[48:51]
	s_waitcnt lgkmcnt(7)
	v_mfma_f32_16x16x32_bf16 v[52:55], v[88:91], v[40:43], v[52:55]
	v_mfma_f32_16x16x32_bf16 v[48:51], v[76:79], v[44:47], v[48:51]
	s_waitcnt lgkmcnt(6)
	v_mfma_f32_16x16x32_bf16 v[52:55], v[92:95], v[44:47], v[52:55]
	v_exp_f32_e32 v195, v194
	global_load_dword v169, v209, s[46:47]
	v_mul_f32_e32 v24, v24, v195
	v_mul_f32_e32 v25, v25, v195
	v_mul_f32_e32 v26, v26, v195
	v_mul_f32_e32 v27, v27, v195
	v_cvt_pk_bf16_f32 v184, v8, v9
	v_cvt_pk_bf16_f32 v185, v10, v11
	s_add_u32 s66, s54, 3
	s_cmp_lt_u32 s66, s39
	s_cselect_b32 s74, 0xc0000, 0
	s_cselect_b32 s75, 0x280000, 0
	s_cselect_b32 s76, 0x4000, 0
	s_add_u32 s40, s40, s74
	s_addc_u32 s41, s41, 0
	s_add_u32 s42, s42, s75
	s_addc_u32 s43, s43, 0
	s_add_u32 s44, s44, s76
	s_addc_u32 s45, s45, 0
	s_add_u32 s46, s46, s76
	s_addc_u32 s47, s47, 0
	v_cvt_pk_bf16_f32 v186, v12, v13
	v_cvt_pk_bf16_f32 v187, v14, v15
	s_waitcnt vmcnt(10)
	v_cvt_pk_bf16_f32 v188, v16, v17
	v_cvt_pk_bf16_f32 v189, v18, v19
	ds_write_b128 v212, v[140:143]
	v_cvt_pk_bf16_f32 v190, v20, v21
	v_cvt_pk_bf16_f32 v191, v22, v23
	ds_write_b64 v248, v[184:185]
	ds_write_b128 v212, v[144:147] offset:8192
	ds_write_b64 v248, v[186:187] offset:4096
	ds_write_b64 v249, v[188:189]
	ds_write_b128 v212, v[132:135] offset:16384
	ds_write_b64 v249, v[190:191] offset:4096
	s_waitcnt lgkmcnt(7)
	v_lshlrev_b32_e32 v112, 16, v126
	ds_write_b128 v212, v[136:139] offset:24576
	v_and_b32_e32 v113, 0xffff0000, v126
	v_lshlrev_b32_e32 v114, 16, v127
	v_sub_f32_e32 v200, v117, v116
	v_and_b32_e32 v115, 0xffff0000, v127
	v_mul_f32_e32 v120, 0xbfb8aa3b, v112
	v_mul_f32_e32 v200, 0x3fb8aa3b, v200
	v_mul_f32_e32 v121, 0xbfb8aa3b, v113
	v_mul_f32_e32 v122, 0xbfb8aa3b, v114
	v_exp_f32_e32 v200, v200
	v_mul_f32_e32 v123, 0xbfb8aa3b, v115
	v_exp_f32_e32 v120, v120
	v_lshlrev_b32_e32 v196, 16, v4
	v_exp_f32_e32 v121, v121
	v_exp_f32_e32 v122, v122
	v_and_b32_e32 v197, 0xffff0000, v4
	v_exp_f32_e32 v123, v123
	v_add_f32_e32 v120, 1.0, v120
	v_lshlrev_b32_e32 v198, 16, v5
	v_add_f32_e32 v121, 1.0, v121
	v_add_f32_e32 v122, 1.0, v122
	v_and_b32_e32 v199, 0xffff0000, v5
	v_add_f32_e32 v123, 1.0, v123
	v_rcp_f32_e32 v120, v120
	v_mul_f32_e32 v196, v196, v6
	v_rcp_f32_e32 v121, v121
	v_rcp_f32_e32 v122, v122
	v_mul_f32_e32 v197, v197, v6
	v_rcp_f32_e32 v123, v123
	v_mul_f32_e32 v112, v120, v112
	v_mul_f32_e32 v198, v198, v6
	v_mul_f32_e32 v113, v121, v113
	v_mul_f32_e32 v114, v122, v114
	v_mul_f32_e32 v199, v199, v6
	v_mul_f32_e32 v115, v123, v115
	v_lshlrev_b32_e32 v120, 16, v124
	v_cvt_pk_bf16_f32 v202, v196, v197
	v_and_b32_e32 v121, 0xffff0000, v124
	v_lshlrev_b32_e32 v122, 16, v125
	v_and_b32_e32 v123, 0xffff0000, v125
	v_cvt_pk_bf16_f32 v203, v198, v199
	v_sub_f32_e32 v184, v194, v96
	v_sub_f32_e32 v185, v194, v97
	ds_write_b64 v214, v[202:203] offset:32768
	v_sub_f32_e32 v186, v194, v98
	v_sub_f32_e32 v187, v194, v99
	v_mul_f32_e32 v196, v196, v200
	v_exp_f32_e32 v184, v184
	v_exp_f32_e32 v185, v185
	v_mul_f32_e32 v197, v197, v200
	v_exp_f32_e32 v186, v186
	v_exp_f32_e32 v187, v187
	v_mul_f32_e32 v198, v198, v200
	v_mul_f32_e32 v184, v48, v184
	v_mul_f32_e32 v185, v49, v185
	v_mul_f32_e32 v199, v199, v200
	v_mul_f32_e32 v186, v50, v186
	v_mul_f32_e32 v187, v51, v187
; __device__ __forceinline__ void phase_ssd(const Params& P, int seg, unsigned char* smem) {
;     ...
;             bf16x8 cf[4];
; #pragma unroll
;             for (int k = 0; k < 4; ++k) cf[k] = *(const bf16x8*)(sb + T_CS + (lt * 16 + fr) * 272 + (k * 32 + fq * 8) * 2);
;             f32x4 yo = {0.f, 0.f, 0.f, 0.f};
; #pragma unroll
;             for (int k = 0; k < 4; ++k) { const bf16x8 bb = *(const bf16x8*)((const unsigned char*)StR + (pt * 16 + fr) * 272 + (k * 32 + fq * 8) * 2); yo = mfma16(cf[k], bb, yo); }
; { const f32x4 a4 = *(const f32x4*)(acP + lt * 16 + fq * 4);
; #pragma unroll
;               for (int j = 0; j < 4; ++j) yo[j] *= __expf(a4[j]); }
;             const float acl_fr = acP[lt * 16 + fr]; const int lrow = lt * 16 + fr;
; #pragma unroll
;             for (int t = 0; t < 2; ++t) {
;                 if (2 * t <= lt) {
;                     v2u xb0, xb1;
;                     { const unsigned a0 = lds0 + par * T_BUF + T_XD + (32 * t + 4 * fq + tq) * 80 + (pt * 16 + 4 * tp) * 2, a1 = a0 + 16 * 80; TR_ISSUE(xb0, a0); TR_ISSUE(xb1, a1); }
;                     float m[8];
;                     { f32x4 s0 = {0.f, 0.f, 0.f, 0.f}, s1 = {0.f, 0.f, 0.f, 0.f};
; #pragma unroll
;                       for (int k = 0; k < 4; ++k) { const bf16x8 bf0 = *(const bf16x8*)(sb + T_BS + ((2 * t) * 16 + fr) * 272 + (k * 32 + fq * 8) * 2), bf1 = *(const bf16x8*)(sb + T_BS + ((2 * t + 1) * 16 + fr) * 272 + (k * 32 + fq * 8) * 2);
;                           s0 = mfma16(bf0, cf[k], s0); s1 = mfma16(bf1, cf[k], s1); }
;                       const f32x4 a0 = *(const f32x4*)(acP + (2 * t) * 16 + fq * 4), a1 = *(const f32x4*)(acP + (2 * t + 1) * 16 + fq * 4);
; #pragma unroll
;                       for (int j = 0; j < 4; ++j) { const int si0 = (2 * t) * 16 + fq * 4 + j, si1 = si0 + 16;
;                           const float e0 = s0[j] * __expf(fminf(acl_fr - a0[j], 0.f)), e1 = s1[j] * __expf(fminf(acl_fr - a1[j], 0.f));
;                           m[j] = (si0 <= lrow) ? e0 : 0.f; m[4 + j] = (si1 <= lrow) ? e1 : 0.f; } }
;                     v4u mp; mp.x = cvt_pk_bf16(m[0], m[1]); mp.y = cvt_pk_bf16(m[2], m[3]); mp.z = cvt_pk_bf16(m[4], m[5]); mp.w = cvt_pk_bf16(m[6], m[7]);
;                     asm volatile("s_waitcnt lgkmcnt(0)" : "+v"(xb0), "+v"(xb1) :: "memory");
;                     yo = mfma16(__builtin_bit_cast(bf16x8, mp), mk8(xb0, xb1), yo);
	v_cvt_pk_bf16_f32 v192, v196, v197
	v_sub_f32_e32 v188, v194, v100
	v_sub_f32_e32 v189, v194, v101
	v_cvt_pk_bf16_f32 v193, v198, v199
	v_sub_f32_e32 v190, v194, v102
	v_sub_f32_e32 v191, v194, v103
	ds_write_b64 v214, v[192:193] offset:37888
	v_exp_f32_e32 v188, v188
	v_exp_f32_e32 v189, v189
	ds_write_b64 v216, v[4:5] offset:43008
	v_exp_f32_e32 v190, v190
	v_exp_f32_e32 v191, v191
	ds_write_b64 v216, v[36:37] offset:47616
	v_mul_f32_e32 v188, v52, v188
	v_mul_f32_e32 v189, v53, v189
	v_mul_f32_e32 v201, 0x3fb8aa3b, v116
	v_mul_f32_e32 v190, v54, v190
	v_mul_f32_e32 v191, v55, v191
	ds_write_b32 v218, v201
	v_cndmask_b32_e64 v188, 0, v188, s[14:15]
	v_cndmask_b32_e64 v189, 0, v189, s[16:17]
	v_mul_f32_e32 v174, 0x3fb8aa3b, v117
	v_cndmask_b32_e64 v190, 0, v190, s[22:23]
	v_cndmask_b32_e64 v191, 0, v191, s[34:35]
	v_exp_f32_e32 v174, v174
	v_cvt_pk_bf16_f32 v128, v184, v185
	v_cvt_pk_bf16_f32 v129, v186, v187
	v_cvt_pk_bf16_f32 v130, v188, v189
	v_cvt_pk_bf16_f32 v131, v190, v191
	s_nop 1
	v_mfma_f32_16x16x32_bf16 v[24:27], v[56:59], v[128:131], v[24:27]
	s_mul_i32 s65, s56, 0x2000
	s_add_u32 s65, s65, 0x304f1000
	s_add_u32 s48, s0, s65
	s_addc_u32 s49, s1, 0
	s_nop 3
	v_fma_f32 v184, s61, v120, v24
	v_fma_f32 v185, s61, v121, v25
	v_fma_f32 v186, s61, v122, v26
	v_fma_f32 v187, s61, v123, v27
	v_mul_f32_e32 v184, v184, v112
	v_mul_f32_e32 v185, v185, v113
	v_mul_f32_e32 v186, v186, v114
	v_mul_f32_e32 v187, v187, v115
	v_cvt_pk_bf16_f32 v170, v184, v185
	v_cvt_pk_bf16_f32 v171, v186, v187
	global_store_dwordx2 v210, v[170:171], s[48:49]
	s_add_u32 s65, s54, 1
	s_sub_u32 s65, s65, s60
	s_lshl_b32 s65, s65, 6
	s_add_u32 s56, s65, s20
	s_waitcnt lgkmcnt(0)
	s_barrier
	s_add_u32 s54, s54, 1
	s_cmp_lt_u32 s54, s39
	s_cbranch_scc1 .Lssd_loop1
	s_branch .Lssd_done
.Lssd_loop2:
	ds_read_b128 v[28:31], v219 offset:8192
	ds_read_b128 v[32:35], v220 offset:8192
	ds_read_b128 v[40:43], v221 offset:8192
	ds_read_b128 v[44:47], v222 offset:8192
	ds_read_b128 v[48:51], v227
	ds_read_b128 v[52:55], v228
	ds_read_b128 v[56:59], v229
	ds_read_b128 v[60:63], v230
	ds_read_b32 v194, v231 offset:128
	ds_read_b128 v[64:67], v219 offset:16384
	ds_read_b128 v[68:71], v220 offset:16384
	ds_read_b128 v[72:75], v221 offset:16384
	ds_read_b128 v[76:79], v222 offset:16384
	ds_read_b128 v[80:83], v219 offset:20480
	ds_read_b128 v[84:87], v220 offset:20480
	global_load_dwordx4 v[140:143], v204, s[40:41] offset:2048
	s_waitcnt lgkmcnt(11)
	ds_read_b128 v[88:91], v221 offset:20480
	ds_read_b128 v[92:95], v222 offset:20480
	ds_read_b128 v[96:99], v232
	ds_read_b128 v[100:103], v232 offset:64
	s_waitcnt lgkmcnt(11)
	ds_read_b64 v[124:125], v235 offset:45312
	global_load_dwordx4 v[144:147], v205, s[40:41] offset:2048
	ds_read_b64 v[126:127], v235 offset:49920
	v_mfma_f32_16x16x32_bf16 v[24:27], v[48:51], v[28:31], 0
	v_mfma_f32_16x16x32_bf16 v[24:27], v[52:55], v[32:35], v[24:27]
	v_mfma_f32_16x16x32_bf16 v[24:27], v[56:59], v[40:43], v[24:27]
	v_mfma_f32_16x16x32_bf16 v[24:27], v[60:63], v[44:47], v[24:27]
	ds_read_b64_tr_b16 v[56:57], v233 offset:32768
	global_load_dwordx4 v[132:135], v204, s[40:41]
	ds_read_b64_tr_b16 v[58:59], v233 offset:34048
	s_waitcnt lgkmcnt(13)
	v_mfma_f32_16x16x32_bf16 v[48:51], v[64:67], v[28:31], 0
	s_waitcnt lgkmcnt(9)
	v_mfma_f32_16x16x32_bf16 v[52:55], v[80:83], v[28:31], 0
	v_mfma_f32_16x16x32_bf16 v[48:51], v[68:71], v[32:35], v[48:51]
	s_waitcnt lgkmcnt(8)
	v_mfma_f32_16x16x32_bf16 v[52:55], v[84:87], v[32:35], v[52:55]
	global_load_dwordx4 v[136:139], v205, s[40:41]
	v_mfma_f32_16x16x32_bf16 v[48:51], v[72:75], v[40:43], v[48:51]
	s_waitcnt lgkmcnt(7)
	v_mfma_f32_16x16x32_bf16 v[52:55], v[88:91], v[40:43], v[52:55]
	v_mfma_f32_16x16x32_bf16 v[48:51], v[76:79], v[44:47], v[48:51]
	s_waitcnt lgkmcnt(6)
	v_mfma_f32_16x16x32_bf16 v[52:55], v[92:95], v[44:47], v[52:55]
	ds_read_b128 v[64:67], v219 offset:24576
	ds_read_b128 v[68:71], v220 offset:24576
	global_load_dwordx2 v[4:5], v206, s[40:41]
	ds_read_b128 v[72:75], v221 offset:24576
	ds_read_b128 v[76:79], v222 offset:24576
	ds_read_b64_tr_b16 v[60:61], v233 offset:35328
	ds_read_b64_tr_b16 v[62:63], v233 offset:36608
	v_exp_f32_e32 v195, v194
	s_nop 0
	v_mul_f32_e32 v24, v24, v195
	global_load_dwordx2 v[36:37], v207, s[42:43] nt
	v_mul_f32_e32 v25, v25, v195
	v_mul_f32_e32 v26, v26, v195
	v_mul_f32_e32 v27, v27, v195
	s_waitcnt lgkmcnt(8)
	v_lshlrev_b32_e32 v112, 16, v126
	v_and_b32_e32 v113, 0xffff0000, v126
	global_load_dword v6, v208, s[44:45]
	v_lshlrev_b32_e32 v114, 16, v127
	v_and_b32_e32 v115, 0xffff0000, v127
	v_mul_f32_e32 v120, 0xbfb8aa3b, v112
	v_mul_f32_e32 v121, 0xbfb8aa3b, v113
	v_mul_f32_e32 v122, 0xbfb8aa3b, v114
	v_mul_f32_e32 v123, 0xbfb8aa3b, v115
	global_load_dword v116, v208, s[46:47]
	v_exp_f32_e32 v120, v120
	v_exp_f32_e32 v121, v121
	v_exp_f32_e32 v122, v122
	v_exp_f32_e32 v123, v123
	v_add_f32_e32 v120, 1.0, v120
	global_load_dword v117, v209, s[46:47]
	v_add_f32_e32 v121, 1.0, v121
	v_add_f32_e32 v122, 1.0, v122
	v_add_f32_e32 v123, 1.0, v123
	v_rcp_f32_e32 v120, v120
	v_rcp_f32_e32 v121, v121
	v_rcp_f32_e32 v122, v122
	s_add_u32 s66, s54, 3
	s_cmp_lt_u32 s66, s39
	s_cselect_b32 s74, 0xc0000, 0
	s_cselect_b32 s75, 0x280000, 0
	s_cselect_b32 s76, 0x4000, 0
	s_add_u32 s40, s40, s74
	s_addc_u32 s41, s41, 0
	s_add_u32 s42, s42, s75
	s_addc_u32 s43, s43, 0
	s_add_u32 s44, s44, s76
	s_addc_u32 s45, s45, 0
	s_add_u32 s46, s46, s76
	s_addc_u32 s47, s47, 0
	v_rcp_f32_e32 v123, v123
	v_mul_f32_e32 v112, v120, v112
	s_waitcnt vmcnt(10)
; __device__ __forceinline__ void phase_ssd(const Params& P, int seg, unsigned char* smem) {
;     ...
;         auto step = [&](int ci, Pre& R, const int par) {
;             const int row0 = chunk_row0(ci); unsigned char* sb = smem + par * T_BUF; float* acP = acS + par * 64;
;             const bf16* StR = StS + par * (T_STSZ / 2); bf16* StW = StS + (par ^ 1) * (T_STSZ / 2);
;             const float dec = __expf(R.alast);
;             { const float e2 = __expf(R.alast - R.acl);
; #pragma unroll
;               for (int i = 0; i < 2; ++i) { const int q = tid + 512 * i, l = q >> 4, c8 = q & 15; *(v4u*)(sb + T_CS + l * 272 + c8 * 16) = R.Cr[i]; *(v4u*)(sb + T_BS + l * 272 + c8 * 16) = R.Br[i]; }
;               const int l = tid >> 3, p4 = (tid & 7) * 4;
;               const float x0 = bflo(R.Xr.x) * R.dtl, x1 = bfhi(R.Xr.x) * R.dtl, x2 = bflo(R.Xr.y) * R.dtl, x3 = bfhi(R.Xr.y) * R.dtl;
;               v2u d; d.x = cvt_pk_bf16(x0, x1); d.y = cvt_pk_bf16(x2, x3); *(v2u*)(sb + T_XD + l * 80 + p4 * 2) = d;
;               v2u e; e.x = cvt_pk_bf16(x0 * e2, x1 * e2); e.y = cvt_pk_bf16(x2 * e2, x3 * e2); *(v2u*)(sb + T_XE + l * 80 + p4 * 2) = e;
;               *(v2u*)(sb + T_XS + l * 64 + p4 * 2) = R.Xr; *(v2u*)(sb + T_ZS + l * 64 + p4 * 2) = R.Zr;
;               if (w == 0) acP[lane] = R.aclane; }
;             BAR_LDS();
;             if (ci + 2 < nchunks) load_chunk(ci + 2, R);
;             bf16x8 cf[4];
; #pragma unroll
;             for (int k = 0; k < 4; ++k) cf[k] = *(const bf16x8*)(sb + T_CS + (lt * 16 + fr) * 272 + (k * 32 + fq * 8) * 2);
;             f32x4 yo = {0.f, 0.f, 0.f, 0.f};
; #pragma unroll
;             for (int k = 0; k < 4; ++k) { const bf16x8 bb = *(const bf16x8*)((const unsigned char*)StR + (pt * 16 + fr) * 272 + (k * 32 + fq * 8) * 2); yo = mfma16(cf[k], bb, yo); }
; { const f32x4 a4 = *(const f32x4*)(acP + lt * 16 + fq * 4);
; #pragma unroll
;               for (int j = 0; j < 4; ++j) yo[j] *= __expf(a4[j]); }
;             const float acl_fr = acP[lt * 16 + fr]; const int lrow = lt * 16 + fr;
; #pragma unroll
;             for (int t = 0; t < 2; ++t) {
;                 if (2 * t <= lt) {
;                     v2u xb0, xb1;
;                     { const unsigned a0 = lds0 + par * T_BUF + T_XD + (32 * t + 4 * fq + tq) * 80 + (pt * 16 + 4 * tp) * 2, a1 = a0 + 16 * 80; TR_ISSUE(xb0, a0); TR_ISSUE(xb1, a1); }
;                     float m[8];
	v_mul_f32_e32 v113, v121, v113
	v_mul_f32_e32 v114, v122, v114
	ds_write_b128 v213, v[156:159]
	v_mul_f32_e32 v115, v123, v115
	v_lshlrev_b32_e32 v120, 16, v124
	ds_write_b128 v213, v[160:163] offset:8192
	v_and_b32_e32 v121, 0xffff0000, v124
	ds_write_b128 v213, v[148:151] offset:16384
	v_lshlrev_b32_e32 v122, 16, v125
	v_and_b32_e32 v123, 0xffff0000, v125
	ds_write_b128 v213, v[152:155] offset:24576
	v_sub_f32_e32 v184, v194, v96
	v_sub_f32_e32 v185, v194, v97
	v_sub_f32_e32 v200, v169, v168
	v_sub_f32_e32 v186, v194, v98
	v_sub_f32_e32 v187, v194, v99
	v_mul_f32_e32 v200, 0x3fb8aa3b, v200
	v_exp_f32_e32 v184, v184
	v_exp_f32_e32 v185, v185
	v_exp_f32_e32 v200, v200
	v_exp_f32_e32 v186, v186
	v_exp_f32_e32 v187, v187
	v_lshlrev_b32_e32 v196, 16, v164
	v_mul_f32_e32 v184, v48, v184
	v_mul_f32_e32 v185, v49, v185
	v_and_b32_e32 v197, 0xffff0000, v164
	v_mul_f32_e32 v186, v50, v186
	v_lshlrev_b32_e32 v198, 16, v165
	v_mul_f32_e32 v187, v51, v187
	v_sub_f32_e32 v188, v194, v100
	v_and_b32_e32 v199, 0xffff0000, v165
	v_sub_f32_e32 v189, v194, v101
	v_sub_f32_e32 v190, v194, v102
	v_mul_f32_e32 v196, v196, v118
	v_sub_f32_e32 v191, v194, v103
	v_exp_f32_e32 v188, v188
	v_mul_f32_e32 v197, v197, v118
	v_exp_f32_e32 v189, v189
	v_exp_f32_e32 v190, v190
	v_mul_f32_e32 v198, v198, v118
	v_exp_f32_e32 v191, v191
	v_mul_f32_e32 v188, v52, v188
	v_mul_f32_e32 v199, v199, v118
	v_mul_f32_e32 v189, v53, v189
	v_mul_f32_e32 v190, v54, v190
	v_cvt_pk_bf16_f32 v202, v196, v197
	v_mul_f32_e32 v191, v55, v191
	v_cvt_pk_bf16_f32 v128, v184, v185
	v_cvt_pk_bf16_f32 v203, v198, v199
	v_cvt_pk_bf16_f32 v129, v186, v187
	ds_write_b64 v215, v[202:203] offset:32768
	v_cvt_pk_bf16_f32 v130, v188, v189
	v_cvt_pk_bf16_f32 v131, v190, v191
	v_mul_f32_e32 v196, v196, v200
	s_waitcnt lgkmcnt(11)
	v_mfma_f32_16x16x32_bf16 v[24:27], v[56:59], v[128:131], v[24:27]
	ds_read_b128 v[96:99], v232 offset:128
	v_mul_f32_e32 v197, v197, v200
	s_waitcnt lgkmcnt(11)
	v_mfma_f32_16x16x32_bf16 v[48:51], v[64:67], v[28:31], 0
	s_waitcnt lgkmcnt(10)
	v_mfma_f32_16x16x32_bf16 v[48:51], v[68:71], v[32:35], v[48:51]
	v_mul_f32_e32 v198, v198, v200
	s_waitcnt lgkmcnt(9)
	v_mfma_f32_16x16x32_bf16 v[48:51], v[72:75], v[40:43], v[48:51]
	s_waitcnt lgkmcnt(8)
	v_mfma_f32_16x16x32_bf16 v[48:51], v[76:79], v[44:47], v[48:51]
	v_mul_f32_e32 v199, v199, v200
	s_waitcnt lgkmcnt(0)
	v_sub_f32_e32 v184, v194, v96
	v_sub_f32_e32 v185, v194, v97
	v_cvt_pk_bf16_f32 v192, v196, v197
	v_sub_f32_e32 v186, v194, v98
	v_sub_f32_e32 v187, v194, v99
	v_cvt_pk_bf16_f32 v193, v198, v199
	v_exp_f32_e32 v184, v184
	ds_write_b64 v215, v[192:193] offset:37888
	v_exp_f32_e32 v185, v185
	v_exp_f32_e32 v186, v186
	ds_write_b64 v217, v[164:165] offset:43008
	v_exp_f32_e32 v187, v187
	v_mul_f32_e32 v184, v48, v184
	ds_write_b64 v217, v[166:167] offset:47616
	v_mul_f32_e32 v185, v49, v185
	v_mul_f32_e32 v186, v50, v186
	v_mul_f32_e32 v201, 0x3fb8aa3b, v168
	v_mul_f32_e32 v187, v51, v187
	v_cndmask_b32_e64 v184, 0, v184, s[14:15]
	ds_write_b32 v218, v201 offset:256
	v_cndmask_b32_e64 v185, 0, v185, s[16:17]
	v_cndmask_b32_e64 v186, 0, v186, s[22:23]
	v_mul_f32_e32 v174, 0x3fb8aa3b, v169
	v_cndmask_b32_e64 v187, 0, v187, s[34:35]
	v_cvt_pk_bf16_f32 v128, v184, v185
	v_exp_f32_e32 v174, v174
	v_cvt_pk_bf16_f32 v129, v186, v187
	v_mov_b32_e32 v130, 0
	v_mov_b32_e32 v131, 0
	s_nop 1
	v_mfma_f32_16x16x32_bf16 v[24:27], v[60:63], v[128:131], v[24:27]
	s_mul_i32 s65, s56, 0x2000
	s_add_u32 s65, s65, 0x304f1000
	s_add_u32 s48, s0, s65
	s_addc_u32 s49, s1, 0
	s_nop 3
	v_fma_f32 v184, s61, v120, v24
	v_fma_f32 v185, s61, v121, v25
	v_fma_f32 v186, s61, v122, v26
	v_fma_f32 v187, s61, v123, v27
	v_mul_f32_e32 v184, v184, v112
	v_mul_f32_e32 v185, v185, v113
	v_mul_f32_e32 v186, v186, v114
	v_mul_f32_e32 v187, v187, v115
	v_cvt_pk_bf16_f32 v170, v184, v185
	v_cvt_pk_bf16_f32 v171, v186, v187
	global_store_dwordx2 v210, v[170:171], s[48:49]
	s_add_u32 s65, s54, 1
	s_sub_u32 s65, s65, s60
	s_lshl_b32 s65, s65, 6
	s_add_u32 s56, s65, s20
	s_waitcnt lgkmcnt(0)
	s_barrier
	s_add_u32 s54, s54, 1
	s_cmp_ge_u32 s54, s39
	s_cbranch_scc1 .Lssd_done
	ds_read_b128 v[28:31], v223 offset:8192
	ds_read_b128 v[32:35], v224 offset:8192
	ds_read_b128 v[40:43], v225 offset:8192
	ds_read_b128 v[44:47], v226 offset:8192
	ds_read_b128 v[48:51], v227 offset:8192
	ds_read_b128 v[52:55], v228 offset:8192
	ds_read_b128 v[56:59], v229 offset:8192
	ds_read_b128 v[60:63], v230 offset:8192
	ds_read_b32 v194, v231 offset:384
	ds_read_b128 v[64:67], v223 offset:16384
	ds_read_b128 v[68:71], v224 offset:16384
	ds_read_b128 v[72:75], v225 offset:16384
	ds_read_b128 v[76:79], v226 offset:16384
	ds_read_b128 v[80:83], v223 offset:20480
	ds_read_b128 v[84:87], v224 offset:20480
	global_load_dwordx4 v[156:159], v204, s[40:41] offset:2048
	s_waitcnt lgkmcnt(11)
	ds_read_b128 v[88:91], v225 offset:20480
	ds_read_b128 v[92:95], v226 offset:20480
	ds_read_b128 v[96:99], v232 offset:256
	ds_read_b128 v[100:103], v232 offset:320
	s_waitcnt lgkmcnt(11)
	ds_read_b64 v[124:125], v236 offset:45312
	global_load_dwordx4 v[160:163], v205, s[40:41] offset:2048
	ds_read_b64 v[126:127], v236 offset:49920
	v_mfma_f32_16x16x32_bf16 v[24:27], v[48:51], v[28:31], 0
	v_mfma_f32_16x16x32_bf16 v[24:27], v[52:55], v[32:35], v[24:27]
	v_mfma_f32_16x16x32_bf16 v[24:27], v[56:59], v[40:43], v[24:27]
	v_mfma_f32_16x16x32_bf16 v[24:27], v[60:63], v[44:47], v[24:27]
	ds_read_b64_tr_b16 v[56:57], v234 offset:32768
	global_load_dwordx4 v[148:151], v204, s[40:41]
	ds_read_b64_tr_b16 v[58:59], v234 offset:34048
	s_waitcnt lgkmcnt(13)
	v_mfma_f32_16x16x32_bf16 v[48:51], v[64:67], v[28:31], 0
	s_waitcnt lgkmcnt(9)
; __device__ __forceinline__ void phase_ssd(const Params& P, int seg, unsigned char* smem) {
;     ...
;         auto step = [&](int ci, Pre& R, const int par) {
;             const int row0 = chunk_row0(ci); unsigned char* sb = smem + par * T_BUF; float* acP = acS + par * 64;
;             const bf16* StR = StS + par * (T_STSZ / 2); bf16* StW = StS + (par ^ 1) * (T_STSZ / 2);
;             const float dec = __expf(R.alast);
;             { const float e2 = __expf(R.alast - R.acl);
; #pragma unroll
;               for (int i = 0; i < 2; ++i) { const int q = tid + 512 * i, l = q >> 4, c8 = q & 15; *(v4u*)(sb + T_CS + l * 272 + c8 * 16) = R.Cr[i]; *(v4u*)(sb + T_BS + l * 272 + c8 * 16) = R.Br[i]; }
;               const int l = tid >> 3, p4 = (tid & 7) * 4;
;               const float x0 = bflo(R.Xr.x) * R.dtl, x1 = bfhi(R.Xr.x) * R.dtl, x2 = bflo(R.Xr.y) * R.dtl, x3 = bfhi(R.Xr.y) * R.dtl;
;               v2u d; d.x = cvt_pk_bf16(x0, x1); d.y = cvt_pk_bf16(x2, x3); *(v2u*)(sb + T_XD + l * 80 + p4 * 2) = d;
;               v2u e; e.x = cvt_pk_bf16(x0 * e2, x1 * e2); e.y = cvt_pk_bf16(x2 * e2, x3 * e2); *(v2u*)(sb + T_XE + l * 80 + p4 * 2) = e;
;               *(v2u*)(sb + T_XS + l * 64 + p4 * 2) = R.Xr; *(v2u*)(sb + T_ZS + l * 64 + p4 * 2) = R.Zr;
;               if (w == 0) acP[lane] = R.aclane; }
;             BAR_LDS();
;             if (ci + 2 < nchunks) load_chunk(ci + 2, R);
;             bf16x8 cf[4];
; #pragma unroll
;             for (int k = 0; k < 4; ++k) cf[k] = *(const bf16x8*)(sb + T_CS + (lt * 16 + fr) * 272 + (k * 32 + fq * 8) * 2);
;             f32x4 yo = {0.f, 0.f, 0.f, 0.f};
; #pragma unroll
;             for (int k = 0; k < 4; ++k) { const bf16x8 bb = *(const bf16x8*)((const unsigned char*)StR + (pt * 16 + fr) * 272 + (k * 32 + fq * 8) * 2); yo = mfma16(cf[k], bb, yo); }
; { const f32x4 a4 = *(const f32x4*)(acP + lt * 16 + fq * 4);
; #pragma unroll
;               for (int j = 0; j < 4; ++j) yo[j] *= __expf(a4[j]); }
;             const float acl_fr = acP[lt * 16 + fr]; const int lrow = lt * 16 + fr;
; #pragma unroll
;             for (int t = 0; t < 2; ++t) {
;                 if (2 * t <= lt) {
;                     v2u xb0, xb1;
;                     { const unsigned a0 = lds0 + par * T_BUF + T_XD + (32 * t + 4 * fq + tq) * 80 + (pt * 16 + 4 * tp) * 2, a1 = a0 + 16 * 80; TR_ISSUE(xb0, a0); TR_ISSUE(xb1, a1); }
;                     float m[8];
	v_mfma_f32_16x16x32_bf16 v[52:55], v[80:83], v[28:31], 0
	v_mfma_f32_16x16x32_bf16 v[48:51], v[68:71], v[32:35], v[48:51]
	s_waitcnt lgkmcnt(8)
	v_mfma_f32_16x16x32_bf16 v[52:55], v[84:87], v[32:35], v[52:55]
	global_load_dwordx4 v[152:155], v205, s[40:41]
	v_mfma_f32_16x16x32_bf16 v[48:51], v[72:75], v[40:43], v[48:51]
	s_waitcnt lgkmcnt(7)
	v_mfma_f32_16x16x32_bf16 v[52:55], v[88:91], v[40:43], v[52:55]
	v_mfma_f32_16x16x32_bf16 v[48:51], v[76:79], v[44:47], v[48:51]
	s_waitcnt lgkmcnt(6)
	v_mfma_f32_16x16x32_bf16 v[52:55], v[92:95], v[44:47], v[52:55]
	ds_read_b128 v[64:67], v223 offset:24576
	ds_read_b128 v[68:71], v224 offset:24576
	global_load_dwordx2 v[164:165], v206, s[40:41]
	ds_read_b128 v[72:75], v225 offset:24576
	ds_read_b128 v[76:79], v226 offset:24576
	ds_read_b64_tr_b16 v[60:61], v234 offset:35328
	ds_read_b64_tr_b16 v[62:63], v234 offset:36608
	v_exp_f32_e32 v195, v194
	s_nop 0
	v_mul_f32_e32 v24, v24, v195
	global_load_dwordx2 v[166:167], v207, s[42:43] nt
	v_mul_f32_e32 v25, v25, v195
	v_mul_f32_e32 v26, v26, v195
	v_mul_f32_e32 v27, v27, v195
	s_waitcnt lgkmcnt(8)
	v_lshlrev_b32_e32 v112, 16, v126
	v_and_b32_e32 v113, 0xffff0000, v126
	global_load_dword v118, v208, s[44:45]
	v_lshlrev_b32_e32 v114, 16, v127
	v_and_b32_e32 v115, 0xffff0000, v127
	v_mul_f32_e32 v120, 0xbfb8aa3b, v112
	v_mul_f32_e32 v121, 0xbfb8aa3b, v113
	v_mul_f32_e32 v122, 0xbfb8aa3b, v114
	v_mul_f32_e32 v123, 0xbfb8aa3b, v115
	global_load_dword v168, v208, s[46:47]
	v_exp_f32_e32 v120, v120
	v_exp_f32_e32 v121, v121
	v_exp_f32_e32 v122, v122
	v_exp_f32_e32 v123, v123
	v_add_f32_e32 v120, 1.0, v120
	global_load_dword v169, v209, s[46:47]
	v_add_f32_e32 v121, 1.0, v121
	v_add_f32_e32 v122, 1.0, v122
	v_add_f32_e32 v123, 1.0, v123
	v_rcp_f32_e32 v120, v120
	v_rcp_f32_e32 v121, v121
	v_rcp_f32_e32 v122, v122
	s_add_u32 s66, s54, 3
	s_cmp_lt_u32 s66, s39
	s_cselect_b32 s74, 0xc0000, 0
	s_cselect_b32 s75, 0x280000, 0
	s_cselect_b32 s76, 0x4000, 0
	s_add_u32 s40, s40, s74
	s_addc_u32 s41, s41, 0
	s_add_u32 s42, s42, s75
	s_addc_u32 s43, s43, 0
	s_add_u32 s44, s44, s76
	s_addc_u32 s45, s45, 0
	s_add_u32 s46, s46, s76
	s_addc_u32 s47, s47, 0
	v_rcp_f32_e32 v123, v123
	v_mul_f32_e32 v112, v120, v112
	s_waitcnt vmcnt(10)
	v_mul_f32_e32 v113, v121, v113
	v_mul_f32_e32 v114, v122, v114
	ds_write_b128 v212, v[140:143]
	v_mul_f32_e32 v115, v123, v115
	v_lshlrev_b32_e32 v120, 16, v124
	ds_write_b128 v212, v[144:147] offset:8192
	v_and_b32_e32 v121, 0xffff0000, v124
	ds_write_b128 v212, v[132:135] offset:16384
	v_lshlrev_b32_e32 v122, 16, v125
	v_and_b32_e32 v123, 0xffff0000, v125
	ds_write_b128 v212, v[136:139] offset:24576
	v_sub_f32_e32 v184, v194, v96
	v_sub_f32_e32 v185, v194, v97
	v_sub_f32_e32 v200, v117, v116
	v_sub_f32_e32 v186, v194, v98
	v_sub_f32_e32 v187, v194, v99
	v_mul_f32_e32 v200, 0x3fb8aa3b, v200
	v_exp_f32_e32 v184, v184
	v_exp_f32_e32 v185, v185
	v_exp_f32_e32 v200, v200
	v_exp_f32_e32 v186, v186
	v_exp_f32_e32 v187, v187
	v_lshlrev_b32_e32 v196, 16, v4
	v_mul_f32_e32 v184, v48, v184
	v_mul_f32_e32 v185, v49, v185
	v_and_b32_e32 v197, 0xffff0000, v4
	v_mul_f32_e32 v186, v50, v186
	v_lshlrev_b32_e32 v198, 16, v5
	v_mul_f32_e32 v187, v51, v187
	v_sub_f32_e32 v188, v194, v100
	v_and_b32_e32 v199, 0xffff0000, v5
	v_sub_f32_e32 v189, v194, v101
	v_sub_f32_e32 v190, v194, v102
	v_mul_f32_e32 v196, v196, v6
	v_sub_f32_e32 v191, v194, v103
	v_exp_f32_e32 v188, v188
	v_mul_f32_e32 v197, v197, v6
	v_exp_f32_e32 v189, v189
	v_exp_f32_e32 v190, v190
	v_mul_f32_e32 v198, v198, v6
	v_exp_f32_e32 v191, v191
	v_mul_f32_e32 v188, v52, v188
	v_mul_f32_e32 v199, v199, v6
	v_mul_f32_e32 v189, v53, v189
	v_mul_f32_e32 v190, v54, v190
	v_cvt_pk_bf16_f32 v202, v196, v197
	v_mul_f32_e32 v191, v55, v191
	v_cvt_pk_bf16_f32 v128, v184, v185
	v_cvt_pk_bf16_f32 v203, v198, v199
	v_cvt_pk_bf16_f32 v129, v186, v187
	ds_write_b64 v214, v[202:203] offset:32768
	v_cvt_pk_bf16_f32 v130, v188, v189
	v_cvt_pk_bf16_f32 v131, v190, v191
	v_mul_f32_e32 v196, v196, v200
	s_waitcnt lgkmcnt(11)
	v_mfma_f32_16x16x32_bf16 v[24:27], v[56:59], v[128:131], v[24:27]
	ds_read_b128 v[96:99], v232 offset:384
	v_mul_f32_e32 v197, v197, v200
	s_waitcnt lgkmcnt(11)
	v_mfma_f32_16x16x32_bf16 v[48:51], v[64:67], v[28:31], 0
	s_waitcnt lgkmcnt(10)
	v_mfma_f32_16x16x32_bf16 v[48:51], v[68:71], v[32:35], v[48:51]
	v_mul_f32_e32 v198, v198, v200
	s_waitcnt lgkmcnt(9)
	v_mfma_f32_16x16x32_bf16 v[48:51], v[72:75], v[40:43], v[48:51]
	s_waitcnt lgkmcnt(8)
	v_mfma_f32_16x16x32_bf16 v[48:51], v[76:79], v[44:47], v[48:51]
	v_mul_f32_e32 v199, v199, v200
	s_waitcnt lgkmcnt(0)
	v_sub_f32_e32 v184, v194, v96
	v_sub_f32_e32 v185, v194, v97
	v_cvt_pk_bf16_f32 v192, v196, v197
	v_sub_f32_e32 v186, v194, v98
	v_sub_f32_e32 v187, v194, v99
	v_cvt_pk_bf16_f32 v193, v198, v199
	v_exp_f32_e32 v184, v184
	ds_write_b64 v214, v[192:193] offset:37888
	v_exp_f32_e32 v185, v185
	v_exp_f32_e32 v186, v186
	ds_write_b64 v216, v[4:5] offset:43008
	v_exp_f32_e32 v187, v187
	v_mul_f32_e32 v184, v48, v184
	ds_write_b64 v216, v[36:37] offset:47616
	v_mul_f32_e32 v185, v49, v185
	v_mul_f32_e32 v186, v50, v186
	v_mul_f32_e32 v201, 0x3fb8aa3b, v116
	v_mul_f32_e32 v187, v51, v187
	v_cndmask_b32_e64 v184, 0, v184, s[14:15]
	ds_write_b32 v218, v201
	v_cndmask_b32_e64 v185, 0, v185, s[16:17]
	v_cndmask_b32_e64 v186, 0, v186, s[22:23]
	v_mul_f32_e32 v174, 0x3fb8aa3b, v117
	v_cndmask_b32_e64 v187, 0, v187, s[34:35]
	v_cvt_pk_bf16_f32 v128, v184, v185
	v_exp_f32_e32 v174, v174
	v_cvt_pk_bf16_f32 v129, v186, v187
	v_mov_b32_e32 v130, 0
	v_mov_b32_e32 v131, 0
	s_nop 1
	v_mfma_f32_16x16x32_bf16 v[24:27], v[60:63], v[128:131], v[24:27]
	s_mul_i32 s65, s56, 0x2000
	s_add_u32 s65, s65, 0x304f1000
	s_add_u32 s48, s0, s65
	s_addc_u32 s49, s1, 0
	s_nop 3
	v_fma_f32 v184, s61, v120, v24
	v_fma_f32 v185, s61, v121, v25
	v_fma_f32 v186, s61, v122, v26
	v_fma_f32 v187, s61, v123, v27
	v_mul_f32_e32 v184, v184, v112
	v_mul_f32_e32 v185, v185, v113
	v_mul_f32_e32 v186, v186, v114
	v_mul_f32_e32 v187, v187, v115
	v_cvt_pk_bf16_f32 v170, v184, v185
	v_cvt_pk_bf16_f32 v171, v186, v187
	global_store_dwordx2 v210, v[170:171], s[48:49]
	s_add_u32 s65, s54, 1
	s_sub_u32 s65, s65, s60
	s_lshl_b32 s65, s65, 6
	s_add_u32 s56, s65, s20
	s_waitcnt lgkmcnt(0)
	s_barrier
	s_add_u32 s54, s54, 1
	s_cmp_lt_u32 s54, s39
	s_cbranch_scc1 .Lssd_loop2
	s_branch .Lssd_done
; __device__ __forceinline__ void phase_ssd(const Params& P, int seg, unsigned char* smem) {
;     ...
;         auto step = [&](int ci, Pre& R, const int par) {
;             const int row0 = chunk_row0(ci); unsigned char* sb = smem + par * T_BUF; float* acP = acS + par * 64;
;             const bf16* StR = StS + par * (T_STSZ / 2); bf16* StW = StS + (par ^ 1) * (T_STSZ / 2);
;             const float dec = __expf(R.alast);
;             { const float e2 = __expf(R.alast - R.acl);
; #pragma unroll
;               for (int i = 0; i < 2; ++i) { const int q = tid + 512 * i, l = q >> 4, c8 = q & 15; *(v4u*)(sb + T_CS + l * 272 + c8 * 16) = R.Cr[i]; *(v4u*)(sb + T_BS + l * 272 + c8 * 16) = R.Br[i]; }
;               const int l = tid >> 3, p4 = (tid & 7) * 4;
;               const float x0 = bflo(R.Xr.x) * R.dtl, x1 = bfhi(R.Xr.x) * R.dtl, x2 = bflo(R.Xr.y) * R.dtl, x3 = bfhi(R.Xr.y) * R.dtl;
;               v2u d; d.x = cvt_pk_bf16(x0, x1); d.y = cvt_pk_bf16(x2, x3); *(v2u*)(sb + T_XD + l * 80 + p4 * 2) = d;
;               v2u e; e.x = cvt_pk_bf16(x0 * e2, x1 * e2); e.y = cvt_pk_bf16(x2 * e2, x3 * e2); *(v2u*)(sb + T_XE + l * 80 + p4 * 2) = e;
;               *(v2u*)(sb + T_XS + l * 64 + p4 * 2) = R.Xr; *(v2u*)(sb + T_ZS + l * 64 + p4 * 2) = R.Zr;
;               if (w == 0) acP[lane] = R.aclane; }
;             BAR_LDS();
;             if (ci + 2 < nchunks) load_chunk(ci + 2, R);
;             bf16x8 cf[4];
; #pragma unroll
;             for (int k = 0; k < 4; ++k) cf[k] = *(const bf16x8*)(sb + T_CS + (lt * 16 + fr) * 272 + (k * 32 + fq * 8) * 2);
;             f32x4 yo = {0.f, 0.f, 0.f, 0.f};
; #pragma unroll
;             for (int k = 0; k < 4; ++k) { const bf16x8 bb = *(const bf16x8*)((const unsigned char*)StR + (pt * 16 + fr) * 272 + (k * 32 + fq * 8) * 2); yo = mfma16(cf[k], bb, yo); }
; { const f32x4 a4 = *(const f32x4*)(acP + lt * 16 + fq * 4);
; #pragma unroll
;               for (int j = 0; j < 4; ++j) yo[j] *= __expf(a4[j]); }
;             const float acl_fr = acP[lt * 16 + fr]; const int lrow = lt * 16 + fr;
; #pragma unroll
;             for (int t = 0; t < 2; ++t) {
;                 if (2 * t <= lt) {
;                     v2u xb0, xb1;
;                     { const unsigned a0 = lds0 + par * T_BUF + T_XD + (32 * t + 4 * fq + tq) * 80 + (pt * 16 + 4 * tp) * 2, a1 = a0 + 16 * 80; TR_ISSUE(xb0, a0); TR_ISSUE(xb1, a1); }
;                     float m[8];
.Lssd_loop3:
	ds_read_b128 v[28:31], v219 offset:12288
	ds_read_b128 v[32:35], v220 offset:12288
	ds_read_b128 v[40:43], v221 offset:12288
	ds_read_b128 v[44:47], v222 offset:12288
	ds_read_b128 v[48:51], v227
	ds_read_b128 v[52:55], v228
	ds_read_b128 v[56:59], v229
	ds_read_b128 v[60:63], v230
	ds_read_b32 v194, v231 offset:192
	ds_read_b128 v[64:67], v219 offset:16384
	ds_read_b128 v[68:71], v220 offset:16384
	ds_read_b128 v[72:75], v221 offset:16384
	ds_read_b128 v[76:79], v222 offset:16384
	ds_read_b128 v[80:83], v219 offset:20480
	ds_read_b128 v[84:87], v220 offset:20480
	global_load_dwordx4 v[140:143], v204, s[40:41] offset:2048
	s_waitcnt lgkmcnt(11)
	ds_read_b128 v[88:91], v221 offset:20480
	ds_read_b128 v[92:95], v222 offset:20480
	ds_read_b128 v[96:99], v232
	ds_read_b128 v[100:103], v232 offset:64
	s_waitcnt lgkmcnt(11)
	ds_read_b64 v[124:125], v235 offset:46464
	ds_read_b64 v[126:127], v235 offset:51072
	global_load_dwordx4 v[144:147], v205, s[40:41] offset:2048
	v_mfma_f32_16x16x32_bf16 v[24:27], v[48:51], v[28:31], 0
	v_mfma_f32_16x16x32_bf16 v[24:27], v[52:55], v[32:35], v[24:27]
	v_mfma_f32_16x16x32_bf16 v[24:27], v[56:59], v[40:43], v[24:27]
	v_mfma_f32_16x16x32_bf16 v[24:27], v[60:63], v[44:47], v[24:27]
	ds_read_b64_tr_b16 v[56:57], v233 offset:32768
	ds_read_b64_tr_b16 v[58:59], v233 offset:34048
	s_waitcnt lgkmcnt(13)
	v_mfma_f32_16x16x32_bf16 v[48:51], v[64:67], v[28:31], 0
	global_load_dwordx4 v[132:135], v204, s[40:41]
	s_waitcnt lgkmcnt(9)
	v_mfma_f32_16x16x32_bf16 v[52:55], v[80:83], v[28:31], 0
	v_mfma_f32_16x16x32_bf16 v[48:51], v[68:71], v[32:35], v[48:51]
	s_waitcnt lgkmcnt(8)
	v_mfma_f32_16x16x32_bf16 v[52:55], v[84:87], v[32:35], v[52:55]
	v_mfma_f32_16x16x32_bf16 v[48:51], v[72:75], v[40:43], v[48:51]
	s_waitcnt lgkmcnt(7)
	v_mfma_f32_16x16x32_bf16 v[52:55], v[88:91], v[40:43], v[52:55]
	v_mfma_f32_16x16x32_bf16 v[48:51], v[76:79], v[44:47], v[48:51]
	global_load_dwordx4 v[136:139], v205, s[40:41]
	s_waitcnt lgkmcnt(6)
	v_mfma_f32_16x16x32_bf16 v[52:55], v[92:95], v[44:47], v[52:55]
	ds_read_b128 v[64:67], v219 offset:24576
	ds_read_b128 v[68:71], v220 offset:24576
	ds_read_b128 v[72:75], v221 offset:24576
	ds_read_b128 v[76:79], v222 offset:24576
	ds_read_b128 v[80:83], v219 offset:28672
	ds_read_b128 v[84:87], v220 offset:28672
	global_load_dwordx2 v[4:5], v206, s[40:41]
	ds_read_b128 v[88:91], v221 offset:28672
	ds_read_b128 v[92:95], v222 offset:28672
	ds_read_b64_tr_b16 v[60:61], v233 offset:35328
	s_waitcnt lgkmcnt(11)
	ds_read_b64_tr_b16 v[62:63], v233 offset:36608
	v_exp_f32_e32 v195, v194
	s_nop 0
	v_mul_f32_e32 v24, v24, v195
	v_mul_f32_e32 v25, v25, v195
	global_load_dwordx2 v[36:37], v207, s[42:43] nt
	v_mul_f32_e32 v26, v26, v195
	v_mul_f32_e32 v27, v27, v195
	v_lshlrev_b32_e32 v112, 16, v126
	v_and_b32_e32 v113, 0xffff0000, v126
	v_lshlrev_b32_e32 v114, 16, v127
	v_and_b32_e32 v115, 0xffff0000, v127
	global_load_dword v6, v208, s[44:45]
	v_mul_f32_e32 v120, 0xbfb8aa3b, v112
	v_mul_f32_e32 v121, 0xbfb8aa3b, v113
	v_mul_f32_e32 v122, 0xbfb8aa3b, v114
	v_mul_f32_e32 v123, 0xbfb8aa3b, v115
	v_exp_f32_e32 v120, v120
	v_exp_f32_e32 v121, v121
	v_exp_f32_e32 v122, v122
	global_load_dword v116, v208, s[46:47]
	v_exp_f32_e32 v123, v123
	v_add_f32_e32 v120, 1.0, v120
	v_add_f32_e32 v121, 1.0, v121
	v_add_f32_e32 v122, 1.0, v122
	v_add_f32_e32 v123, 1.0, v123
	v_rcp_f32_e32 v120, v120
	v_rcp_f32_e32 v121, v121
	global_load_dword v117, v209, s[46:47]
	v_rcp_f32_e32 v122, v122
	v_rcp_f32_e32 v123, v123
	v_mul_f32_e32 v112, v120, v112
	v_mul_f32_e32 v113, v121, v113
	v_mul_f32_e32 v114, v122, v114
	v_mul_f32_e32 v115, v123, v115
	s_add_u32 s66, s54, 3
	s_cmp_lt_u32 s66, s39
	s_cselect_b32 s74, 0xc0000, 0
	s_cselect_b32 s75, 0x280000, 0
	s_cselect_b32 s76, 0x4000, 0
	s_add_u32 s40, s40, s74
	s_addc_u32 s41, s41, 0
	s_add_u32 s42, s42, s75
	s_addc_u32 s43, s43, 0
	s_add_u32 s44, s44, s76
	s_addc_u32 s45, s45, 0
	s_add_u32 s46, s46, s76
	s_addc_u32 s47, s47, 0
	v_lshlrev_b32_e32 v120, 16, v124
	v_and_b32_e32 v121, 0xffff0000, v124
	v_lshlrev_b32_e32 v122, 16, v125
	s_waitcnt vmcnt(10)
	v_and_b32_e32 v123, 0xffff0000, v125
	v_sub_f32_e32 v184, v194, v96
	ds_write_b128 v213, v[156:159]
	v_sub_f32_e32 v185, v194, v97
	v_sub_f32_e32 v186, v194, v98
	ds_write_b128 v213, v[160:163] offset:8192
	v_sub_f32_e32 v187, v194, v99
	v_exp_f32_e32 v184, v184
	ds_write_b128 v213, v[148:151] offset:16384
	v_exp_f32_e32 v185, v185
	v_exp_f32_e32 v186, v186
	s_waitcnt lgkmcnt(11)
	ds_write_b128 v213, v[152:155] offset:24576
	v_exp_f32_e32 v187, v187
	v_mul_f32_e32 v184, v48, v184
	v_mul_f32_e32 v185, v49, v185
	v_sub_f32_e32 v200, v169, v168
	v_mul_f32_e32 v186, v50, v186
	v_mul_f32_e32 v187, v51, v187
	v_mul_f32_e32 v200, 0x3fb8aa3b, v200
	v_sub_f32_e32 v188, v194, v100
	v_sub_f32_e32 v189, v194, v101
	v_exp_f32_e32 v200, v200
	v_sub_f32_e32 v190, v194, v102
	v_sub_f32_e32 v191, v194, v103
	v_lshlrev_b32_e32 v196, 16, v164
	v_exp_f32_e32 v188, v188
	v_exp_f32_e32 v189, v189
	v_exp_f32_e32 v190, v190
	v_and_b32_e32 v197, 0xffff0000, v164
	v_exp_f32_e32 v191, v191
	v_mul_f32_e32 v188, v52, v188
	v_lshlrev_b32_e32 v198, 16, v165
	v_mul_f32_e32 v189, v53, v189
	v_mul_f32_e32 v190, v54, v190
	v_and_b32_e32 v199, 0xffff0000, v165
	v_mul_f32_e32 v191, v55, v191
	v_cvt_pk_bf16_f32 v128, v184, v185
	v_mul_f32_e32 v196, v196, v118
	v_cvt_pk_bf16_f32 v129, v186, v187
	v_cvt_pk_bf16_f32 v130, v188, v189
	v_mul_f32_e32 v197, v197, v118
	v_cvt_pk_bf16_f32 v131, v190, v191
	s_nop 1
	v_mfma_f32_16x16x32_bf16 v[24:27], v[56:59], v[128:131], v[24:27]
	ds_read_b128 v[96:99], v232 offset:128
	v_mul_f32_e32 v198, v198, v118
	ds_read_b128 v[100:103], v232 offset:192
	v_mfma_f32_16x16x32_bf16 v[48:51], v[64:67], v[28:31], 0
	v_mul_f32_e32 v199, v199, v118
	s_waitcnt lgkmcnt(11)
; __device__ __forceinline__ void phase_ssd(const Params& P, int seg, unsigned char* smem) {
;     ...
;         auto step = [&](int ci, Pre& R, const int par) {
;             const int row0 = chunk_row0(ci); unsigned char* sb = smem + par * T_BUF; float* acP = acS + par * 64;
;             const bf16* StR = StS + par * (T_STSZ / 2); bf16* StW = StS + (par ^ 1) * (T_STSZ / 2);
;             const float dec = __expf(R.alast);
;             { const float e2 = __expf(R.alast - R.acl);
; #pragma unroll
;               for (int i = 0; i < 2; ++i) { const int q = tid + 512 * i, l = q >> 4, c8 = q & 15; *(v4u*)(sb + T_CS + l * 272 + c8 * 16) = R.Cr[i]; *(v4u*)(sb + T_BS + l * 272 + c8 * 16) = R.Br[i]; }
;               const int l = tid >> 3, p4 = (tid & 7) * 4;
;               const float x0 = bflo(R.Xr.x) * R.dtl, x1 = bfhi(R.Xr.x) * R.dtl, x2 = bflo(R.Xr.y) * R.dtl, x3 = bfhi(R.Xr.y) * R.dtl;
;               v2u d; d.x = cvt_pk_bf16(x0, x1); d.y = cvt_pk_bf16(x2, x3); *(v2u*)(sb + T_XD + l * 80 + p4 * 2) = d;
;               v2u e; e.x = cvt_pk_bf16(x0 * e2, x1 * e2); e.y = cvt_pk_bf16(x2 * e2, x3 * e2); *(v2u*)(sb + T_XE + l * 80 + p4 * 2) = e;
;               *(v2u*)(sb + T_XS + l * 64 + p4 * 2) = R.Xr; *(v2u*)(sb + T_ZS + l * 64 + p4 * 2) = R.Zr;
;               if (w == 0) acP[lane] = R.aclane; }
;             BAR_LDS();
;             if (ci + 2 < nchunks) load_chunk(ci + 2, R);
;             bf16x8 cf[4];
; #pragma unroll
;             for (int k = 0; k < 4; ++k) cf[k] = *(const bf16x8*)(sb + T_CS + (lt * 16 + fr) * 272 + (k * 32 + fq * 8) * 2);
;             f32x4 yo = {0.f, 0.f, 0.f, 0.f};
; #pragma unroll
;             for (int k = 0; k < 4; ++k) { const bf16x8 bb = *(const bf16x8*)((const unsigned char*)StR + (pt * 16 + fr) * 272 + (k * 32 + fq * 8) * 2); yo = mfma16(cf[k], bb, yo); }
; { const f32x4 a4 = *(const f32x4*)(acP + lt * 16 + fq * 4);
; #pragma unroll
;               for (int j = 0; j < 4; ++j) yo[j] *= __expf(a4[j]); }
;             const float acl_fr = acP[lt * 16 + fr]; const int lrow = lt * 16 + fr;
; #pragma unroll
;             for (int t = 0; t < 2; ++t) {
;                 if (2 * t <= lt) {
;                     v2u xb0, xb1;
;                     { const unsigned a0 = lds0 + par * T_BUF + T_XD + (32 * t + 4 * fq + tq) * 80 + (pt * 16 + 4 * tp) * 2, a1 = a0 + 16 * 80; TR_ISSUE(xb0, a0); TR_ISSUE(xb1, a1); }
;                     float m[8];
	v_mfma_f32_16x16x32_bf16 v[52:55], v[80:83], v[28:31], 0
	v_mfma_f32_16x16x32_bf16 v[48:51], v[68:71], v[32:35], v[48:51]
	v_cvt_pk_bf16_f32 v202, v196, v197
	s_waitcnt lgkmcnt(10)
	v_mfma_f32_16x16x32_bf16 v[52:55], v[84:87], v[32:35], v[52:55]
	v_mfma_f32_16x16x32_bf16 v[48:51], v[72:75], v[40:43], v[48:51]
	v_cvt_pk_bf16_f32 v203, v198, v199
	s_waitcnt lgkmcnt(9)
	v_mfma_f32_16x16x32_bf16 v[52:55], v[88:91], v[40:43], v[52:55]
	v_mfma_f32_16x16x32_bf16 v[48:51], v[76:79], v[44:47], v[48:51]
	ds_write_b64 v215, v[202:203] offset:32768
	s_waitcnt lgkmcnt(9)
	v_mfma_f32_16x16x32_bf16 v[52:55], v[92:95], v[44:47], v[52:55]
	s_waitcnt lgkmcnt(2)
	v_sub_f32_e32 v184, v194, v96
	v_sub_f32_e32 v185, v194, v97
	v_mul_f32_e32 v196, v196, v200
	v_sub_f32_e32 v186, v194, v98
	v_sub_f32_e32 v187, v194, v99
	v_mul_f32_e32 v197, v197, v200
	v_exp_f32_e32 v184, v184
	v_exp_f32_e32 v185, v185
	v_mul_f32_e32 v198, v198, v200
	v_exp_f32_e32 v186, v186
	v_exp_f32_e32 v187, v187
	v_mul_f32_e32 v199, v199, v200
	v_mul_f32_e32 v184, v48, v184
	v_mul_f32_e32 v185, v49, v185
	v_mul_f32_e32 v186, v50, v186
	v_cvt_pk_bf16_f32 v192, v196, v197
	v_mul_f32_e32 v187, v51, v187
	s_waitcnt lgkmcnt(1)
	v_sub_f32_e32 v188, v194, v100
	v_cvt_pk_bf16_f32 v193, v198, v199
	v_sub_f32_e32 v189, v194, v101
	v_sub_f32_e32 v190, v194, v102
	ds_write_b64 v215, v[192:193] offset:37888
	v_sub_f32_e32 v191, v194, v103
	v_exp_f32_e32 v188, v188
	ds_write_b64 v217, v[164:165] offset:43008
	v_exp_f32_e32 v189, v189
	v_exp_f32_e32 v190, v190
	ds_write_b64 v217, v[166:167] offset:47616
	v_exp_f32_e32 v191, v191
	v_mul_f32_e32 v188, v52, v188
	v_mul_f32_e32 v189, v53, v189
	v_mul_f32_e32 v201, 0x3fb8aa3b, v168
	v_mul_f32_e32 v190, v54, v190
	v_mul_f32_e32 v191, v55, v191
	ds_write_b32 v218, v201 offset:256
	v_cndmask_b32_e64 v188, 0, v188, s[14:15]
	v_cndmask_b32_e64 v189, 0, v189, s[16:17]
	v_mul_f32_e32 v174, 0x3fb8aa3b, v169
	v_cndmask_b32_e64 v190, 0, v190, s[22:23]
	v_cndmask_b32_e64 v191, 0, v191, s[34:35]
	v_exp_f32_e32 v174, v174
	v_cvt_pk_bf16_f32 v128, v184, v185
	v_cvt_pk_bf16_f32 v129, v186, v187
	v_cvt_pk_bf16_f32 v130, v188, v189
	v_cvt_pk_bf16_f32 v131, v190, v191
	s_nop 1
	v_mfma_f32_16x16x32_bf16 v[24:27], v[60:63], v[128:131], v[24:27]
	s_mul_i32 s65, s56, 0x2000
	s_add_u32 s65, s65, 0x304f1000
	s_add_u32 s48, s0, s65
	s_addc_u32 s49, s1, 0
	s_nop 3
	v_fma_f32 v184, s61, v120, v24
	v_fma_f32 v185, s61, v121, v25
	v_fma_f32 v186, s61, v122, v26
	v_fma_f32 v187, s61, v123, v27
	v_mul_f32_e32 v184, v184, v112
	v_mul_f32_e32 v185, v185, v113
	v_mul_f32_e32 v186, v186, v114
	v_mul_f32_e32 v187, v187, v115
	v_cvt_pk_bf16_f32 v170, v184, v185
	v_cvt_pk_bf16_f32 v171, v186, v187
	global_store_dwordx2 v210, v[170:171], s[48:49]
	s_add_u32 s65, s54, 1
	s_sub_u32 s65, s65, s60
	s_lshl_b32 s65, s65, 6
	s_add_u32 s56, s65, s20
	s_waitcnt lgkmcnt(0)
	s_barrier
	s_add_u32 s54, s54, 1
	s_cmp_ge_u32 s54, s39
	s_cbranch_scc1 .Lssd_done
	ds_read_b128 v[28:31], v223 offset:12288
	ds_read_b128 v[32:35], v224 offset:12288
	ds_read_b128 v[40:43], v225 offset:12288
	ds_read_b128 v[44:47], v226 offset:12288
	ds_read_b128 v[48:51], v227 offset:8192
	ds_read_b128 v[52:55], v228 offset:8192
	ds_read_b128 v[56:59], v229 offset:8192
	ds_read_b128 v[60:63], v230 offset:8192
	ds_read_b32 v194, v231 offset:448
	ds_read_b128 v[64:67], v223 offset:16384
	ds_read_b128 v[68:71], v224 offset:16384
	ds_read_b128 v[72:75], v225 offset:16384
	ds_read_b128 v[76:79], v226 offset:16384
	ds_read_b128 v[80:83], v223 offset:20480
	ds_read_b128 v[84:87], v224 offset:20480
	global_load_dwordx4 v[156:159], v204, s[40:41] offset:2048
	s_waitcnt lgkmcnt(11)
	ds_read_b128 v[88:91], v225 offset:20480
	ds_read_b128 v[92:95], v226 offset:20480
	ds_read_b128 v[96:99], v232 offset:256
	ds_read_b128 v[100:103], v232 offset:320
	s_waitcnt lgkmcnt(11)
	ds_read_b64 v[124:125], v236 offset:46464
	ds_read_b64 v[126:127], v236 offset:51072
	global_load_dwordx4 v[160:163], v205, s[40:41] offset:2048
	v_mfma_f32_16x16x32_bf16 v[24:27], v[48:51], v[28:31], 0
	v_mfma_f32_16x16x32_bf16 v[24:27], v[52:55], v[32:35], v[24:27]
	v_mfma_f32_16x16x32_bf16 v[24:27], v[56:59], v[40:43], v[24:27]
	v_mfma_f32_16x16x32_bf16 v[24:27], v[60:63], v[44:47], v[24:27]
	ds_read_b64_tr_b16 v[56:57], v234 offset:32768
	ds_read_b64_tr_b16 v[58:59], v234 offset:34048
	s_waitcnt lgkmcnt(13)
	v_mfma_f32_16x16x32_bf16 v[48:51], v[64:67], v[28:31], 0
	global_load_dwordx4 v[148:151], v204, s[40:41]
	s_waitcnt lgkmcnt(9)
	v_mfma_f32_16x16x32_bf16 v[52:55], v[80:83], v[28:31], 0
	v_mfma_f32_16x16x32_bf16 v[48:51], v[68:71], v[32:35], v[48:51]
	s_waitcnt lgkmcnt(8)
	v_mfma_f32_16x16x32_bf16 v[52:55], v[84:87], v[32:35], v[52:55]
	v_mfma_f32_16x16x32_bf16 v[48:51], v[72:75], v[40:43], v[48:51]
	s_waitcnt lgkmcnt(7)
	v_mfma_f32_16x16x32_bf16 v[52:55], v[88:91], v[40:43], v[52:55]
	v_mfma_f32_16x16x32_bf16 v[48:51], v[76:79], v[44:47], v[48:51]
	global_load_dwordx4 v[152:155], v205, s[40:41]
	s_waitcnt lgkmcnt(6)
	v_mfma_f32_16x16x32_bf16 v[52:55], v[92:95], v[44:47], v[52:55]
	ds_read_b128 v[64:67], v223 offset:24576
	ds_read_b128 v[68:71], v224 offset:24576
	ds_read_b128 v[72:75], v225 offset:24576
	ds_read_b128 v[76:79], v226 offset:24576
	ds_read_b128 v[80:83], v223 offset:28672
	ds_read_b128 v[84:87], v224 offset:28672
	global_load_dwordx2 v[164:165], v206, s[40:41]
	ds_read_b128 v[88:91], v225 offset:28672
	ds_read_b128 v[92:95], v226 offset:28672
	ds_read_b64_tr_b16 v[60:61], v234 offset:35328
	s_waitcnt lgkmcnt(11)
; __device__ __forceinline__ void phase_ssd(const Params& P, int seg, unsigned char* smem) {
;     ...
;         auto step = [&](int ci, Pre& R, const int par) {
;             const int row0 = chunk_row0(ci); unsigned char* sb = smem + par * T_BUF; float* acP = acS + par * 64;
;             const bf16* StR = StS + par * (T_STSZ / 2); bf16* StW = StS + (par ^ 1) * (T_STSZ / 2);
;             const float dec = __expf(R.alast);
;             { const float e2 = __expf(R.alast - R.acl);
; #pragma unroll
;               for (int i = 0; i < 2; ++i) { const int q = tid + 512 * i, l = q >> 4, c8 = q & 15; *(v4u*)(sb + T_CS + l * 272 + c8 * 16) = R.Cr[i]; *(v4u*)(sb + T_BS + l * 272 + c8 * 16) = R.Br[i]; }
;               const int l = tid >> 3, p4 = (tid & 7) * 4;
;               const float x0 = bflo(R.Xr.x) * R.dtl, x1 = bfhi(R.Xr.x) * R.dtl, x2 = bflo(R.Xr.y) * R.dtl, x3 = bfhi(R.Xr.y) * R.dtl;
;               v2u d; d.x = cvt_pk_bf16(x0, x1); d.y = cvt_pk_bf16(x2, x3); *(v2u*)(sb + T_XD + l * 80 + p4 * 2) = d;
;               v2u e; e.x = cvt_pk_bf16(x0 * e2, x1 * e2); e.y = cvt_pk_bf16(x2 * e2, x3 * e2); *(v2u*)(sb + T_XE + l * 80 + p4 * 2) = e;
;               *(v2u*)(sb + T_XS + l * 64 + p4 * 2) = R.Xr; *(v2u*)(sb + T_ZS + l * 64 + p4 * 2) = R.Zr;
;               if (w == 0) acP[lane] = R.aclane; }
;             BAR_LDS();
;             if (ci + 2 < nchunks) load_chunk(ci + 2, R);
;             bf16x8 cf[4];
; #pragma unroll
;             for (int k = 0; k < 4; ++k) cf[k] = *(const bf16x8*)(sb + T_CS + (lt * 16 + fr) * 272 + (k * 32 + fq * 8) * 2);
;             f32x4 yo = {0.f, 0.f, 0.f, 0.f};
; #pragma unroll
;             for (int k = 0; k < 4; ++k) { const bf16x8 bb = *(const bf16x8*)((const unsigned char*)StR + (pt * 16 + fr) * 272 + (k * 32 + fq * 8) * 2); yo = mfma16(cf[k], bb, yo); }
; { const f32x4 a4 = *(const f32x4*)(acP + lt * 16 + fq * 4);
; #pragma unroll
;               for (int j = 0; j < 4; ++j) yo[j] *= __expf(a4[j]); }
;             const float acl_fr = acP[lt * 16 + fr]; const int lrow = lt * 16 + fr;
; #pragma unroll
;             for (int t = 0; t < 2; ++t) {
;                 if (2 * t <= lt) {
;                     v2u xb0, xb1;
;                     { const unsigned a0 = lds0 + par * T_BUF + T_XD + (32 * t + 4 * fq + tq) * 80 + (pt * 16 + 4 * tp) * 2, a1 = a0 + 16 * 80; TR_ISSUE(xb0, a0); TR_ISSUE(xb1, a1); }
;                     float m[8];
	ds_read_b64_tr_b16 v[62:63], v234 offset:36608
	v_exp_f32_e32 v195, v194
	s_nop 0
	v_mul_f32_e32 v24, v24, v195
	v_mul_f32_e32 v25, v25, v195
	global_load_dwordx2 v[166:167], v207, s[42:43] nt
	v_mul_f32_e32 v26, v26, v195
	v_mul_f32_e32 v27, v27, v195
	v_lshlrev_b32_e32 v112, 16, v126
	v_and_b32_e32 v113, 0xffff0000, v126
	v_lshlrev_b32_e32 v114, 16, v127
	v_and_b32_e32 v115, 0xffff0000, v127
	global_load_dword v118, v208, s[44:45]
	v_mul_f32_e32 v120, 0xbfb8aa3b, v112
	v_mul_f32_e32 v121, 0xbfb8aa3b, v113
	v_mul_f32_e32 v122, 0xbfb8aa3b, v114
	v_mul_f32_e32 v123, 0xbfb8aa3b, v115
	v_exp_f32_e32 v120, v120
	v_exp_f32_e32 v121, v121
	v_exp_f32_e32 v122, v122
	global_load_dword v168, v208, s[46:47]
	v_exp_f32_e32 v123, v123
	v_add_f32_e32 v120, 1.0, v120
	v_add_f32_e32 v121, 1.0, v121
	v_add_f32_e32 v122, 1.0, v122
	v_add_f32_e32 v123, 1.0, v123
	v_rcp_f32_e32 v120, v120
	v_rcp_f32_e32 v121, v121
	global_load_dword v169, v209, s[46:47]
	v_rcp_f32_e32 v122, v122
	v_rcp_f32_e32 v123, v123
	v_mul_f32_e32 v112, v120, v112
	v_mul_f32_e32 v113, v121, v113
	v_mul_f32_e32 v114, v122, v114
	v_mul_f32_e32 v115, v123, v115
	s_add_u32 s66, s54, 3
	s_cmp_lt_u32 s66, s39
	s_cselect_b32 s74, 0xc0000, 0
	s_cselect_b32 s75, 0x280000, 0
	s_cselect_b32 s76, 0x4000, 0
	s_add_u32 s40, s40, s74
	s_addc_u32 s41, s41, 0
	s_add_u32 s42, s42, s75
	s_addc_u32 s43, s43, 0
	s_add_u32 s44, s44, s76
	s_addc_u32 s45, s45, 0
	s_add_u32 s46, s46, s76
	s_addc_u32 s47, s47, 0
	v_lshlrev_b32_e32 v120, 16, v124
	v_and_b32_e32 v121, 0xffff0000, v124
	v_lshlrev_b32_e32 v122, 16, v125
	s_waitcnt vmcnt(10)
	v_and_b32_e32 v123, 0xffff0000, v125
	v_sub_f32_e32 v184, v194, v96
	ds_write_b128 v212, v[140:143]
	v_sub_f32_e32 v185, v194, v97
	v_sub_f32_e32 v186, v194, v98
	ds_write_b128 v212, v[144:147] offset:8192
	v_sub_f32_e32 v187, v194, v99
	v_exp_f32_e32 v184, v184
	ds_write_b128 v212, v[132:135] offset:16384
	v_exp_f32_e32 v185, v185
	v_exp_f32_e32 v186, v186
	s_waitcnt lgkmcnt(11)
	ds_write_b128 v212, v[136:139] offset:24576
	v_exp_f32_e32 v187, v187
	v_mul_f32_e32 v184, v48, v184
	v_mul_f32_e32 v185, v49, v185
	v_sub_f32_e32 v200, v117, v116
	v_mul_f32_e32 v186, v50, v186
	v_mul_f32_e32 v187, v51, v187
	v_mul_f32_e32 v200, 0x3fb8aa3b, v200
	v_sub_f32_e32 v188, v194, v100
	v_sub_f32_e32 v189, v194, v101
	v_exp_f32_e32 v200, v200
	v_sub_f32_e32 v190, v194, v102
	v_sub_f32_e32 v191, v194, v103
	v_lshlrev_b32_e32 v196, 16, v4
	v_exp_f32_e32 v188, v188
	v_exp_f32_e32 v189, v189
	v_exp_f32_e32 v190, v190
	v_and_b32_e32 v197, 0xffff0000, v4
	v_exp_f32_e32 v191, v191
	v_mul_f32_e32 v188, v52, v188
	v_lshlrev_b32_e32 v198, 16, v5
	v_mul_f32_e32 v189, v53, v189
	v_mul_f32_e32 v190, v54, v190
	v_and_b32_e32 v199, 0xffff0000, v5
	v_mul_f32_e32 v191, v55, v191
	v_cvt_pk_bf16_f32 v128, v184, v185
	v_mul_f32_e32 v196, v196, v6
	v_cvt_pk_bf16_f32 v129, v186, v187
	v_cvt_pk_bf16_f32 v130, v188, v189
	v_mul_f32_e32 v197, v197, v6
	v_cvt_pk_bf16_f32 v131, v190, v191
	s_nop 1
	v_mfma_f32_16x16x32_bf16 v[24:27], v[56:59], v[128:131], v[24:27]
	ds_read_b128 v[96:99], v232 offset:384
	v_mul_f32_e32 v198, v198, v6
	ds_read_b128 v[100:103], v232 offset:448
	v_mfma_f32_16x16x32_bf16 v[48:51], v[64:67], v[28:31], 0
	v_mul_f32_e32 v199, v199, v6
	s_waitcnt lgkmcnt(11)
	v_mfma_f32_16x16x32_bf16 v[52:55], v[80:83], v[28:31], 0
	v_mfma_f32_16x16x32_bf16 v[48:51], v[68:71], v[32:35], v[48:51]
	v_cvt_pk_bf16_f32 v202, v196, v197
	s_waitcnt lgkmcnt(10)
	v_mfma_f32_16x16x32_bf16 v[52:55], v[84:87], v[32:35], v[52:55]
	v_mfma_f32_16x16x32_bf16 v[48:51], v[72:75], v[40:43], v[48:51]
	v_cvt_pk_bf16_f32 v203, v198, v199
	s_waitcnt lgkmcnt(9)
	v_mfma_f32_16x16x32_bf16 v[52:55], v[88:91], v[40:43], v[52:55]
	v_mfma_f32_16x16x32_bf16 v[48:51], v[76:79], v[44:47], v[48:51]
	ds_write_b64 v214, v[202:203] offset:32768
	s_waitcnt lgkmcnt(9)
	v_mfma_f32_16x16x32_bf16 v[52:55], v[92:95], v[44:47], v[52:55]
	s_waitcnt lgkmcnt(2)
	v_sub_f32_e32 v184, v194, v96
	v_sub_f32_e32 v185, v194, v97
	v_mul_f32_e32 v196, v196, v200
	v_sub_f32_e32 v186, v194, v98
	v_sub_f32_e32 v187, v194, v99
	v_mul_f32_e32 v197, v197, v200
	v_exp_f32_e32 v184, v184
	v_exp_f32_e32 v185, v185
	v_mul_f32_e32 v198, v198, v200
	v_exp_f32_e32 v186, v186
	v_exp_f32_e32 v187, v187
	v_mul_f32_e32 v199, v199, v200
	v_mul_f32_e32 v184, v48, v184
	v_mul_f32_e32 v185, v49, v185
	v_mul_f32_e32 v186, v50, v186
	v_cvt_pk_bf16_f32 v192, v196, v197
	v_mul_f32_e32 v187, v51, v187
	s_waitcnt lgkmcnt(1)
	v_sub_f32_e32 v188, v194, v100
	v_cvt_pk_bf16_f32 v193, v198, v199
	v_sub_f32_e32 v189, v194, v101
	v_sub_f32_e32 v190, v194, v102
	ds_write_b64 v214, v[192:193] offset:37888
	v_sub_f32_e32 v191, v194, v103
	v_exp_f32_e32 v188, v188
	ds_write_b64 v216, v[4:5] offset:43008
	v_exp_f32_e32 v189, v189
	v_exp_f32_e32 v190, v190
	ds_write_b64 v216, v[36:37] offset:47616
	v_exp_f32_e32 v191, v191
	v_mul_f32_e32 v188, v52, v188
	v_mul_f32_e32 v189, v53, v189
	v_mul_f32_e32 v201, 0x3fb8aa3b, v116
	v_mul_f32_e32 v190, v54, v190
	v_mul_f32_e32 v191, v55, v191
	ds_write_b32 v218, v201
	v_cndmask_b32_e64 v188, 0, v188, s[14:15]
	v_cndmask_b32_e64 v189, 0, v189, s[16:17]
	v_mul_f32_e32 v174, 0x3fb8aa3b, v117
	v_cndmask_b32_e64 v190, 0, v190, s[22:23]
	v_cndmask_b32_e64 v191, 0, v191, s[34:35]
	v_exp_f32_e32 v174, v174
	v_cvt_pk_bf16_f32 v128, v184, v185
	v_cvt_pk_bf16_f32 v129, v186, v187
	v_cvt_pk_bf16_f32 v130, v188, v189
	v_cvt_pk_bf16_f32 v131, v190, v191
	s_nop 1
	v_mfma_f32_16x16x32_bf16 v[24:27], v[60:63], v[128:131], v[24:27]
	s_mul_i32 s65, s56, 0x2000
	s_add_u32 s65, s65, 0x304f1000
	s_add_u32 s48, s0, s65
	s_addc_u32 s49, s1, 0
	s_nop 3
	v_fma_f32 v184, s61, v120, v24
	v_fma_f32 v185, s61, v121, v25
	v_fma_f32 v186, s61, v122, v26
	v_fma_f32 v187, s61, v123, v27
	v_mul_f32_e32 v184, v184, v112
	v_mul_f32_e32 v185, v185, v113
	v_mul_f32_e32 v186, v186, v114
	v_mul_f32_e32 v187, v187, v115
	v_cvt_pk_bf16_f32 v170, v184, v185
	v_cvt_pk_bf16_f32 v171, v186, v187
	global_store_dwordx2 v210, v[170:171], s[48:49]
	s_add_u32 s65, s54, 1
	s_sub_u32 s65, s65, s60
	s_lshl_b32 s65, s65, 6
	s_add_u32 s56, s65, s20
	s_waitcnt lgkmcnt(0)
	s_barrier
	s_add_u32 s54, s54, 1
	s_cmp_lt_u32 s54, s39
	s_cbranch_scc1 .Lssd_loop3
.Lssd_done:
	s_cmp_eq_u32 s24, 3
	s_cbranch_scc1 .Lssd_nostore
	s_cmp_ge_u32 s55, 2
	s_cbranch_scc1 .Lssd_nostore
	s_nop 7
	v_add_u32_e32 v185, 0x2000, v211
	global_store_dwordx4 v211, v[8:11], s[50:51]
	global_store_dwordx4 v185, v[12:15], s[50:51]
	global_store_dwordx4 v211, v[16:19], s[50:51] offset:64
	global_store_dwordx4 v185, v[20:23], s[50:51] offset:64
.Lssd_nostore:
	s_barrier
	s_add_u32 s18, s18, s63
	s_cmp_lt_u32 s18, 256
	s_cbranch_scc1 .Lssd_item

.Ltramp75:
	s_branch .LBB0_75

; #define GAS __attribute__((address_space(1)))
; __global__ void __launch_bounds__(NTHREADS, 2) hybrid_fwd(Params P) {
;     extern __shared__ __attribute__((aligned(16))) unsigned char smem[];
;     cg::grid_group grid = cg::this_grid();
;     gws_t ws = (gws_t)P.ws;
;     volatile LAS unsigned* xst = (volatile LAS unsigned*)(smem + LDS_STAGE);
;     if (threadIdx.x < 2) xst[threadIdx.x] = 0u;
;     __syncthreads();
;     if (blockIdx.x == 0) { GAS unsigned* bw = (GAS unsigned*)(ws + WS_BAR);
;         for (int i = threadIdx.x; i < XCD_BAR_WORDS; i += NTHREADS) bw[i] = 0u;
;         __threadfence(); }
;     for (int rep = 0; rep < REP_P0; ++rep) phase_prep(P, smem);
;     grid.sync();
;     XcdBarrier xb = xcd_barrier_post((unsigned*)(GAS unsigned*)(ws + WS_BAR), xst);
;     for (int seg = 0; seg < NSEG; ++seg) {
;         ws = launder_s((const void*)ws);
;         { Epi1 E; E.O = (GAS bf16*)(ws + WS_PROJ); E.rstd = (const GAS float*)(ws + WS_RSTD1) + (size_t)seg * RSB;
;           for (int rep = 0; rep < REP_G1; ++rep) run_gemm(smem, (const GAS bf16*)(ws + WS_XB) + (size_t)seg * RSB * DM, (const GAS bf16*)(ws + WS_WIN), RS, NPROJ, DM, E); }
;         for (int rep = 0; rep < REP_SIDE; ++rep) side_gemm1(P, seg);
;         xcd_barrier(xb);
;         for (int rep = 0; rep < REP_ELT; ++rep) phase_conv(P, seg);
;         xcd_barrier(xb);
;         for (int rep = 0; rep < REP_SSD; ++rep) phase_ssd(P, seg, smem);
;         xcd_barrier(xb);
;         phase_gnorm(P, seg);
;         ws = launder_s((const void*)ws);
;         { EpiGate<0> E; E.proj = (const GAS bf16*)(ws + WS_PROJ); E.bgate = P.b_gate; E.ta = (GAS bf16*)(ws + WS_TA); E.mix = (GAS bf16*)(ws + WS_MIX);
;           for (int rep = 0; rep < REP_GX; ++rep) run_gemm(smem, (const GAS bf16*)(ws + WS_YA), (const GAS bf16*)(ws + WS_WA), RS, DM, DM, E); }
;         if (seg == 0) side_gemm2(P, smem);
;         xcd_barrier(xb);
;         ws = launder_s((const void*)ws);
;         { EpiGate<1> E; E.proj = (const GAS bf16*)(ws + WS_PROJ); E.bgate = P.b_gate; E.ta = (GAS bf16*)(ws + WS_TA); E.mix = (GAS bf16*)(ws + WS_MIX);
;           for (int rep = 0; rep < REP_GX; ++rep) run_gemm(smem, (const GAS bf16*)(ws + WS_YPRE), (const GAS bf16*)(ws + WS_WM), RS, DM, DINNER, E); }
;         if (seg == 0) side_gemm3(P, smem);
;         xcd_barrier(xb);
;         ws = launder_s((const void*)ws);
	.amdhsa_kernel _Z10hybrid_fwd6Params
		.amdhsa_group_segment_fixed_size 0
		.amdhsa_private_segment_fixed_size 0
		.amdhsa_kernarg_size 440
		.amdhsa_user_sgpr_count 2
		.amdhsa_user_sgpr_dispatch_ptr 0
		.amdhsa_user_sgpr_queue_ptr 0
		.amdhsa_user_sgpr_kernarg_segment_ptr 1
		.amdhsa_user_sgpr_dispatch_id 0
		.amdhsa_user_sgpr_kernarg_preload_length 0
		.amdhsa_user_sgpr_kernarg_preload_offset 0
		.amdhsa_user_sgpr_private_segment_size 0
		.amdhsa_uses_dynamic_stack 0
		.amdhsa_enable_private_segment 0
		.amdhsa_system_sgpr_workgroup_id_x 1
		.amdhsa_system_sgpr_workgroup_id_y 0
		.amdhsa_system_sgpr_workgroup_id_z 0
		.amdhsa_system_sgpr_workgroup_info 0
		.amdhsa_system_vgpr_workitem_id 2
		.amdhsa_next_free_vgpr 256
		.amdhsa_next_free_sgpr 102
		.amdhsa_accum_offset 256
		.amdhsa_reserve_vcc 1
		.amdhsa_float_round_mode_32 0
		.amdhsa_float_round_mode_16_64 0
		.amdhsa_float_denorm_mode_32 3
		.amdhsa_float_denorm_mode_16_64 3
		.amdhsa_dx10_clamp 1
		.amdhsa_ieee_mode 1
		.amdhsa_fp16_overflow 0
		.amdhsa_tg_split 0
		.amdhsa_exception_fp_ieee_invalid_op 0
		.amdhsa_exception_fp_denorm_src 0
		.amdhsa_exception_fp_ieee_div_zero 0
		.amdhsa_exception_fp_ieee_overflow 0
		.amdhsa_exception_fp_ieee_underflow 0
		.amdhsa_exception_fp_ieee_inexact 0
		.amdhsa_exception_int_div_zero 0
	.end_amdhsa_kernel

; #define GAS __attribute__((address_space(1)))
; __global__ void __launch_bounds__(NTHREADS, 2) hybrid_fwd(Params P) {
;     extern __shared__ __attribute__((aligned(16))) unsigned char smem[];
;     cg::grid_group grid = cg::this_grid();
;     gws_t ws = (gws_t)P.ws;
;     volatile LAS unsigned* xst = (volatile LAS unsigned*)(smem + LDS_STAGE);
;     if (threadIdx.x < 2) xst[threadIdx.x] = 0u;
;     __syncthreads();
;     if (blockIdx.x == 0) { GAS unsigned* bw = (GAS unsigned*)(ws + WS_BAR);
;         for (int i = threadIdx.x; i < XCD_BAR_WORDS; i += NTHREADS) bw[i] = 0u;
;         __threadfence(); }
;     for (int rep = 0; rep < REP_P0; ++rep) phase_prep(P, smem);
;     grid.sync();
;     XcdBarrier xb = xcd_barrier_post((unsigned*)(GAS unsigned*)(ws + WS_BAR), xst);
;     for (int seg = 0; seg < NSEG; ++seg) {
;         ws = launder_s((const void*)ws);
;         { Epi1 E; E.O = (GAS bf16*)(ws + WS_PROJ); E.rstd = (const GAS float*)(ws + WS_RSTD1) + (size_t)seg * RSB;
;           for (int rep = 0; rep < REP_G1; ++rep) run_gemm(smem, (const GAS bf16*)(ws + WS_XB) + (size_t)seg * RSB * DM, (const GAS bf16*)(ws + WS_WIN), RS, NPROJ, DM, E); }
;         for (int rep = 0; rep < REP_SIDE; ++rep) side_gemm1(P, seg);
;         xcd_barrier(xb);
;         for (int rep = 0; rep < REP_ELT; ++rep) phase_conv(P, seg);
;         xcd_barrier(xb);
;         for (int rep = 0; rep < REP_SSD; ++rep) phase_ssd(P, seg, smem);
;         xcd_barrier(xb);
;         phase_gnorm(P, seg);
;         ws = launder_s((const void*)ws);
;         { EpiGate<0> E; E.proj = (const GAS bf16*)(ws + WS_PROJ); E.bgate = P.b_gate; E.ta = (GAS bf16*)(ws + WS_TA); E.mix = (GAS bf16*)(ws + WS_MIX);
;           for (int rep = 0; rep < REP_GX; ++rep) run_gemm(smem, (const GAS bf16*)(ws + WS_YA), (const GAS bf16*)(ws + WS_WA), RS, DM, DM, E); }
;         if (seg == 0) side_gemm2(P, smem);
;         xcd_barrier(xb);
;         ws = launder_s((const void*)ws);
;         { EpiGate<1> E; E.proj = (const GAS bf16*)(ws + WS_PROJ); E.bgate = P.b_gate; E.ta = (GAS bf16*)(ws + WS_TA); E.mix = (GAS bf16*)(ws + WS_MIX);
;           for (int rep = 0; rep < REP_GX; ++rep) run_gemm(smem, (const GAS bf16*)(ws + WS_YPRE), (const GAS bf16*)(ws + WS_WM), RS, DM, DINNER, E); }
;         if (seg == 0) side_gemm3(P, smem);
;         xcd_barrier(xb);
;         ws = launder_s((const void*)ws);
amdhsa.kernels:
  - .agpr_count:     0
    .args:
      - .offset:         0
        .size:           184
        .value_kind:     by_value
      - .offset:         184
        .size:           4
        .value_kind:     hidden_block_count_x
      - .offset:         188
        .size:           4
        .value_kind:     hidden_block_count_y
      - .offset:         192
        .size:           4
        .value_kind:     hidden_block_count_z
      - .offset:         196
        .size:           2
        .value_kind:     hidden_group_size_x
      - .offset:         198
        .size:           2
        .value_kind:     hidden_group_size_y
      - .offset:         200
        .size:           2
        .value_kind:     hidden_group_size_z
      - .offset:         202
        .size:           2
        .value_kind:     hidden_remainder_x
      - .offset:         204
        .size:           2
        .value_kind:     hidden_remainder_y
      - .offset:         206
        .size:           2
        .value_kind:     hidden_remainder_z
      - .offset:         224
        .size:           8
        .value_kind:     hidden_global_offset_x
      - .offset:         232
        .size:           8
        .value_kind:     hidden_global_offset_y
      - .offset:         240
        .size:           8
        .value_kind:     hidden_global_offset_z
      - .offset:         248
        .size:           2
        .value_kind:     hidden_grid_dims
      - .offset:         272
        .size:           8
        .value_kind:     hidden_multigrid_sync_arg
      - .offset:         304
        .size:           4
        .value_kind:     hidden_dynamic_lds_size
    .group_segment_fixed_size: 0
    .kernarg_segment_align: 8
    .kernarg_segment_size: 440
    .language:       OpenCL C
    .language_version:
      - 2
      - 0
    .max_flat_workgroup_size: 512
    .name:           _Z10hybrid_fwd6Params
    .private_segment_fixed_size: 0
    .sgpr_count:     108
    .sgpr_spill_count: 217
    .symbol:         _Z10hybrid_fwd6Params.kd
    .uniform_work_group_size: 1
    .uses_dynamic_stack: false
    .vgpr_count:     256
    .vgpr_spill_count: 0
    .wavefront_size: 64
